# K-loop: global loads issued before each M0 MFMA group and LDS writes before each M1 group (earlier issue, same counts)
# speedup vs baseline: 1.0527x; 1.0037x over previous
; #define GLOAD(ra, rb, koff)                                                        \
;   {                                                                                \
;     _Pragma("unroll") for (int j = 0; j < 4; j++) ra[j] = *(const u32x4*)(pa + j * sa32 + (koff));   \
;     _Pragma("unroll") for (int j = 0; j < NB_; j++) rb[j] = *(const u32x4*)(pbv[j] + (koff));         \
;   }
; template <int NT, bool PRE> ...
;     ...
;   const int wsw = ((tid & 7) ^ ((tid >> 4) & 7)) * 8;
;   const int rsw = (lane & 15) >> 1;
;     ...
;   if (!PRE) {
;     GLOAD(ra0, rb0, 0);
;     GLOAD(ra1, rb1, 64);
;   }
;   __syncthreads();
;   for (int k0 = 0; k0 < K; k0 += 128) {
;     LSTORE(ra0, rb0, 0);
;     __syncthreads();
;     GLOAD(ra0, rb0, min(k0 + 128, K - 128));
;     __builtin_amdgcn_sched_barrier(0);
;     COMPUTE(0);
;     LSTORE(ra1, rb1, 1);
;     __syncthreads();
;     GLOAD(ra1, rb1, min(k0 + 192, K - 64));
;     __builtin_amdgcn_sched_barrier(0);
;     COMPUTE(1);
.LBB0_231:
	s_add_i32 s4, s1, 0x100
	s_min_u32 s4, s4, 0x380
	s_lshl_b32 s54, s4, 1
	ds_read_b128 v[164:167], v160
	ds_read_b128 v[210:213], v161 offset:16384
	ds_read_b128 v[214:217], v161 offset:18432
	ds_read_b128 v[218:221], v161 offset:20480
	ds_read_b128 v[222:225], v161 offset:22528
	ds_read_b128 v[198:201], v160 offset:2048
	ds_read_b128 v[202:205], v160 offset:4096
	ds_read_b128 v[206:209], v160 offset:6144
	ds_read_b128 v[226:229], v162
	ds_read_b128 v[230:233], v162 offset:2048
	ds_read_b128 v[234:237], v162 offset:4096
	ds_read_b128 v[238:241], v162 offset:6144
	ds_read_b128 v[242:245], v163 offset:16384
	v_lshl_add_u64 v[112:113], v[152:153], 0, s[54:55]
	v_add_co_u32_e32 v114, vcc, s33, v112
	v_lshl_add_u64 v[64:65], v[144:145], 0, s[54:55]
	s_nop 0
	v_addc_co_u32_e32 v115, vcc, 0, v113, vcc
	v_add_co_u32_e32 v116, vcc, s56, v112
	v_lshl_add_u64 v[66:67], v[146:147], 0, s[54:55]
	s_nop 0
	v_addc_co_u32_e32 v117, vcc, 0, v113, vcc
	v_add_co_u32_e32 v118, vcc, s57, v112
	v_lshl_add_u64 v[68:69], v[148:149], 0, s[54:55]
	v_lshl_add_u64 v[70:71], v[150:151], 0, s[54:55]
	v_addc_co_u32_e32 v119, vcc, 0, v113, vcc
	s_addk_i32 s1, 0x80
	s_setprio 1
	global_load_dwordx4 v[104:107], v[64:65], off
	s_nop 0
	global_load_dwordx4 v[84:87], v[66:67], off
	s_waitcnt lgkmcnt(11)
	v_mfma_f32_16x16x32_bf16 v[60:63], v[210:213], v[164:167], v[60:63]
	s_waitcnt lgkmcnt(10)
	v_mfma_f32_16x16x32_bf16 v[44:47], v[214:217], v[164:167], v[44:47]
	s_waitcnt lgkmcnt(9)
	v_mfma_f32_16x16x32_bf16 v[28:31], v[218:221], v[164:167], v[28:31]
	s_waitcnt lgkmcnt(8)
	v_mfma_f32_16x16x32_bf16 v[12:15], v[222:225], v[164:167], v[12:15]
	ds_read_b128 v[164:167], v163 offset:18432
	global_load_dwordx4 v[64:67], v[68:69], off
	s_nop 0
	global_load_dwordx4 v[68:71], v[70:71], off
	s_waitcnt lgkmcnt(8)
	v_mfma_f32_16x16x32_bf16 v[56:59], v[210:213], v[198:201], v[56:59]
	v_mfma_f32_16x16x32_bf16 v[40:43], v[214:217], v[198:201], v[40:43]
	v_mfma_f32_16x16x32_bf16 v[24:27], v[218:221], v[198:201], v[24:27]
	v_mfma_f32_16x16x32_bf16 v[8:11], v[222:225], v[198:201], v[8:11]
	ds_read_b128 v[198:201], v163 offset:20480
	global_load_dwordx4 v[124:127], v[112:113], off
	s_nop 0
	global_load_dwordx4 v[120:123], v[114:115], off
	s_waitcnt lgkmcnt(8)
	v_mfma_f32_16x16x32_bf16 v[52:55], v[210:213], v[202:205], v[52:55]
	v_mfma_f32_16x16x32_bf16 v[36:39], v[214:217], v[202:205], v[36:39]
	v_mfma_f32_16x16x32_bf16 v[20:23], v[218:221], v[202:205], v[20:23]
	v_mfma_f32_16x16x32_bf16 v[4:7], v[222:225], v[202:205], v[4:7]
	ds_read_b128 v[202:205], v163 offset:22528
	global_load_dwordx4 v[112:115], v[116:117], off
	s_nop 0
	global_load_dwordx4 v[116:119], v[118:119], off
	s_waitcnt lgkmcnt(8)
	v_mfma_f32_16x16x32_bf16 v[48:51], v[210:213], v[206:209], v[48:51]
	v_mfma_f32_16x16x32_bf16 v[32:35], v[214:217], v[206:209], v[32:35]
	v_mfma_f32_16x16x32_bf16 v[16:19], v[218:221], v[206:209], v[16:19]
	v_mfma_f32_16x16x32_bf16 v[0:3], v[222:225], v[206:209], v[0:3]
	s_waitcnt lgkmcnt(3)
	s_waitcnt vmcnt(14)
	ds_write_b128 v130, v[76:79] offset:49152
	ds_write_b128 v130, v[80:83] offset:53248
	v_mfma_f32_16x16x32_bf16 v[60:63], v[242:245], v[226:229], v[60:63]
	v_mfma_f32_16x16x32_bf16 v[56:59], v[242:245], v[230:233], v[56:59]
	v_mfma_f32_16x16x32_bf16 v[52:55], v[242:245], v[234:237], v[52:55]
	v_mfma_f32_16x16x32_bf16 v[48:51], v[242:245], v[238:241], v[48:51]
	s_waitcnt lgkmcnt(4)
	s_waitcnt vmcnt(11)
	ds_write_b128 v130, v[88:91] offset:57344
	ds_write_b128 v130, v[72:75] offset:32768
	v_mfma_f32_16x16x32_bf16 v[44:47], v[164:167], v[226:229], v[44:47]
	v_mfma_f32_16x16x32_bf16 v[40:43], v[164:167], v[230:233], v[40:43]
	v_mfma_f32_16x16x32_bf16 v[36:39], v[164:167], v[234:237], v[36:39]
	v_mfma_f32_16x16x32_bf16 v[32:35], v[164:167], v[238:241], v[32:35]
	s_waitcnt lgkmcnt(5)
	s_waitcnt vmcnt(9)
	ds_write_b128 v130, v[96:99] offset:36864
	ds_write_b128 v130, v[100:103] offset:40960
	v_mfma_f32_16x16x32_bf16 v[28:31], v[198:201], v[226:229], v[28:31]
	v_mfma_f32_16x16x32_bf16 v[24:27], v[198:201], v[230:233], v[24:27]
	v_mfma_f32_16x16x32_bf16 v[20:23], v[198:201], v[234:237], v[20:23]
	v_mfma_f32_16x16x32_bf16 v[16:19], v[198:201], v[238:241], v[16:19]
	s_waitcnt lgkmcnt(6)
	s_waitcnt vmcnt(8)
	ds_write_b128 v130, v[108:111] offset:45056
	ds_write_b128 v130, v[92:95] offset:61440
	v_mfma_f32_16x16x32_bf16 v[12:15], v[202:205], v[226:229], v[12:15]
	v_mfma_f32_16x16x32_bf16 v[8:11], v[202:205], v[230:233], v[8:11]
	v_mfma_f32_16x16x32_bf16 v[4:7], v[202:205], v[234:237], v[4:7]
	v_mfma_f32_16x16x32_bf16 v[0:3], v[202:205], v[238:241], v[0:3]
	s_setprio 0
	s_waitcnt lgkmcnt(0)
	s_barrier
; #define GLOAD(ra, rb, koff)                                                        \
;   {                                                                                \
;     _Pragma("unroll") for (int j = 0; j < 4; j++) ra[j] = *(const u32x4*)(pa + j * sa32 + (koff));   \
;     _Pragma("unroll") for (int j = 0; j < NB_; j++) rb[j] = *(const u32x4*)(pbv[j] + (koff));         \
;   }
; template <int NT, bool PRE> ...
;     ...
;   const int wsw = ((tid & 7) ^ ((tid >> 4) & 7)) * 8;
;   const int rsw = (lane & 15) >> 1;
;     ...
;   if (!PRE) {
;     GLOAD(ra0, rb0, 0);
;     GLOAD(ra1, rb1, 64);
;   }
;   __syncthreads();
;   for (int k0 = 0; k0 < K; k0 += 128) {
;     LSTORE(ra0, rb0, 0);
;     __syncthreads();
;     GLOAD(ra0, rb0, min(k0 + 128, K - 128));
;     __builtin_amdgcn_sched_barrier(0);
;     COMPUTE(0);
;     LSTORE(ra1, rb1, 1);
;     __syncthreads();
;     GLOAD(ra1, rb1, min(k0 + 192, K - 64));
;     __builtin_amdgcn_sched_barrier(0);
;     COMPUTE(1);
	s_min_u32 s4, s1, 0x300
	s_lshl_b32 s54, s4, 1
	ds_read_b128 v[164:167], v160 offset:32768
	ds_read_b128 v[210:213], v161 offset:49152
	ds_read_b128 v[214:217], v161 offset:51200
	ds_read_b128 v[218:221], v161 offset:53248
	ds_read_b128 v[222:225], v161 offset:55296
	ds_read_b128 v[198:201], v160 offset:34816
	ds_read_b128 v[202:205], v160 offset:36864
	ds_read_b128 v[206:209], v160 offset:38912
	ds_read_b128 v[226:229], v162 offset:32768
	ds_read_b128 v[230:233], v162 offset:34816
	ds_read_b128 v[234:237], v162 offset:36864
	ds_read_b128 v[238:241], v162 offset:38912
	ds_read_b128 v[242:245], v163 offset:49152
	v_lshl_add_u64 v[72:73], v[152:153], 0, s[54:55]
	v_add_co_u32_e32 v96, vcc, s33, v72
	v_lshl_add_u64 v[74:75], v[144:145], 0, s[54:55]
	s_nop 0
	v_addc_co_u32_e32 v97, vcc, 0, v73, vcc
	v_add_co_u32_e32 v100, vcc, s56, v72
	v_lshl_add_u64 v[80:81], v[146:147], 0, s[54:55]
	s_nop 0
	v_addc_co_u32_e32 v101, vcc, 0, v73, vcc
	v_add_co_u32_e32 v108, vcc, s57, v72
	v_lshl_add_u64 v[88:89], v[148:149], 0, s[54:55]
	v_lshl_add_u64 v[92:93], v[150:151], 0, s[54:55]
	v_addc_co_u32_e32 v109, vcc, 0, v73, vcc
	s_setprio 1
	global_load_dwordx4 v[76:79], v[74:75], off offset:384
	s_nop 0
	global_load_dwordx4 v[80:83], v[80:81], off offset:384
	s_waitcnt lgkmcnt(11)
	v_mfma_f32_16x16x32_bf16 v[60:63], v[210:213], v[164:167], v[60:63]
	s_waitcnt lgkmcnt(10)
	v_mfma_f32_16x16x32_bf16 v[44:47], v[214:217], v[164:167], v[44:47]
	s_waitcnt lgkmcnt(9)
	v_mfma_f32_16x16x32_bf16 v[28:31], v[218:221], v[164:167], v[28:31]
	s_waitcnt lgkmcnt(8)
	v_mfma_f32_16x16x32_bf16 v[12:15], v[222:225], v[164:167], v[12:15]
	ds_read_b128 v[164:167], v163 offset:51200
	global_load_dwordx4 v[88:91], v[88:89], off offset:384
	s_nop 0
	global_load_dwordx4 v[92:95], v[92:93], off offset:384
	s_waitcnt lgkmcnt(8)
	v_mfma_f32_16x16x32_bf16 v[56:59], v[210:213], v[198:201], v[56:59]
	v_mfma_f32_16x16x32_bf16 v[40:43], v[214:217], v[198:201], v[40:43]
	v_mfma_f32_16x16x32_bf16 v[24:27], v[218:221], v[198:201], v[24:27]
	v_mfma_f32_16x16x32_bf16 v[8:11], v[222:225], v[198:201], v[8:11]
	ds_read_b128 v[198:201], v163 offset:53248
	global_load_dwordx4 v[72:75], v[72:73], off offset:384
	s_nop 0
	global_load_dwordx4 v[96:99], v[96:97], off offset:384
	s_waitcnt lgkmcnt(8)
	v_mfma_f32_16x16x32_bf16 v[52:55], v[210:213], v[202:205], v[52:55]
	v_mfma_f32_16x16x32_bf16 v[36:39], v[214:217], v[202:205], v[36:39]
	v_mfma_f32_16x16x32_bf16 v[20:23], v[218:221], v[202:205], v[20:23]
	v_mfma_f32_16x16x32_bf16 v[4:7], v[222:225], v[202:205], v[4:7]
	ds_read_b128 v[202:205], v163 offset:55296
	global_load_dwordx4 v[100:103], v[100:101], off offset:384
	s_nop 0
	global_load_dwordx4 v[108:111], v[108:109], off offset:384
	s_waitcnt lgkmcnt(8)
	v_mfma_f32_16x16x32_bf16 v[48:51], v[210:213], v[206:209], v[48:51]
	v_mfma_f32_16x16x32_bf16 v[32:35], v[214:217], v[206:209], v[32:35]
	v_mfma_f32_16x16x32_bf16 v[16:19], v[218:221], v[206:209], v[16:19]
	v_mfma_f32_16x16x32_bf16 v[0:3], v[222:225], v[206:209], v[0:3]
	s_waitcnt lgkmcnt(3)
	s_waitcnt vmcnt(14)
	ds_write_b128 v130, v[104:107] offset:16384
	ds_write_b128 v130, v[84:87] offset:20480
	v_mfma_f32_16x16x32_bf16 v[60:63], v[242:245], v[226:229], v[60:63]
	v_mfma_f32_16x16x32_bf16 v[56:59], v[242:245], v[230:233], v[56:59]
	v_mfma_f32_16x16x32_bf16 v[52:55], v[242:245], v[234:237], v[52:55]
	v_mfma_f32_16x16x32_bf16 v[48:51], v[242:245], v[238:241], v[48:51]
	s_waitcnt lgkmcnt(4)
	s_waitcnt vmcnt(12)
	ds_write_b128 v130, v[64:67] offset:24576
	ds_write_b128 v130, v[68:71] offset:28672
	v_mfma_f32_16x16x32_bf16 v[44:47], v[164:167], v[226:229], v[44:47]
	v_mfma_f32_16x16x32_bf16 v[40:43], v[164:167], v[230:233], v[40:43]
	v_mfma_f32_16x16x32_bf16 v[36:39], v[164:167], v[234:237], v[36:39]
	v_mfma_f32_16x16x32_bf16 v[32:35], v[164:167], v[238:241], v[32:35]
	s_waitcnt lgkmcnt(5)
	s_waitcnt vmcnt(10)
	ds_write_b128 v130, v[124:127]
	ds_write_b128 v130, v[120:123] offset:4096
	v_mfma_f32_16x16x32_bf16 v[28:31], v[198:201], v[226:229], v[28:31]
	v_mfma_f32_16x16x32_bf16 v[24:27], v[198:201], v[230:233], v[24:27]
	v_mfma_f32_16x16x32_bf16 v[20:23], v[198:201], v[234:237], v[20:23]
	v_mfma_f32_16x16x32_bf16 v[16:19], v[198:201], v[238:241], v[16:19]
	s_waitcnt lgkmcnt(6)
	s_waitcnt vmcnt(8)
	ds_write_b128 v130, v[112:115] offset:8192
	ds_write_b128 v130, v[116:119] offset:12288
	v_mfma_f32_16x16x32_bf16 v[12:15], v[202:205], v[226:229], v[12:15]
	v_mfma_f32_16x16x32_bf16 v[8:11], v[202:205], v[230:233], v[8:11]
	v_mfma_f32_16x16x32_bf16 v[4:7], v[202:205], v[234:237], v[4:7]
	v_mfma_f32_16x16x32_bf16 v[0:3], v[202:205], v[238:241], v[0:3]
	s_setprio 0
	s_waitcnt lgkmcnt(0)
	s_barrier
	s_cmpk_lt_u32 s1, 0x300
	s_cbranch_scc1 .LBB0_231
; #define GLOAD(ra, rb, koff)                                                        \
;   {                                                                                \
;     _Pragma("unroll") for (int j = 0; j < 4; j++) ra[j] = *(const u32x4*)(pa + j * sa32 + (koff));   \
;     _Pragma("unroll") for (int j = 0; j < NB_; j++) rb[j] = *(const u32x4*)(pbv[j] + (koff));         \
;   }
; template <int NT, bool PRE> ...
;     ...
;   if (!PRE) {
;     GLOAD(ra0, rb0, 0);
;     GLOAD(ra1, rb1, 64);
;   }
;   __syncthreads();
;   for (int k0 = 0; k0 < K; k0 += 128) {
;     LSTORE(ra0, rb0, 0);
;     __syncthreads();
;     GLOAD(ra0, rb0, min(k0 + 128, K - 128));
;     __builtin_amdgcn_sched_barrier(0);
;     COMPUTE(0);
;     LSTORE(ra1, rb1, 1);
;     __syncthreads();
;     GLOAD(ra1, rb1, min(k0 + 192, K - 64));
;     __builtin_amdgcn_sched_barrier(0);
;     COMPUTE(1);
	ds_read_b128 v[164:167], v160
	ds_read_b128 v[210:213], v161 offset:16384
	ds_read_b128 v[214:217], v161 offset:18432
	ds_read_b128 v[218:221], v161 offset:20480
	ds_read_b128 v[222:225], v161 offset:22528
	ds_read_b128 v[198:201], v160 offset:2048
	ds_read_b128 v[202:205], v160 offset:4096
	ds_read_b128 v[206:209], v160 offset:6144
	ds_read_b128 v[226:229], v162
	ds_read_b128 v[230:233], v162 offset:2048
	ds_read_b128 v[234:237], v162 offset:4096
	ds_read_b128 v[238:241], v162 offset:6144
	ds_read_b128 v[242:245], v163 offset:16384
	s_addk_i32 s1, 0x80
	s_setprio 1
	s_waitcnt lgkmcnt(11)
	v_mfma_f32_16x16x32_bf16 v[60:63], v[210:213], v[164:167], v[60:63]
	s_waitcnt lgkmcnt(10)
	v_mfma_f32_16x16x32_bf16 v[44:47], v[214:217], v[164:167], v[44:47]
	s_waitcnt lgkmcnt(9)
	v_mfma_f32_16x16x32_bf16 v[28:31], v[218:221], v[164:167], v[28:31]
	s_waitcnt lgkmcnt(8)
	v_mfma_f32_16x16x32_bf16 v[12:15], v[222:225], v[164:167], v[12:15]
	ds_read_b128 v[164:167], v163 offset:18432
	s_waitcnt lgkmcnt(8)
	v_mfma_f32_16x16x32_bf16 v[56:59], v[210:213], v[198:201], v[56:59]
	v_mfma_f32_16x16x32_bf16 v[40:43], v[214:217], v[198:201], v[40:43]
	v_mfma_f32_16x16x32_bf16 v[24:27], v[218:221], v[198:201], v[24:27]
	v_mfma_f32_16x16x32_bf16 v[8:11], v[222:225], v[198:201], v[8:11]
	ds_read_b128 v[198:201], v163 offset:20480
	s_waitcnt lgkmcnt(8)
	v_mfma_f32_16x16x32_bf16 v[52:55], v[210:213], v[202:205], v[52:55]
	v_mfma_f32_16x16x32_bf16 v[36:39], v[214:217], v[202:205], v[36:39]
	v_mfma_f32_16x16x32_bf16 v[20:23], v[218:221], v[202:205], v[20:23]
	v_mfma_f32_16x16x32_bf16 v[4:7], v[222:225], v[202:205], v[4:7]
	ds_read_b128 v[202:205], v163 offset:22528
	s_waitcnt lgkmcnt(8)
	v_mfma_f32_16x16x32_bf16 v[48:51], v[210:213], v[206:209], v[48:51]
	v_mfma_f32_16x16x32_bf16 v[32:35], v[214:217], v[206:209], v[32:35]
	v_mfma_f32_16x16x32_bf16 v[16:19], v[218:221], v[206:209], v[16:19]
	v_mfma_f32_16x16x32_bf16 v[0:3], v[222:225], v[206:209], v[0:3]
	s_waitcnt lgkmcnt(3)
	s_waitcnt vmcnt(6)
	ds_write_b128 v130, v[76:79] offset:49152
	ds_write_b128 v130, v[80:83] offset:53248
	v_mfma_f32_16x16x32_bf16 v[60:63], v[242:245], v[226:229], v[60:63]
	v_mfma_f32_16x16x32_bf16 v[56:59], v[242:245], v[230:233], v[56:59]
	v_mfma_f32_16x16x32_bf16 v[52:55], v[242:245], v[234:237], v[52:55]
	v_mfma_f32_16x16x32_bf16 v[48:51], v[242:245], v[238:241], v[48:51]
	s_waitcnt lgkmcnt(4)
	s_waitcnt vmcnt(3)
	ds_write_b128 v130, v[88:91] offset:57344
	ds_write_b128 v130, v[72:75] offset:32768
	v_mfma_f32_16x16x32_bf16 v[44:47], v[164:167], v[226:229], v[44:47]
	v_mfma_f32_16x16x32_bf16 v[40:43], v[164:167], v[230:233], v[40:43]
	v_mfma_f32_16x16x32_bf16 v[36:39], v[164:167], v[234:237], v[36:39]
	v_mfma_f32_16x16x32_bf16 v[32:35], v[164:167], v[238:241], v[32:35]
	s_waitcnt lgkmcnt(5)
	s_waitcnt vmcnt(1)
	ds_write_b128 v130, v[96:99] offset:36864
	ds_write_b128 v130, v[100:103] offset:40960
	v_mfma_f32_16x16x32_bf16 v[28:31], v[198:201], v[226:229], v[28:31]
	v_mfma_f32_16x16x32_bf16 v[24:27], v[198:201], v[230:233], v[24:27]
	v_mfma_f32_16x16x32_bf16 v[20:23], v[198:201], v[234:237], v[20:23]
	v_mfma_f32_16x16x32_bf16 v[16:19], v[198:201], v[238:241], v[16:19]
	s_waitcnt lgkmcnt(6)
	s_waitcnt vmcnt(0)
	ds_write_b128 v130, v[108:111] offset:45056
	ds_write_b128 v130, v[92:95] offset:61440
	v_mfma_f32_16x16x32_bf16 v[12:15], v[202:205], v[226:229], v[12:15]
	v_mfma_f32_16x16x32_bf16 v[8:11], v[202:205], v[230:233], v[8:11]
	v_mfma_f32_16x16x32_bf16 v[4:7], v[202:205], v[234:237], v[4:7]
	v_mfma_f32_16x16x32_bf16 v[0:3], v[202:205], v[238:241], v[0:3]
	s_setprio 0
	s_waitcnt lgkmcnt(0)
	s_barrier
; template <int NT>
; __device__ __forceinline__ void zgemm_tile(char* ws, int m0, int n0, u16* sA, u16* sB, int tq) {
;     ...
;       int col = GEMM_COL(ni, NT * 32);
;       int cb = col & ~15;
; #pragma unroll
;       for (int mi = 0; mi < 4; mi++) {
;         int row = GEMM_ROW(mi);
;         int b = row >= NPB ? 1 : 0;
;         int n = row - b * NPB;
;         f32x4 v = acc[mi][ni];
;         if (cb < 2480) *(uint2*)(Z + (size_t)row * ZLD + col) = pack4(v);
	ds_read_b128 v[164:167], v160 offset:32768
	ds_read_b128 v[210:213], v161 offset:49152
	ds_read_b128 v[214:217], v161 offset:51200
	ds_read_b128 v[218:221], v161 offset:53248
	ds_read_b128 v[222:225], v161 offset:55296
	ds_read_b128 v[198:201], v160 offset:34816
	ds_read_b128 v[202:205], v160 offset:36864
	ds_read_b128 v[206:209], v160 offset:38912
	ds_read_b128 v[226:229], v162 offset:32768
	ds_read_b128 v[230:233], v162 offset:34816
	ds_read_b128 v[234:237], v162 offset:36864
	ds_read_b128 v[238:241], v162 offset:38912
	ds_read_b128 v[242:245], v163 offset:49152
	s_setprio 1
	s_waitcnt lgkmcnt(11)
	v_mfma_f32_16x16x32_bf16 v[60:63], v[210:213], v[164:167], v[60:63]
	s_waitcnt lgkmcnt(10)
	v_mfma_f32_16x16x32_bf16 v[44:47], v[214:217], v[164:167], v[44:47]
	s_waitcnt lgkmcnt(9)
	v_mfma_f32_16x16x32_bf16 v[28:31], v[218:221], v[164:167], v[28:31]
	s_waitcnt lgkmcnt(8)
	v_mfma_f32_16x16x32_bf16 v[12:15], v[222:225], v[164:167], v[12:15]
	ds_read_b128 v[164:167], v163 offset:51200
	s_waitcnt lgkmcnt(8)
	v_mfma_f32_16x16x32_bf16 v[56:59], v[210:213], v[198:201], v[56:59]
	v_mfma_f32_16x16x32_bf16 v[40:43], v[214:217], v[198:201], v[40:43]
	v_mfma_f32_16x16x32_bf16 v[24:27], v[218:221], v[198:201], v[24:27]
	v_mfma_f32_16x16x32_bf16 v[8:11], v[222:225], v[198:201], v[8:11]
	ds_read_b128 v[198:201], v163 offset:53248
	s_waitcnt lgkmcnt(8)
	v_mfma_f32_16x16x32_bf16 v[52:55], v[210:213], v[202:205], v[52:55]
	v_mfma_f32_16x16x32_bf16 v[36:39], v[214:217], v[202:205], v[36:39]
	v_mfma_f32_16x16x32_bf16 v[20:23], v[218:221], v[202:205], v[20:23]
	v_mfma_f32_16x16x32_bf16 v[4:7], v[222:225], v[202:205], v[4:7]
	ds_read_b128 v[202:205], v163 offset:55296
	s_waitcnt lgkmcnt(8)
	v_mfma_f32_16x16x32_bf16 v[48:51], v[210:213], v[206:209], v[48:51]
	v_mfma_f32_16x16x32_bf16 v[32:35], v[214:217], v[206:209], v[32:35]
	v_mfma_f32_16x16x32_bf16 v[16:19], v[218:221], v[206:209], v[16:19]
	v_mfma_f32_16x16x32_bf16 v[0:3], v[222:225], v[206:209], v[0:3]
	s_waitcnt lgkmcnt(3)
	v_mfma_f32_16x16x32_bf16 v[60:63], v[242:245], v[226:229], v[60:63]
	v_mfma_f32_16x16x32_bf16 v[56:59], v[242:245], v[230:233], v[56:59]
	v_mfma_f32_16x16x32_bf16 v[52:55], v[242:245], v[234:237], v[52:55]
	v_mfma_f32_16x16x32_bf16 v[48:51], v[242:245], v[238:241], v[48:51]
	s_waitcnt lgkmcnt(2)
	v_mfma_f32_16x16x32_bf16 v[44:47], v[164:167], v[226:229], v[44:47]
	v_mfma_f32_16x16x32_bf16 v[40:43], v[164:167], v[230:233], v[40:43]
	v_mfma_f32_16x16x32_bf16 v[36:39], v[164:167], v[234:237], v[36:39]
	v_mfma_f32_16x16x32_bf16 v[32:35], v[164:167], v[238:241], v[32:35]
	s_waitcnt lgkmcnt(1)
	v_mfma_f32_16x16x32_bf16 v[28:31], v[198:201], v[226:229], v[28:31]
	v_mfma_f32_16x16x32_bf16 v[24:27], v[198:201], v[230:233], v[24:27]
	v_mfma_f32_16x16x32_bf16 v[20:23], v[198:201], v[234:237], v[20:23]
	v_mfma_f32_16x16x32_bf16 v[16:19], v[198:201], v[238:241], v[16:19]
	s_waitcnt lgkmcnt(0)
	v_mfma_f32_16x16x32_bf16 v[12:15], v[202:205], v[226:229], v[12:15]
	v_mfma_f32_16x16x32_bf16 v[8:11], v[202:205], v[230:233], v[8:11]
	v_mfma_f32_16x16x32_bf16 v[4:7], v[202:205], v[234:237], v[4:7]
	v_mfma_f32_16x16x32_bf16 v[0:3], v[202:205], v[238:241], v[0:3]
	s_setprio 0
	s_waitcnt lgkmcnt(0)
	s_waitcnt vmcnt(13)
	v_or_b32_e32 v65, s0, v159
	v_or_b32_e32 v130, v65, v156
	v_or_b32_e32 v64, s3, v154
	s_movk_i32 s0, 0x9b0
	v_ashrrev_i32_e32 v67, 31, v130
	v_mov_b32_e32 v66, v130
	v_add_u32_e32 v64, v64, v158
	v_cmp_gt_i32_e64 s[50:51], s0, v65
	s_waitcnt vmcnt(12)
	v_lshl_add_u64 v[70:71], v[66:67], 1, s[18:19]
	s_and_saveexec_b64 s[0:1], s[50:51]
	s_cbranch_execz .LBB0_234
	v_cvt_pk_bf16_f32 v66, v60, v61
	v_cvt_pk_bf16_f32 v67, v62, v63
	v_mad_i64_i32 v[68:69], s[4:5], v64, s91, v[70:71]
	global_store_dwordx2 v[68:69], v[66:67], off

; #define GLOAD(ra, rb, koff)                                                        \
;   {                                                                                \
;     _Pragma("unroll") for (int j = 0; j < 4; j++) ra[j] = *(const u32x4*)(pa + j * sa32 + (koff));   \
;     _Pragma("unroll") for (int j = 0; j < NB_; j++) rb[j] = *(const u32x4*)(pbv[j] + (koff));         \
;   }
; template <int NT, bool PRE> ...
;     ...
;   const int wsw = ((tid & 7) ^ ((tid >> 4) & 7)) * 8;
;   const int rsw = (lane & 15) >> 1;
;     ...
;   if (!PRE) {
;     GLOAD(ra0, rb0, 0);
;     GLOAD(ra1, rb1, 64);
;   }
;   __syncthreads();
;   for (int k0 = 0; k0 < K; k0 += 128) {
;     LSTORE(ra0, rb0, 0);
;     __syncthreads();
;     GLOAD(ra0, rb0, min(k0 + 128, K - 128));
;     __builtin_amdgcn_sched_barrier(0);
;     COMPUTE(0);
;     LSTORE(ra1, rb1, 1);
;     __syncthreads();
;     GLOAD(ra1, rb1, min(k0 + 192, K - 64));
;     __builtin_amdgcn_sched_barrier(0);
;     COMPUTE(1);
.LBB0_1989:
	s_add_i32 s22, s21, 0x100
	s_min_u32 s22, s22, 0x380
	s_lshl_b32 s54, s22, 1
	ds_read_b128 v[158:161], v153
	ds_read_b128 v[206:209], v154 offset:16384
	ds_read_b128 v[210:213], v154 offset:18432
	ds_read_b128 v[214:217], v154 offset:20480
	ds_read_b128 v[218:221], v154 offset:22528
	ds_read_b128 v[162:165], v153 offset:2048
	ds_read_b128 v[198:201], v153 offset:4096
	ds_read_b128 v[202:205], v153 offset:6144
	ds_read_b128 v[222:225], v155
	ds_read_b128 v[226:229], v155 offset:2048
	ds_read_b128 v[230:233], v155 offset:4096
	ds_read_b128 v[234:237], v155 offset:6144
	ds_read_b128 v[238:241], v156 offset:16384
	ds_read_b128 v[242:245], v156 offset:18432
	v_lshl_add_u64 v[108:109], v[144:145], 0, s[54:55]
	v_add_co_u32_e32 v112, vcc, s33, v108
	v_lshl_add_u64 v[72:73], v[136:137], 0, s[54:55]
	s_nop 0
	v_addc_co_u32_e32 v113, vcc, 0, v109, vcc
	v_add_co_u32_e32 v114, vcc, s56, v108
	v_lshl_add_u64 v[74:75], v[138:139], 0, s[54:55]
	s_nop 0
	v_addc_co_u32_e32 v115, vcc, 0, v109, vcc
	v_add_co_u32_e32 v116, vcc, s57, v108
	v_lshl_add_u64 v[92:93], v[140:141], 0, s[54:55]
	v_lshl_add_u64 v[94:95], v[142:143], 0, s[54:55]
	v_addc_co_u32_e32 v117, vcc, 0, v109, vcc
	s_addk_i32 s21, 0x80
	s_setprio 1
	global_load_dwordx4 v[100:103], v[72:73], off
	s_nop 0
	global_load_dwordx4 v[84:87], v[74:75], off
	s_waitcnt lgkmcnt(12)
	v_mfma_f32_16x16x32_bf16 v[124:127], v[206:209], v[158:161], v[124:127]
	s_waitcnt lgkmcnt(11)
	v_mfma_f32_16x16x32_bf16 v[56:59], v[210:213], v[158:161], v[56:59]
	s_waitcnt lgkmcnt(10)
	v_mfma_f32_16x16x32_bf16 v[52:55], v[214:217], v[158:161], v[52:55]
	s_waitcnt lgkmcnt(9)
	v_mfma_f32_16x16x32_bf16 v[48:51], v[218:221], v[158:161], v[48:51]
	ds_read_b128 v[158:161], v156 offset:20480
	global_load_dwordx4 v[72:75], v[92:93], off
	s_nop 0
	global_load_dwordx4 v[92:95], v[94:95], off
	s_waitcnt lgkmcnt(9)
	v_mfma_f32_16x16x32_bf16 v[44:47], v[206:209], v[162:165], v[44:47]
	v_mfma_f32_16x16x32_bf16 v[40:43], v[210:213], v[162:165], v[40:43]
	v_mfma_f32_16x16x32_bf16 v[36:39], v[214:217], v[162:165], v[36:39]
	v_mfma_f32_16x16x32_bf16 v[32:35], v[218:221], v[162:165], v[32:35]
	ds_read_b128 v[162:165], v156 offset:22528
	global_load_dwordx4 v[108:111], v[108:109], off
	s_nop 0
	global_load_dwordx4 v[120:123], v[112:113], off
	s_waitcnt lgkmcnt(9)
	v_mfma_f32_16x16x32_bf16 v[28:31], v[206:209], v[198:201], v[28:31]
	v_mfma_f32_16x16x32_bf16 v[24:27], v[210:213], v[198:201], v[24:27]
	v_mfma_f32_16x16x32_bf16 v[20:23], v[214:217], v[198:201], v[20:23]
	v_mfma_f32_16x16x32_bf16 v[16:19], v[218:221], v[198:201], v[16:19]
	global_load_dwordx4 v[112:115], v[114:115], off
	s_nop 0
	global_load_dwordx4 v[116:119], v[116:117], off
	s_waitcnt lgkmcnt(8)
	v_mfma_f32_16x16x32_bf16 v[12:15], v[206:209], v[202:205], v[12:15]
	v_mfma_f32_16x16x32_bf16 v[8:11], v[210:213], v[202:205], v[8:11]
	v_mfma_f32_16x16x32_bf16 v[4:7], v[214:217], v[202:205], v[4:7]
	v_mfma_f32_16x16x32_bf16 v[0:3], v[218:221], v[202:205], v[0:3]
	s_waitcnt lgkmcnt(3)
	s_waitcnt vmcnt(14)
	ds_write_b128 v148, v[64:67] offset:49152
	ds_write_b128 v148, v[68:71] offset:53248
	v_mfma_f32_16x16x32_bf16 v[124:127], v[238:241], v[222:225], v[124:127]
	v_mfma_f32_16x16x32_bf16 v[44:47], v[238:241], v[226:229], v[44:47]
	v_mfma_f32_16x16x32_bf16 v[28:31], v[238:241], v[230:233], v[28:31]
	v_mfma_f32_16x16x32_bf16 v[12:15], v[238:241], v[234:237], v[12:15]
	s_waitcnt lgkmcnt(4)
	s_waitcnt vmcnt(11)
	ds_write_b128 v148, v[76:79] offset:57344
	ds_write_b128 v148, v[60:63] offset:32768
	v_mfma_f32_16x16x32_bf16 v[56:59], v[242:245], v[222:225], v[56:59]
	v_mfma_f32_16x16x32_bf16 v[40:43], v[242:245], v[226:229], v[40:43]
	v_mfma_f32_16x16x32_bf16 v[24:27], v[242:245], v[230:233], v[24:27]
	v_mfma_f32_16x16x32_bf16 v[8:11], v[242:245], v[234:237], v[8:11]
	s_waitcnt lgkmcnt(5)
	s_waitcnt vmcnt(9)
	ds_write_b128 v148, v[80:83] offset:36864
	ds_write_b128 v148, v[96:99] offset:40960
	v_mfma_f32_16x16x32_bf16 v[52:55], v[158:161], v[222:225], v[52:55]
	v_mfma_f32_16x16x32_bf16 v[36:39], v[158:161], v[226:229], v[36:39]
	v_mfma_f32_16x16x32_bf16 v[20:23], v[158:161], v[230:233], v[20:23]
	v_mfma_f32_16x16x32_bf16 v[4:7], v[158:161], v[234:237], v[4:7]
	s_waitcnt lgkmcnt(6)
	s_waitcnt vmcnt(8)
	ds_write_b128 v148, v[104:107] offset:45056
	ds_write_b128 v148, v[88:91] offset:61440
	v_mfma_f32_16x16x32_bf16 v[48:51], v[162:165], v[222:225], v[48:51]
	v_mfma_f32_16x16x32_bf16 v[32:35], v[162:165], v[226:229], v[32:35]
	v_mfma_f32_16x16x32_bf16 v[16:19], v[162:165], v[230:233], v[16:19]
	v_mfma_f32_16x16x32_bf16 v[0:3], v[162:165], v[234:237], v[0:3]
	s_setprio 0
	s_waitcnt lgkmcnt(0)
	s_barrier
; #define GLOAD(ra, rb, koff)                                                        \
;   {                                                                                \
;     _Pragma("unroll") for (int j = 0; j < 4; j++) ra[j] = *(const u32x4*)(pa + j * sa32 + (koff));   \
;     _Pragma("unroll") for (int j = 0; j < NB_; j++) rb[j] = *(const u32x4*)(pbv[j] + (koff));         \
;   }
; template <int NT, bool PRE> ...
;     ...
;   const int wsw = ((tid & 7) ^ ((tid >> 4) & 7)) * 8;
;   const int rsw = (lane & 15) >> 1;
;     ...
;   if (!PRE) {
;     GLOAD(ra0, rb0, 0);
;     GLOAD(ra1, rb1, 64);
;   }
;   __syncthreads();
;   for (int k0 = 0; k0 < K; k0 += 128) {
;     LSTORE(ra0, rb0, 0);
;     __syncthreads();
;     GLOAD(ra0, rb0, min(k0 + 128, K - 128));
;     __builtin_amdgcn_sched_barrier(0);
;     COMPUTE(0);
;     LSTORE(ra1, rb1, 1);
;     __syncthreads();
;     GLOAD(ra1, rb1, min(k0 + 192, K - 64));
;     __builtin_amdgcn_sched_barrier(0);
;     COMPUTE(1);
	s_min_u32 s22, s21, 0x300
	s_lshl_b32 s54, s22, 1
	ds_read_b128 v[158:161], v153 offset:32768
	ds_read_b128 v[206:209], v154 offset:49152
	ds_read_b128 v[210:213], v154 offset:51200
	ds_read_b128 v[214:217], v154 offset:53248
	ds_read_b128 v[218:221], v154 offset:55296
	ds_read_b128 v[162:165], v153 offset:34816
	ds_read_b128 v[198:201], v153 offset:36864
	ds_read_b128 v[202:205], v153 offset:38912
	ds_read_b128 v[222:225], v155 offset:32768
	ds_read_b128 v[226:229], v155 offset:34816
	ds_read_b128 v[230:233], v155 offset:36864
	ds_read_b128 v[234:237], v155 offset:38912
	ds_read_b128 v[238:241], v156 offset:49152
	ds_read_b128 v[242:245], v156 offset:51200
	v_lshl_add_u64 v[60:61], v[144:145], 0, s[54:55]
	v_add_co_u32_e32 v82, vcc, s33, v60
	v_lshl_add_u64 v[62:63], v[136:137], 0, s[54:55]
	s_nop 0
	v_addc_co_u32_e32 v83, vcc, 0, v61, vcc
	v_add_co_u32_e32 v96, vcc, s56, v60
	v_lshl_add_u64 v[68:69], v[138:139], 0, s[54:55]
	s_nop 0
	v_addc_co_u32_e32 v97, vcc, 0, v61, vcc
	v_add_co_u32_e32 v104, vcc, s57, v60
	v_lshl_add_u64 v[76:77], v[140:141], 0, s[54:55]
	v_lshl_add_u64 v[80:81], v[142:143], 0, s[54:55]
	v_addc_co_u32_e32 v105, vcc, 0, v61, vcc
	s_setprio 1
	global_load_dwordx4 v[64:67], v[62:63], off offset:384
	s_nop 0
	global_load_dwordx4 v[68:71], v[68:69], off offset:384
	s_waitcnt lgkmcnt(12)
	v_mfma_f32_16x16x32_bf16 v[124:127], v[206:209], v[158:161], v[124:127]
	s_waitcnt lgkmcnt(11)
	v_mfma_f32_16x16x32_bf16 v[56:59], v[210:213], v[158:161], v[56:59]
	s_waitcnt lgkmcnt(10)
	v_mfma_f32_16x16x32_bf16 v[52:55], v[214:217], v[158:161], v[52:55]
	s_waitcnt lgkmcnt(9)
	v_mfma_f32_16x16x32_bf16 v[48:51], v[218:221], v[158:161], v[48:51]
	ds_read_b128 v[158:161], v156 offset:53248
	global_load_dwordx4 v[76:79], v[76:77], off offset:384
	s_nop 0
	global_load_dwordx4 v[88:91], v[80:81], off offset:384
	s_waitcnt lgkmcnt(9)
	v_mfma_f32_16x16x32_bf16 v[44:47], v[206:209], v[162:165], v[44:47]
	v_mfma_f32_16x16x32_bf16 v[40:43], v[210:213], v[162:165], v[40:43]
	v_mfma_f32_16x16x32_bf16 v[36:39], v[214:217], v[162:165], v[36:39]
	v_mfma_f32_16x16x32_bf16 v[32:35], v[218:221], v[162:165], v[32:35]
	ds_read_b128 v[162:165], v156 offset:55296
	global_load_dwordx4 v[60:63], v[60:61], off offset:384
	s_nop 0
	global_load_dwordx4 v[80:83], v[82:83], off offset:384
	s_waitcnt lgkmcnt(9)
	v_mfma_f32_16x16x32_bf16 v[28:31], v[206:209], v[198:201], v[28:31]
	v_mfma_f32_16x16x32_bf16 v[24:27], v[210:213], v[198:201], v[24:27]
	v_mfma_f32_16x16x32_bf16 v[20:23], v[214:217], v[198:201], v[20:23]
	v_mfma_f32_16x16x32_bf16 v[16:19], v[218:221], v[198:201], v[16:19]
	global_load_dwordx4 v[96:99], v[96:97], off offset:384
	s_nop 0
	global_load_dwordx4 v[104:107], v[104:105], off offset:384
	s_waitcnt lgkmcnt(8)
	v_mfma_f32_16x16x32_bf16 v[12:15], v[206:209], v[202:205], v[12:15]
	v_mfma_f32_16x16x32_bf16 v[8:11], v[210:213], v[202:205], v[8:11]
	v_mfma_f32_16x16x32_bf16 v[4:7], v[214:217], v[202:205], v[4:7]
	v_mfma_f32_16x16x32_bf16 v[0:3], v[218:221], v[202:205], v[0:3]
	s_waitcnt lgkmcnt(3)
	s_waitcnt vmcnt(14)
	ds_write_b128 v148, v[100:103] offset:16384
	ds_write_b128 v148, v[84:87] offset:20480
	v_mfma_f32_16x16x32_bf16 v[124:127], v[238:241], v[222:225], v[124:127]
	v_mfma_f32_16x16x32_bf16 v[44:47], v[238:241], v[226:229], v[44:47]
	v_mfma_f32_16x16x32_bf16 v[28:31], v[238:241], v[230:233], v[28:31]
	v_mfma_f32_16x16x32_bf16 v[12:15], v[238:241], v[234:237], v[12:15]
	s_waitcnt lgkmcnt(4)
	s_waitcnt vmcnt(12)
	ds_write_b128 v148, v[72:75] offset:24576
	ds_write_b128 v148, v[92:95] offset:28672
	v_mfma_f32_16x16x32_bf16 v[56:59], v[242:245], v[222:225], v[56:59]
	v_mfma_f32_16x16x32_bf16 v[40:43], v[242:245], v[226:229], v[40:43]
	v_mfma_f32_16x16x32_bf16 v[24:27], v[242:245], v[230:233], v[24:27]
	v_mfma_f32_16x16x32_bf16 v[8:11], v[242:245], v[234:237], v[8:11]
	s_waitcnt lgkmcnt(5)
	s_waitcnt vmcnt(10)
	ds_write_b128 v148, v[108:111]
	ds_write_b128 v148, v[120:123] offset:4096
	v_mfma_f32_16x16x32_bf16 v[52:55], v[158:161], v[222:225], v[52:55]
	v_mfma_f32_16x16x32_bf16 v[36:39], v[158:161], v[226:229], v[36:39]
	v_mfma_f32_16x16x32_bf16 v[20:23], v[158:161], v[230:233], v[20:23]
	v_mfma_f32_16x16x32_bf16 v[4:7], v[158:161], v[234:237], v[4:7]
	s_waitcnt lgkmcnt(6)
	s_waitcnt vmcnt(8)
	ds_write_b128 v148, v[112:115] offset:8192
	ds_write_b128 v148, v[116:119] offset:12288
	v_mfma_f32_16x16x32_bf16 v[48:51], v[162:165], v[222:225], v[48:51]
	v_mfma_f32_16x16x32_bf16 v[32:35], v[162:165], v[226:229], v[32:35]
	v_mfma_f32_16x16x32_bf16 v[16:19], v[162:165], v[230:233], v[16:19]
	v_mfma_f32_16x16x32_bf16 v[0:3], v[162:165], v[234:237], v[0:3]
	s_setprio 0
	s_waitcnt lgkmcnt(0)
	s_barrier
	s_cmpk_lt_u32 s21, 0x300
	s_cbranch_scc1 .LBB0_1989
; #define GLOAD(ra, rb, koff)                                                        \
;   {                                                                                \
;     _Pragma("unroll") for (int j = 0; j < 4; j++) ra[j] = *(const u32x4*)(pa + j * sa32 + (koff));   \
;     _Pragma("unroll") for (int j = 0; j < NB_; j++) rb[j] = *(const u32x4*)(pbv[j] + (koff));         \
;   }
; template <int NT, bool PRE> ...
;     ...
;   if (!PRE) {
;     GLOAD(ra0, rb0, 0);
;     GLOAD(ra1, rb1, 64);
;   }
;   __syncthreads();
;   for (int k0 = 0; k0 < K; k0 += 128) {
;     LSTORE(ra0, rb0, 0);
;     __syncthreads();
;     GLOAD(ra0, rb0, min(k0 + 128, K - 128));
;     __builtin_amdgcn_sched_barrier(0);
;     COMPUTE(0);
;     LSTORE(ra1, rb1, 1);
;     __syncthreads();
;     GLOAD(ra1, rb1, min(k0 + 192, K - 64));
;     __builtin_amdgcn_sched_barrier(0);
;     COMPUTE(1);
	ds_read_b128 v[158:161], v153
	ds_read_b128 v[206:209], v154 offset:16384
	ds_read_b128 v[210:213], v154 offset:18432
	ds_read_b128 v[214:217], v154 offset:20480
	ds_read_b128 v[218:221], v154 offset:22528
	ds_read_b128 v[162:165], v153 offset:2048
	ds_read_b128 v[198:201], v153 offset:4096
	ds_read_b128 v[202:205], v153 offset:6144
	ds_read_b128 v[222:225], v155
	ds_read_b128 v[226:229], v155 offset:2048
	ds_read_b128 v[230:233], v155 offset:4096
	ds_read_b128 v[234:237], v155 offset:6144
	ds_read_b128 v[238:241], v156 offset:16384
	ds_read_b128 v[242:245], v156 offset:18432
	s_addk_i32 s21, 0x80
	s_setprio 1
	s_waitcnt lgkmcnt(12)
	v_mfma_f32_16x16x32_bf16 v[124:127], v[206:209], v[158:161], v[124:127]
	s_waitcnt lgkmcnt(11)
	v_mfma_f32_16x16x32_bf16 v[56:59], v[210:213], v[158:161], v[56:59]
	s_waitcnt lgkmcnt(10)
	v_mfma_f32_16x16x32_bf16 v[52:55], v[214:217], v[158:161], v[52:55]
	s_waitcnt lgkmcnt(9)
	v_mfma_f32_16x16x32_bf16 v[48:51], v[218:221], v[158:161], v[48:51]
	ds_read_b128 v[158:161], v156 offset:20480
	s_waitcnt lgkmcnt(9)
	v_mfma_f32_16x16x32_bf16 v[44:47], v[206:209], v[162:165], v[44:47]
	v_mfma_f32_16x16x32_bf16 v[40:43], v[210:213], v[162:165], v[40:43]
	v_mfma_f32_16x16x32_bf16 v[36:39], v[214:217], v[162:165], v[36:39]
	v_mfma_f32_16x16x32_bf16 v[32:35], v[218:221], v[162:165], v[32:35]
	ds_read_b128 v[162:165], v156 offset:22528
	s_waitcnt lgkmcnt(9)
	v_mfma_f32_16x16x32_bf16 v[28:31], v[206:209], v[198:201], v[28:31]
	v_mfma_f32_16x16x32_bf16 v[24:27], v[210:213], v[198:201], v[24:27]
	v_mfma_f32_16x16x32_bf16 v[20:23], v[214:217], v[198:201], v[20:23]
	v_mfma_f32_16x16x32_bf16 v[16:19], v[218:221], v[198:201], v[16:19]
	s_waitcnt lgkmcnt(8)
	v_mfma_f32_16x16x32_bf16 v[12:15], v[206:209], v[202:205], v[12:15]
	v_mfma_f32_16x16x32_bf16 v[8:11], v[210:213], v[202:205], v[8:11]
	v_mfma_f32_16x16x32_bf16 v[4:7], v[214:217], v[202:205], v[4:7]
	v_mfma_f32_16x16x32_bf16 v[0:3], v[218:221], v[202:205], v[0:3]
	s_waitcnt lgkmcnt(3)
	s_waitcnt vmcnt(6)
	ds_write_b128 v148, v[64:67] offset:49152
	ds_write_b128 v148, v[68:71] offset:53248
	v_mfma_f32_16x16x32_bf16 v[124:127], v[238:241], v[222:225], v[124:127]
	v_mfma_f32_16x16x32_bf16 v[44:47], v[238:241], v[226:229], v[44:47]
	v_mfma_f32_16x16x32_bf16 v[28:31], v[238:241], v[230:233], v[28:31]
	v_mfma_f32_16x16x32_bf16 v[12:15], v[238:241], v[234:237], v[12:15]
	s_waitcnt lgkmcnt(4)
	s_waitcnt vmcnt(3)
	ds_write_b128 v148, v[76:79] offset:57344
	ds_write_b128 v148, v[60:63] offset:32768
	v_mfma_f32_16x16x32_bf16 v[56:59], v[242:245], v[222:225], v[56:59]
	v_mfma_f32_16x16x32_bf16 v[40:43], v[242:245], v[226:229], v[40:43]
	v_mfma_f32_16x16x32_bf16 v[24:27], v[242:245], v[230:233], v[24:27]
	v_mfma_f32_16x16x32_bf16 v[8:11], v[242:245], v[234:237], v[8:11]
	s_waitcnt lgkmcnt(5)
	s_waitcnt vmcnt(1)
	ds_write_b128 v148, v[80:83] offset:36864
	ds_write_b128 v148, v[96:99] offset:40960
	v_mfma_f32_16x16x32_bf16 v[52:55], v[158:161], v[222:225], v[52:55]
	v_mfma_f32_16x16x32_bf16 v[36:39], v[158:161], v[226:229], v[36:39]
	v_mfma_f32_16x16x32_bf16 v[20:23], v[158:161], v[230:233], v[20:23]
	v_mfma_f32_16x16x32_bf16 v[4:7], v[158:161], v[234:237], v[4:7]
	s_waitcnt lgkmcnt(6)
	s_waitcnt vmcnt(0)
	ds_write_b128 v148, v[104:107] offset:45056
	ds_write_b128 v148, v[88:91] offset:61440
	v_mfma_f32_16x16x32_bf16 v[48:51], v[162:165], v[222:225], v[48:51]
	v_mfma_f32_16x16x32_bf16 v[32:35], v[162:165], v[226:229], v[32:35]
	v_mfma_f32_16x16x32_bf16 v[16:19], v[162:165], v[230:233], v[16:19]
	v_mfma_f32_16x16x32_bf16 v[0:3], v[162:165], v[234:237], v[0:3]
	s_setprio 0
	s_waitcnt lgkmcnt(0)
	s_barrier
	ds_read_b128 v[158:161], v153 offset:32768
	ds_read_b128 v[206:209], v154 offset:49152
	ds_read_b128 v[210:213], v154 offset:51200
	ds_read_b128 v[214:217], v154 offset:53248
	ds_read_b128 v[218:221], v154 offset:55296
	ds_read_b128 v[162:165], v153 offset:34816
	ds_read_b128 v[198:201], v153 offset:36864
	ds_read_b128 v[202:205], v153 offset:38912
	ds_read_b128 v[222:225], v155 offset:32768
	ds_read_b128 v[226:229], v155 offset:34816
	ds_read_b128 v[230:233], v155 offset:36864
	ds_read_b128 v[234:237], v155 offset:38912
	ds_read_b128 v[238:241], v156 offset:49152
	ds_read_b128 v[242:245], v156 offset:51200
	s_setprio 1
	s_waitcnt lgkmcnt(12)
	v_mfma_f32_16x16x32_bf16 v[124:127], v[206:209], v[158:161], v[124:127]
	s_waitcnt lgkmcnt(11)
	v_mfma_f32_16x16x32_bf16 v[56:59], v[210:213], v[158:161], v[56:59]
	s_waitcnt lgkmcnt(10)
	v_mfma_f32_16x16x32_bf16 v[52:55], v[214:217], v[158:161], v[52:55]
	s_waitcnt lgkmcnt(9)
	v_mfma_f32_16x16x32_bf16 v[48:51], v[218:221], v[158:161], v[48:51]
	ds_read_b128 v[158:161], v156 offset:53248
	s_waitcnt lgkmcnt(9)
	v_mfma_f32_16x16x32_bf16 v[44:47], v[206:209], v[162:165], v[44:47]
	v_mfma_f32_16x16x32_bf16 v[40:43], v[210:213], v[162:165], v[40:43]
	v_mfma_f32_16x16x32_bf16 v[36:39], v[214:217], v[162:165], v[36:39]
	v_mfma_f32_16x16x32_bf16 v[32:35], v[218:221], v[162:165], v[32:35]
	ds_read_b128 v[162:165], v156 offset:55296
	s_waitcnt lgkmcnt(9)
	v_mfma_f32_16x16x32_bf16 v[28:31], v[206:209], v[198:201], v[28:31]
	v_mfma_f32_16x16x32_bf16 v[24:27], v[210:213], v[198:201], v[24:27]
	v_mfma_f32_16x16x32_bf16 v[20:23], v[214:217], v[198:201], v[20:23]
	v_mfma_f32_16x16x32_bf16 v[16:19], v[218:221], v[198:201], v[16:19]
	s_waitcnt lgkmcnt(8)
	v_mfma_f32_16x16x32_bf16 v[12:15], v[206:209], v[202:205], v[12:15]
	v_mfma_f32_16x16x32_bf16 v[8:11], v[210:213], v[202:205], v[8:11]
	v_mfma_f32_16x16x32_bf16 v[4:7], v[214:217], v[202:205], v[4:7]
	v_mfma_f32_16x16x32_bf16 v[0:3], v[218:221], v[202:205], v[0:3]
	s_waitcnt lgkmcnt(3)
; __device__ __forceinline__ float sigmoidf_(float x) { return 1.f / (1.f + __expf(-x)); }
; __device__ __forceinline__ void phase_merge(const Params& P, u16* sA, u16* sB) {
;     ...
;       for (int mi = 0; mi < 4; mi++)
; #pragma unroll
;         for (int ni = 0; ni < 4; ni++) {
;           f32x4 g = ag[mi][ni];
;           gp[mi][ni] = u32x2{pk2bf(sigmoidf_(g[0]), sigmoidf_(g[1])), pk2bf(sigmoidf_(g[2]), sigmoidf_(g[3]))};
;         }
	v_mfma_f32_16x16x32_bf16 v[124:127], v[238:241], v[222:225], v[124:127]
	v_mfma_f32_16x16x32_bf16 v[44:47], v[238:241], v[226:229], v[44:47]
	v_mfma_f32_16x16x32_bf16 v[28:31], v[238:241], v[230:233], v[28:31]
	v_mfma_f32_16x16x32_bf16 v[12:15], v[238:241], v[234:237], v[12:15]
	s_waitcnt lgkmcnt(2)
	v_mfma_f32_16x16x32_bf16 v[56:59], v[242:245], v[222:225], v[56:59]
	v_mfma_f32_16x16x32_bf16 v[40:43], v[242:245], v[226:229], v[40:43]
	v_mfma_f32_16x16x32_bf16 v[24:27], v[242:245], v[230:233], v[24:27]
	v_mfma_f32_16x16x32_bf16 v[8:11], v[242:245], v[234:237], v[8:11]
	s_waitcnt lgkmcnt(1)
	v_mfma_f32_16x16x32_bf16 v[52:55], v[158:161], v[222:225], v[52:55]
	v_mfma_f32_16x16x32_bf16 v[36:39], v[158:161], v[226:229], v[36:39]
	v_mfma_f32_16x16x32_bf16 v[20:23], v[158:161], v[230:233], v[20:23]
	v_mfma_f32_16x16x32_bf16 v[4:7], v[158:161], v[234:237], v[4:7]
	s_waitcnt lgkmcnt(0)
	v_mfma_f32_16x16x32_bf16 v[48:51], v[162:165], v[222:225], v[48:51]
	v_mfma_f32_16x16x32_bf16 v[32:35], v[162:165], v[226:229], v[32:35]
	v_mfma_f32_16x16x32_bf16 v[16:19], v[162:165], v[230:233], v[16:19]
	v_mfma_f32_16x16x32_bf16 v[0:3], v[162:165], v[234:237], v[0:3]
	s_setprio 0
	s_waitcnt lgkmcnt(0)
	s_waitcnt vmcnt(3)
	v_mul_f32_e32 v60, 0xbfb8aa3b, v124
	v_mul_f32_e32 v61, 0xbfb8aa3b, v125
	v_exp_f32_e32 v60, v60
	v_exp_f32_e32 v61, v61
	v_mul_f32_e32 v56, 0xbfb8aa3b, v56
	v_mul_f32_e32 v57, 0xbfb8aa3b, v57
	v_exp_f32_e32 v56, v56
	v_pk_add_f32 v[60:61], v[60:61], 1.0 op_sel_hi:[1,0]
	v_exp_f32_e32 v57, v57
	v_div_scale_f32 v62, s[22:23], v61, v61, 1.0
	v_rcp_f32_e32 v63, v62
	v_pk_add_f32 v[56:57], v[56:57], 1.0 op_sel_hi:[1,0]
	v_mul_f32_e32 v52, 0xbfb8aa3b, v52
	v_mul_f32_e32 v53, 0xbfb8aa3b, v53
	v_fma_f32 v64, -v62, v63, 1.0
	v_fmac_f32_e32 v63, v64, v63
	v_div_scale_f32 v64, vcc, 1.0, v61, 1.0
	v_mul_f32_e32 v65, v64, v63
	v_fma_f32 v66, -v62, v65, v64
	v_fmac_f32_e32 v65, v66, v63
	v_fma_f32 v62, -v62, v65, v64
	v_div_fmas_f32 v62, v62, v63, v65
	v_div_fixup_f32 v61, v62, v61, 1.0
	v_div_scale_f32 v62, s[22:23], v60, v60, 1.0
	v_rcp_f32_e32 v63, v62
	v_exp_f32_e32 v52, v52
	v_exp_f32_e32 v53, v53
	v_mul_f32_e32 v48, 0xbfb8aa3b, v48
	v_fma_f32 v64, -v62, v63, 1.0
	v_fmac_f32_e32 v63, v64, v63
	v_div_scale_f32 v64, vcc, 1.0, v60, 1.0
	v_mul_f32_e32 v65, v64, v63
	v_fma_f32 v66, -v62, v65, v64
	v_fmac_f32_e32 v65, v66, v63
	v_fma_f32 v62, -v62, v65, v64
	v_div_fmas_f32 v62, v62, v63, v65
	v_div_fixup_f32 v60, v62, v60, 1.0
	v_cvt_pk_bf16_f32 v60, v60, v61
	v_mul_f32_e32 v61, 0xbfb8aa3b, v126
	v_exp_f32_e32 v62, v61
	v_mul_f32_e32 v61, 0xbfb8aa3b, v127
	v_exp_f32_e32 v63, v61
	v_pk_add_f32 v[52:53], v[52:53], 1.0 op_sel_hi:[1,0]
	v_mul_f32_e32 v49, 0xbfb8aa3b, v49
	v_exp_f32_e32 v48, v48
	v_pk_add_f32 v[62:63], v[62:63], 1.0 op_sel_hi:[1,0]
	v_exp_f32_e32 v49, v49
	v_div_scale_f32 v61, s[22:23], v63, v63, 1.0
	v_rcp_f32_e32 v64, v61
	v_pk_add_f32 v[48:49], v[48:49], 1.0 op_sel_hi:[1,0]
	v_mul_f32_e32 v44, 0xbfb8aa3b, v44
	v_mul_f32_e32 v45, 0xbfb8aa3b, v45
	v_fma_f32 v65, -v61, v64, 1.0
	v_fmac_f32_e32 v64, v65, v64
	v_div_scale_f32 v65, vcc, 1.0, v63, 1.0
	v_mul_f32_e32 v66, v65, v64
	v_fma_f32 v67, -v61, v66, v65
	v_fmac_f32_e32 v66, v67, v64
	v_fma_f32 v61, -v61, v66, v65
	v_div_fmas_f32 v61, v61, v64, v66
	v_div_fixup_f32 v61, v61, v63, 1.0
	v_div_scale_f32 v63, s[22:23], v62, v62, 1.0
	v_rcp_f32_e32 v64, v63
	v_exp_f32_e32 v44, v44
	v_exp_f32_e32 v45, v45
	v_mul_f32_e32 v40, 0xbfb8aa3b, v40
	v_fma_f32 v65, -v63, v64, 1.0
	v_fmac_f32_e32 v64, v65, v64
	v_div_scale_f32 v65, vcc, 1.0, v62, 1.0
	v_mul_f32_e32 v66, v65, v64
	v_fma_f32 v67, -v63, v66, v65
	v_fmac_f32_e32 v66, v67, v64
	v_fma_f32 v63, -v63, v66, v65
	v_div_fmas_f32 v63, v63, v64, v66
	v_div_fixup_f32 v62, v63, v62, 1.0
	v_cvt_pk_bf16_f32 v61, v62, v61
	v_div_scale_f32 v62, s[22:23], v57, v57, 1.0
	v_rcp_f32_e32 v63, v62
	v_pk_add_f32 v[44:45], v[44:45], 1.0 op_sel_hi:[1,0]
	v_mul_f32_e32 v41, 0xbfb8aa3b, v41
	v_exp_f32_e32 v40, v40
	v_fma_f32 v64, -v62, v63, 1.0
	v_fmac_f32_e32 v63, v64, v63
	v_div_scale_f32 v64, vcc, 1.0, v57, 1.0
	v_mul_f32_e32 v65, v64, v63
	v_fma_f32 v66, -v62, v65, v64
	v_fmac_f32_e32 v65, v66, v63
	v_fma_f32 v62, -v62, v65, v64
	v_div_fmas_f32 v62, v62, v63, v65
	v_div_fixup_f32 v57, v62, v57, 1.0
	v_div_scale_f32 v62, s[22:23], v56, v56, 1.0
	v_rcp_f32_e32 v63, v62
	v_exp_f32_e32 v41, v41
	v_mul_f32_e32 v36, 0xbfb8aa3b, v36
	v_mul_f32_e32 v37, 0xbfb8aa3b, v37
	v_fma_f32 v64, -v62, v63, 1.0
	v_fmac_f32_e32 v63, v64, v63
	v_div_scale_f32 v64, vcc, 1.0, v56, 1.0
	v_mul_f32_e32 v65, v64, v63
	v_fma_f32 v66, -v62, v65, v64
	v_fmac_f32_e32 v65, v66, v63
	v_fma_f32 v62, -v62, v65, v64
	v_div_fmas_f32 v62, v62, v63, v65
	v_div_fixup_f32 v56, v62, v56, 1.0
	v_cvt_pk_bf16_f32 v56, v56, v57
	v_mul_f32_e32 v57, 0xbfb8aa3b, v58
	v_exp_f32_e32 v58, v57
	v_mul_f32_e32 v57, 0xbfb8aa3b, v59
	v_exp_f32_e32 v59, v57
	v_pk_add_f32 v[40:41], v[40:41], 1.0 op_sel_hi:[1,0]
	v_exp_f32_e32 v36, v36
	v_exp_f32_e32 v37, v37
	v_pk_add_f32 v[58:59], v[58:59], 1.0 op_sel_hi:[1,0]
	v_mul_f32_e32 v32, 0xbfb8aa3b, v32
	v_div_scale_f32 v57, s[22:23], v59, v59, 1.0
	v_rcp_f32_e32 v62, v57
	v_pk_add_f32 v[36:37], v[36:37], 1.0 op_sel_hi:[1,0]
	v_mul_f32_e32 v33, 0xbfb8aa3b, v33
	v_exp_f32_e32 v32, v32
	v_fma_f32 v63, -v57, v62, 1.0
	v_fmac_f32_e32 v62, v63, v62
	v_div_scale_f32 v63, vcc, 1.0, v59, 1.0
	v_mul_f32_e32 v64, v63, v62
	v_fma_f32 v65, -v57, v64, v63
	v_fmac_f32_e32 v64, v65, v62
	v_fma_f32 v57, -v57, v64, v63
	v_div_fmas_f32 v57, v57, v62, v64
	v_div_fixup_f32 v57, v57, v59, 1.0
	v_div_scale_f32 v59, s[22:23], v58, v58, 1.0
	v_rcp_f32_e32 v62, v59
	v_exp_f32_e32 v33, v33
; __device__ __forceinline__ float sigmoidf_(float x) { return 1.f / (1.f + __expf(-x)); }
; __device__ __forceinline__ void phase_merge(const Params& P, u16* sA, u16* sB) {
;     ...
;       for (int mi = 0; mi < 4; mi++)
; #pragma unroll
;         for (int ni = 0; ni < 4; ni++) {
;           f32x4 g = ag[mi][ni];
;           gp[mi][ni] = u32x2{pk2bf(sigmoidf_(g[0]), sigmoidf_(g[1])), pk2bf(sigmoidf_(g[2]), sigmoidf_(g[3]))};
;         }
	v_mul_f32_e32 v28, 0xbfb8aa3b, v28
	v_mul_f32_e32 v29, 0xbfb8aa3b, v29
	v_fma_f32 v63, -v59, v62, 1.0
	v_fmac_f32_e32 v62, v63, v62
	v_div_scale_f32 v63, vcc, 1.0, v58, 1.0
	v_mul_f32_e32 v64, v63, v62
	v_fma_f32 v65, -v59, v64, v63
	v_fmac_f32_e32 v64, v65, v62
	v_fma_f32 v59, -v59, v64, v63
	v_div_fmas_f32 v59, v59, v62, v64
	v_div_fixup_f32 v58, v59, v58, 1.0
	v_cvt_pk_bf16_f32 v57, v58, v57
	v_div_scale_f32 v58, s[22:23], v53, v53, 1.0
	v_rcp_f32_e32 v59, v58
	v_pk_add_f32 v[32:33], v[32:33], 1.0 op_sel_hi:[1,0]
	v_exp_f32_e32 v28, v28
	v_exp_f32_e32 v29, v29
	v_fma_f32 v62, -v58, v59, 1.0
	v_fmac_f32_e32 v59, v62, v59
	v_div_scale_f32 v62, vcc, 1.0, v53, 1.0
	v_mul_f32_e32 v63, v62, v59
	v_fma_f32 v64, -v58, v63, v62
	v_fmac_f32_e32 v63, v64, v59
	v_fma_f32 v58, -v58, v63, v62
	v_div_fmas_f32 v58, v58, v59, v63
	v_div_fixup_f32 v53, v58, v53, 1.0
	v_div_scale_f32 v58, s[22:23], v52, v52, 1.0
	v_rcp_f32_e32 v59, v58
	v_pk_add_f32 v[28:29], v[28:29], 1.0 op_sel_hi:[1,0]
	v_mul_f32_e32 v24, 0xbfb8aa3b, v24
	v_mul_f32_e32 v25, 0xbfb8aa3b, v25
	v_fma_f32 v62, -v58, v59, 1.0
	v_fmac_f32_e32 v59, v62, v59
	v_div_scale_f32 v62, vcc, 1.0, v52, 1.0
	v_mul_f32_e32 v63, v62, v59
	v_fma_f32 v64, -v58, v63, v62
	v_fmac_f32_e32 v63, v64, v59
	v_fma_f32 v58, -v58, v63, v62
	v_div_fmas_f32 v58, v58, v59, v63
	v_div_fixup_f32 v52, v58, v52, 1.0
	v_cvt_pk_bf16_f32 v52, v52, v53
	v_mul_f32_e32 v53, 0xbfb8aa3b, v54
	v_exp_f32_e32 v54, v53
	v_mul_f32_e32 v53, 0xbfb8aa3b, v55
	v_exp_f32_e32 v55, v53
	v_exp_f32_e32 v24, v24
	v_exp_f32_e32 v25, v25
	v_mul_f32_e32 v20, 0xbfb8aa3b, v20
	v_pk_add_f32 v[54:55], v[54:55], 1.0 op_sel_hi:[1,0]
	v_mul_f32_e32 v21, 0xbfb8aa3b, v21
	v_div_scale_f32 v53, s[22:23], v55, v55, 1.0
	v_rcp_f32_e32 v58, v53
	v_pk_add_f32 v[24:25], v[24:25], 1.0 op_sel_hi:[1,0]
	v_exp_f32_e32 v20, v20
	v_exp_f32_e32 v21, v21
	v_fma_f32 v59, -v53, v58, 1.0
	v_fmac_f32_e32 v58, v59, v58
	v_div_scale_f32 v59, vcc, 1.0, v55, 1.0
	v_mul_f32_e32 v62, v59, v58
	v_fma_f32 v63, -v53, v62, v59
	v_fmac_f32_e32 v62, v63, v58
	v_fma_f32 v53, -v53, v62, v59
	v_div_fmas_f32 v53, v53, v58, v62
	v_div_fixup_f32 v53, v53, v55, 1.0
	v_div_scale_f32 v55, s[22:23], v54, v54, 1.0
	v_rcp_f32_e32 v58, v55
	v_pk_add_f32 v[20:21], v[20:21], 1.0 op_sel_hi:[1,0]
	v_mul_f32_e32 v16, 0xbfb8aa3b, v16
	v_mul_f32_e32 v17, 0xbfb8aa3b, v17
	v_fma_f32 v59, -v55, v58, 1.0
	v_fmac_f32_e32 v58, v59, v58
	v_div_scale_f32 v59, vcc, 1.0, v54, 1.0
	v_mul_f32_e32 v62, v59, v58
	v_fma_f32 v63, -v55, v62, v59
	v_fmac_f32_e32 v62, v63, v58
	v_fma_f32 v55, -v55, v62, v59
	v_div_fmas_f32 v55, v55, v58, v62
	v_div_fixup_f32 v54, v55, v54, 1.0
	v_cvt_pk_bf16_f32 v53, v54, v53
	v_div_scale_f32 v54, s[22:23], v49, v49, 1.0
	v_rcp_f32_e32 v55, v54
	v_exp_f32_e32 v16, v16
	v_exp_f32_e32 v17, v17
	v_mul_f32_e32 v12, 0xbfb8aa3b, v12
	v_fma_f32 v58, -v54, v55, 1.0
	v_fmac_f32_e32 v55, v58, v55
	v_div_scale_f32 v58, vcc, 1.0, v49, 1.0
	v_mul_f32_e32 v59, v58, v55
	v_fma_f32 v62, -v54, v59, v58
	v_fmac_f32_e32 v59, v62, v55
	v_fma_f32 v54, -v54, v59, v58
	v_div_fmas_f32 v54, v54, v55, v59
	v_div_fixup_f32 v49, v54, v49, 1.0
	v_div_scale_f32 v54, s[22:23], v48, v48, 1.0
	v_rcp_f32_e32 v55, v54
	v_pk_add_f32 v[16:17], v[16:17], 1.0 op_sel_hi:[1,0]
	v_mul_f32_e32 v13, 0xbfb8aa3b, v13
	v_exp_f32_e32 v12, v12
	v_fma_f32 v58, -v54, v55, 1.0
	v_fmac_f32_e32 v55, v58, v55
	v_div_scale_f32 v58, vcc, 1.0, v48, 1.0
	v_mul_f32_e32 v59, v58, v55
	v_fma_f32 v62, -v54, v59, v58
	v_fmac_f32_e32 v59, v62, v55
	v_fma_f32 v54, -v54, v59, v58
	v_div_fmas_f32 v54, v54, v55, v59
	v_div_fixup_f32 v48, v54, v48, 1.0
	v_cvt_pk_bf16_f32 v54, v48, v49
	v_mul_f32_e32 v48, 0xbfb8aa3b, v50
	v_mul_f32_e32 v49, 0xbfb8aa3b, v51
	v_exp_f32_e32 v48, v48
	v_exp_f32_e32 v49, v49
	v_exp_f32_e32 v13, v13
	v_mul_f32_e32 v8, 0xbfb8aa3b, v8
	v_mul_f32_e32 v9, 0xbfb8aa3b, v9
	v_pk_add_f32 v[48:49], v[48:49], 1.0 op_sel_hi:[1,0]
	v_pk_add_f32 v[12:13], v[12:13], 1.0 op_sel_hi:[1,0]
	v_div_scale_f32 v50, s[22:23], v49, v49, 1.0
	v_rcp_f32_e32 v51, v50
	v_exp_f32_e32 v8, v8
	v_exp_f32_e32 v9, v9
	v_mul_f32_e32 v4, 0xbfb8aa3b, v4
	v_fma_f32 v55, -v50, v51, 1.0
	v_fmac_f32_e32 v51, v55, v51
	v_div_scale_f32 v55, vcc, 1.0, v49, 1.0
	v_mul_f32_e32 v58, v55, v51
	v_fma_f32 v59, -v50, v58, v55
	v_fmac_f32_e32 v58, v59, v51
	v_fma_f32 v50, -v50, v58, v55
	v_div_fmas_f32 v50, v50, v51, v58
	v_div_fixup_f32 v49, v50, v49, 1.0
	v_div_scale_f32 v50, s[22:23], v48, v48, 1.0
	v_rcp_f32_e32 v51, v50
	v_pk_add_f32 v[8:9], v[8:9], 1.0 op_sel_hi:[1,0]
	v_mul_f32_e32 v5, 0xbfb8aa3b, v5
	v_exp_f32_e32 v4, v4
	v_fma_f32 v55, -v50, v51, 1.0
	v_fmac_f32_e32 v51, v55, v51
	v_div_scale_f32 v55, vcc, 1.0, v48, 1.0
	v_mul_f32_e32 v58, v55, v51
	v_fma_f32 v59, -v50, v58, v55
	v_fmac_f32_e32 v58, v59, v51
	v_fma_f32 v50, -v50, v58, v55
	v_div_fmas_f32 v50, v50, v51, v58
	v_div_fixup_f32 v48, v50, v48, 1.0
	v_cvt_pk_bf16_f32 v50, v48, v49
	v_div_scale_f32 v48, s[22:23], v45, v45, 1.0
	v_rcp_f32_e32 v49, v48
	v_exp_f32_e32 v5, v5
	v_mul_f32_e32 v0, 0xbfb8aa3b, v0
	v_mul_f32_e32 v1, 0xbfb8aa3b, v1
	v_fma_f32 v51, -v48, v49, 1.0
	v_fmac_f32_e32 v49, v51, v49
	v_div_scale_f32 v51, vcc, 1.0, v45, 1.0
	v_mul_f32_e32 v55, v51, v49
	v_fma_f32 v58, -v48, v55, v51
	v_fmac_f32_e32 v55, v58, v49
	v_fma_f32 v48, -v48, v55, v51
	v_div_fmas_f32 v48, v48, v49, v55
	v_div_fixup_f32 v45, v48, v45, 1.0
	v_div_scale_f32 v48, s[22:23], v44, v44, 1.0
	v_rcp_f32_e32 v49, v48
	v_pk_add_f32 v[4:5], v[4:5], 1.0 op_sel_hi:[1,0]
	v_exp_f32_e32 v0, v0
	v_exp_f32_e32 v1, v1
	v_fma_f32 v51, -v48, v49, 1.0
	v_fmac_f32_e32 v49, v51, v49
	v_div_scale_f32 v51, vcc, 1.0, v44, 1.0
	v_mul_f32_e32 v55, v51, v49
	v_fma_f32 v58, -v48, v55, v51
	v_fmac_f32_e32 v55, v58, v49
	v_fma_f32 v48, -v48, v55, v51
	v_div_fmas_f32 v48, v48, v49, v55
	v_div_fixup_f32 v44, v48, v44, 1.0
	v_cvt_pk_bf16_f32 v51, v44, v45
	v_mul_f32_e32 v44, 0xbfb8aa3b, v46
	v_mul_f32_e32 v45, 0xbfb8aa3b, v47
	v_exp_f32_e32 v44, v44
	v_exp_f32_e32 v45, v45
	v_pk_add_f32 v[0:1], v[0:1], 1.0 op_sel_hi:[1,0]
	s_waitcnt vmcnt(2)
; __device__ __forceinline__ float sigmoidf_(float x) { return 1.f / (1.f + __expf(-x)); }
; __device__ __forceinline__ void phase_merge(const Params& P, u16* sA, u16* sB) {
;     ...
;       for (int mi = 0; mi < 4; mi++)
; #pragma unroll
;         for (int ni = 0; ni < 4; ni++) {
;           f32x4 g = ag[mi][ni];
;           gp[mi][ni] = u32x2{pk2bf(sigmoidf_(g[0]), sigmoidf_(g[1])), pk2bf(sigmoidf_(g[2]), sigmoidf_(g[3]))};
;         }
;     }
;     f32x4 macc[4];
; #pragma unroll
;     for (int mi = 0; mi < 4; mi++) macc[mi] = f32x4{0.f, 0.f, 0.f, 0.f};
; #pragma unroll
;     for (int i = 0; i < 4; i++) {
;       f32x4 ap[4][1];
;       zero_acc<1>(ap);
;       gemm_main<1>(Y + i * 256, 1024, (const u16*)(ws + O_WB) + (size_t)i * 1024 * 256, 256, 256, m0, n0, ap, sA, sB);
	v_mov_b32_e32 v82, v169
	v_pk_add_f32 v[44:45], v[44:45], 1.0 op_sel_hi:[1,0]
	v_lshlrev_b32_e32 v83, 4, v82
	v_div_scale_f32 v46, s[22:23], v45, v45, 1.0
	v_rcp_f32_e32 v47, v46
	v_and_b32_e32 v130, 0x70, v83
	v_lshrrev_b32_e32 v84, 4, v82
	v_xor_b32_e32 v85, v84, v82
	v_fma_f32 v48, -v46, v47, 1.0
	v_fmac_f32_e32 v47, v48, v47
	v_div_scale_f32 v48, vcc, 1.0, v45, 1.0
	v_mul_f32_e32 v49, v48, v47
	v_fma_f32 v55, -v46, v49, v48
	v_fmac_f32_e32 v49, v55, v47
	v_fma_f32 v46, -v46, v49, v48
	v_div_fmas_f32 v46, v46, v47, v49
	v_div_fixup_f32 v45, v46, v45, 1.0
	v_div_scale_f32 v46, s[22:23], v44, v44, 1.0
	v_rcp_f32_e32 v47, v46
	v_lshlrev_b32_e32 v85, 4, v85
	v_and_b32_e32 v85, 0x70, v85
	v_and_b32_e32 v86, 15, v82
	v_fma_f32 v48, -v46, v47, 1.0
	v_fmac_f32_e32 v47, v48, v47
	v_div_scale_f32 v48, vcc, 1.0, v44, 1.0
	v_mul_f32_e32 v49, v48, v47
	v_fma_f32 v55, -v46, v49, v48
	v_fmac_f32_e32 v49, v55, v47
	v_fma_f32 v46, -v46, v49, v48
	v_div_fmas_f32 v46, v46, v47, v49
	v_div_fixup_f32 v44, v46, v44, 1.0
	v_cvt_pk_bf16_f32 v55, v44, v45
	v_div_scale_f32 v44, s[22:23], v41, v41, 1.0
	v_rcp_f32_e32 v45, v44
	v_bfe_u32 v87, v82, 1, 3
	v_lshlrev_b32_e32 v86, 7, v86
	s_movk_i32 s21, 0x800
	v_fma_f32 v46, -v44, v45, 1.0
	v_fmac_f32_e32 v45, v46, v45
	v_div_scale_f32 v46, vcc, 1.0, v41, 1.0
	v_mul_f32_e32 v47, v46, v45
	v_fma_f32 v48, -v44, v47, v46
	v_fmac_f32_e32 v47, v48, v45
	v_fma_f32 v44, -v44, v47, v46
	v_div_fmas_f32 v44, v44, v45, v47
	v_div_fixup_f32 v41, v44, v41, 1.0
	v_div_scale_f32 v44, s[22:23], v40, v40, 1.0
	v_rcp_f32_e32 v45, v44
	v_bitop3_b32 v84, v84, v87, 3 bitop3:0x6c
	v_lshlrev_b32_e32 v84, 4, v84
	v_fma_f32 v46, -v44, v45, 1.0
	v_fmac_f32_e32 v45, v46, v45
	v_div_scale_f32 v46, vcc, 1.0, v40, 1.0
	v_mul_f32_e32 v47, v46, v45
	v_fma_f32 v48, -v44, v47, v46
	v_fmac_f32_e32 v47, v48, v45
	v_fma_f32 v44, -v44, v47, v46
	v_div_fmas_f32 v44, v44, v45, v47
	v_div_fixup_f32 v40, v44, v40, 1.0
	v_cvt_pk_bf16_f32 v58, v40, v41
	v_mul_f32_e32 v40, 0xbfb8aa3b, v42
	v_mul_f32_e32 v41, 0xbfb8aa3b, v43
	v_exp_f32_e32 v40, v40
	v_exp_f32_e32 v41, v41
	s_nop 0
	v_pk_add_f32 v[40:41], v[40:41], 1.0 op_sel_hi:[1,0]
	s_nop 0
	v_div_scale_f32 v42, s[22:23], v41, v41, 1.0
	v_rcp_f32_e32 v43, v42
	s_nop 0
	v_fma_f32 v44, -v42, v43, 1.0
	v_fmac_f32_e32 v43, v44, v43
	v_div_scale_f32 v44, vcc, 1.0, v41, 1.0
	v_mul_f32_e32 v45, v44, v43
	v_fma_f32 v46, -v42, v45, v44
	v_fmac_f32_e32 v45, v46, v43
	v_fma_f32 v42, -v42, v45, v44
	v_div_fmas_f32 v42, v42, v43, v45
	v_div_fixup_f32 v41, v42, v41, 1.0
	v_div_scale_f32 v42, s[22:23], v40, v40, 1.0
	v_rcp_f32_e32 v43, v42
	s_nop 0
	v_fma_f32 v44, -v42, v43, 1.0
	v_fmac_f32_e32 v43, v44, v43
	v_div_scale_f32 v44, vcc, 1.0, v40, 1.0
	v_mul_f32_e32 v45, v44, v43
	v_fma_f32 v46, -v42, v45, v44
	v_fmac_f32_e32 v45, v46, v43
	v_fma_f32 v42, -v42, v45, v44
	v_div_fmas_f32 v42, v42, v43, v45
	v_div_fixup_f32 v40, v42, v40, 1.0
	v_cvt_pk_bf16_f32 v59, v40, v41
	v_div_scale_f32 v40, s[22:23], v37, v37, 1.0
	v_rcp_f32_e32 v41, v40
	s_nop 0
	v_fma_f32 v42, -v40, v41, 1.0
	v_fmac_f32_e32 v41, v42, v41
	v_div_scale_f32 v42, vcc, 1.0, v37, 1.0
	v_mul_f32_e32 v43, v42, v41
	v_fma_f32 v44, -v40, v43, v42
	v_fmac_f32_e32 v43, v44, v41
	v_fma_f32 v40, -v40, v43, v42
	v_div_fmas_f32 v40, v40, v41, v43
	v_div_fixup_f32 v37, v40, v37, 1.0
	v_div_scale_f32 v40, s[22:23], v36, v36, 1.0
	v_rcp_f32_e32 v41, v40
	s_nop 0
	v_fma_f32 v42, -v40, v41, 1.0
	v_fmac_f32_e32 v41, v42, v41
	v_div_scale_f32 v42, vcc, 1.0, v36, 1.0
	v_mul_f32_e32 v43, v42, v41
	v_fma_f32 v44, -v40, v43, v42
	v_fmac_f32_e32 v43, v44, v41
	v_fma_f32 v40, -v40, v43, v42
	v_div_fmas_f32 v40, v40, v41, v43
	v_div_fixup_f32 v36, v40, v36, 1.0
	v_cvt_pk_bf16_f32 v62, v36, v37
	v_mul_f32_e32 v36, 0xbfb8aa3b, v38
	v_mul_f32_e32 v37, 0xbfb8aa3b, v39
	v_exp_f32_e32 v36, v36
	v_exp_f32_e32 v37, v37
	s_nop 0
	v_pk_add_f32 v[36:37], v[36:37], 1.0 op_sel_hi:[1,0]
	s_nop 0
	v_div_scale_f32 v38, s[22:23], v37, v37, 1.0
	v_rcp_f32_e32 v39, v38
	s_nop 0
	v_fma_f32 v40, -v38, v39, 1.0
	v_fmac_f32_e32 v39, v40, v39
	v_div_scale_f32 v40, vcc, 1.0, v37, 1.0
	v_mul_f32_e32 v41, v40, v39
	v_fma_f32 v42, -v38, v41, v40
	v_fmac_f32_e32 v41, v42, v39
	v_fma_f32 v38, -v38, v41, v40
	v_div_fmas_f32 v38, v38, v39, v41
	v_div_fixup_f32 v37, v38, v37, 1.0
	v_div_scale_f32 v38, s[22:23], v36, v36, 1.0
	v_rcp_f32_e32 v39, v38
	s_nop 0
	v_fma_f32 v40, -v38, v39, 1.0
	v_fmac_f32_e32 v39, v40, v39
	v_div_scale_f32 v40, vcc, 1.0, v36, 1.0
	v_mul_f32_e32 v41, v40, v39
	v_fma_f32 v42, -v38, v41, v40
	v_fmac_f32_e32 v41, v42, v39
	v_fma_f32 v38, -v38, v41, v40
	v_div_fmas_f32 v38, v38, v39, v41
	v_div_fixup_f32 v36, v38, v36, 1.0
	v_cvt_pk_bf16_f32 v63, v36, v37
	v_div_scale_f32 v36, s[22:23], v33, v33, 1.0
	v_rcp_f32_e32 v37, v36
	s_nop 0
	v_fma_f32 v38, -v36, v37, 1.0
	v_fmac_f32_e32 v37, v38, v37
	v_div_scale_f32 v38, vcc, 1.0, v33, 1.0
	v_mul_f32_e32 v39, v38, v37
	v_fma_f32 v40, -v36, v39, v38
	v_fmac_f32_e32 v39, v40, v37
	v_fma_f32 v36, -v36, v39, v38
	v_div_fmas_f32 v36, v36, v37, v39
	v_div_fixup_f32 v33, v36, v33, 1.0
	v_div_scale_f32 v36, s[22:23], v32, v32, 1.0
	v_rcp_f32_e32 v37, v36
	s_nop 0
	v_fma_f32 v38, -v36, v37, 1.0
	v_fmac_f32_e32 v37, v38, v37
	v_div_scale_f32 v38, vcc, 1.0, v32, 1.0
	v_mul_f32_e32 v39, v38, v37
	v_fma_f32 v40, -v36, v39, v38
	v_fmac_f32_e32 v39, v40, v37
	v_fma_f32 v36, -v36, v39, v38
	v_div_fmas_f32 v36, v36, v37, v39
	v_div_fixup_f32 v32, v36, v32, 1.0
	v_cvt_pk_bf16_f32 v64, v32, v33
	v_mul_f32_e32 v32, 0xbfb8aa3b, v34
	v_mul_f32_e32 v33, 0xbfb8aa3b, v35
	v_exp_f32_e32 v32, v32
	v_exp_f32_e32 v33, v33
	s_nop 0
	v_pk_add_f32 v[32:33], v[32:33], 1.0 op_sel_hi:[1,0]
; __device__ __forceinline__ float sigmoidf_(float x) { return 1.f / (1.f + __expf(-x)); }
; __device__ __forceinline__ void phase_merge(const Params& P, u16* sA, u16* sB) {
;     ...
;       for (int mi = 0; mi < 4; mi++)
; #pragma unroll
;         for (int ni = 0; ni < 4; ni++) {
;           f32x4 g = ag[mi][ni];
;           gp[mi][ni] = u32x2{pk2bf(sigmoidf_(g[0]), sigmoidf_(g[1])), pk2bf(sigmoidf_(g[2]), sigmoidf_(g[3]))};
;         }
	s_nop 0
	v_div_scale_f32 v34, s[22:23], v33, v33, 1.0
	v_rcp_f32_e32 v35, v34
	s_nop 0
	v_fma_f32 v36, -v34, v35, 1.0
	v_fmac_f32_e32 v35, v36, v35
	v_div_scale_f32 v36, vcc, 1.0, v33, 1.0
	v_mul_f32_e32 v37, v36, v35
	v_fma_f32 v38, -v34, v37, v36
	v_fmac_f32_e32 v37, v38, v35
	v_fma_f32 v34, -v34, v37, v36
	v_div_fmas_f32 v34, v34, v35, v37
	v_div_fixup_f32 v33, v34, v33, 1.0
	v_div_scale_f32 v34, s[22:23], v32, v32, 1.0
	v_rcp_f32_e32 v35, v34
	s_nop 0
	v_fma_f32 v36, -v34, v35, 1.0
	v_fmac_f32_e32 v35, v36, v35
	v_div_scale_f32 v36, vcc, 1.0, v32, 1.0
	v_mul_f32_e32 v37, v36, v35
	v_fma_f32 v38, -v34, v37, v36
	v_fmac_f32_e32 v37, v38, v35
	v_fma_f32 v34, -v34, v37, v36
	v_div_fmas_f32 v34, v34, v35, v37
	v_div_fixup_f32 v32, v34, v32, 1.0
	v_cvt_pk_bf16_f32 v65, v32, v33
	v_div_scale_f32 v32, s[22:23], v29, v29, 1.0
	v_rcp_f32_e32 v33, v32
	s_nop 0
	v_fma_f32 v34, -v32, v33, 1.0
	v_fmac_f32_e32 v33, v34, v33
	v_div_scale_f32 v34, vcc, 1.0, v29, 1.0
	v_mul_f32_e32 v35, v34, v33
	v_fma_f32 v36, -v32, v35, v34
	v_fmac_f32_e32 v35, v36, v33
	v_fma_f32 v32, -v32, v35, v34
	v_div_fmas_f32 v32, v32, v33, v35
	v_div_fixup_f32 v29, v32, v29, 1.0
	v_div_scale_f32 v32, s[22:23], v28, v28, 1.0
	v_rcp_f32_e32 v33, v32
	s_nop 0
	v_fma_f32 v34, -v32, v33, 1.0
	v_fmac_f32_e32 v33, v34, v33
	v_div_scale_f32 v34, vcc, 1.0, v28, 1.0
	v_mul_f32_e32 v35, v34, v33
	v_fma_f32 v36, -v32, v35, v34
	v_fmac_f32_e32 v35, v36, v33
	v_fma_f32 v32, -v32, v35, v34
	v_div_fmas_f32 v32, v32, v33, v35
	v_div_fixup_f32 v28, v32, v28, 1.0
	v_cvt_pk_bf16_f32 v66, v28, v29
	v_mul_f32_e32 v28, 0xbfb8aa3b, v30
	v_mul_f32_e32 v29, 0xbfb8aa3b, v31
	v_exp_f32_e32 v28, v28
	v_exp_f32_e32 v29, v29
	s_nop 0
	v_pk_add_f32 v[28:29], v[28:29], 1.0 op_sel_hi:[1,0]
	s_nop 0
	v_div_scale_f32 v30, s[22:23], v29, v29, 1.0
	v_rcp_f32_e32 v31, v30
	s_nop 0
	v_fma_f32 v32, -v30, v31, 1.0
	v_fmac_f32_e32 v31, v32, v31
	v_div_scale_f32 v32, vcc, 1.0, v29, 1.0
	v_mul_f32_e32 v33, v32, v31
	v_fma_f32 v34, -v30, v33, v32
	v_fmac_f32_e32 v33, v34, v31
	v_fma_f32 v30, -v30, v33, v32
	v_div_fmas_f32 v30, v30, v31, v33
	v_div_fixup_f32 v29, v30, v29, 1.0
	v_div_scale_f32 v30, s[22:23], v28, v28, 1.0
	v_rcp_f32_e32 v31, v30
	s_nop 0
	v_fma_f32 v32, -v30, v31, 1.0
	v_fmac_f32_e32 v31, v32, v31
	v_div_scale_f32 v32, vcc, 1.0, v28, 1.0
	v_mul_f32_e32 v33, v32, v31
	v_fma_f32 v34, -v30, v33, v32
	v_fmac_f32_e32 v33, v34, v31
	v_fma_f32 v30, -v30, v33, v32
	v_div_fmas_f32 v30, v30, v31, v33
	v_div_fixup_f32 v28, v30, v28, 1.0
	v_cvt_pk_bf16_f32 v67, v28, v29
	v_div_scale_f32 v28, s[22:23], v25, v25, 1.0
	v_rcp_f32_e32 v29, v28
	s_nop 0
	v_fma_f32 v30, -v28, v29, 1.0
	v_fmac_f32_e32 v29, v30, v29
	v_div_scale_f32 v30, vcc, 1.0, v25, 1.0
	v_mul_f32_e32 v31, v30, v29
	v_fma_f32 v32, -v28, v31, v30
	v_fmac_f32_e32 v31, v32, v29
	v_fma_f32 v28, -v28, v31, v30
	v_div_fmas_f32 v28, v28, v29, v31
	v_div_fixup_f32 v25, v28, v25, 1.0
	v_div_scale_f32 v28, s[22:23], v24, v24, 1.0
	v_rcp_f32_e32 v29, v28
	s_nop 0
	v_fma_f32 v30, -v28, v29, 1.0
	v_fmac_f32_e32 v29, v30, v29
	v_div_scale_f32 v30, vcc, 1.0, v24, 1.0
	v_mul_f32_e32 v31, v30, v29
	v_fma_f32 v32, -v28, v31, v30
	v_fmac_f32_e32 v31, v32, v29
	v_fma_f32 v28, -v28, v31, v30
	v_div_fmas_f32 v28, v28, v29, v31
	v_div_fixup_f32 v24, v28, v24, 1.0
	v_cvt_pk_bf16_f32 v68, v24, v25
	v_mul_f32_e32 v24, 0xbfb8aa3b, v26
	v_mul_f32_e32 v25, 0xbfb8aa3b, v27
	v_exp_f32_e32 v24, v24
	v_exp_f32_e32 v25, v25
	s_nop 0
	v_pk_add_f32 v[24:25], v[24:25], 1.0 op_sel_hi:[1,0]
	s_nop 0
	v_div_scale_f32 v26, s[22:23], v25, v25, 1.0
	v_rcp_f32_e32 v27, v26
	s_nop 0
	v_fma_f32 v28, -v26, v27, 1.0
	v_fmac_f32_e32 v27, v28, v27
	v_div_scale_f32 v28, vcc, 1.0, v25, 1.0
	v_mul_f32_e32 v29, v28, v27
	v_fma_f32 v30, -v26, v29, v28
	v_fmac_f32_e32 v29, v30, v27
	v_fma_f32 v26, -v26, v29, v28
	v_div_fmas_f32 v26, v26, v27, v29
	v_div_fixup_f32 v25, v26, v25, 1.0
	v_div_scale_f32 v26, s[22:23], v24, v24, 1.0
	v_rcp_f32_e32 v27, v26
	s_nop 0
	v_fma_f32 v28, -v26, v27, 1.0
	v_fmac_f32_e32 v27, v28, v27
	v_div_scale_f32 v28, vcc, 1.0, v24, 1.0
	v_mul_f32_e32 v29, v28, v27
	v_fma_f32 v30, -v26, v29, v28
	v_fmac_f32_e32 v29, v30, v27
	v_fma_f32 v26, -v26, v29, v28
	v_div_fmas_f32 v26, v26, v27, v29
	v_div_fixup_f32 v24, v26, v24, 1.0
	v_cvt_pk_bf16_f32 v69, v24, v25
	v_div_scale_f32 v24, s[22:23], v21, v21, 1.0
	v_rcp_f32_e32 v25, v24
	s_nop 0
	v_fma_f32 v26, -v24, v25, 1.0
	v_fmac_f32_e32 v25, v26, v25
	v_div_scale_f32 v26, vcc, 1.0, v21, 1.0
	v_mul_f32_e32 v27, v26, v25
	v_fma_f32 v28, -v24, v27, v26
	v_fmac_f32_e32 v27, v28, v25
	v_fma_f32 v24, -v24, v27, v26
	v_div_fmas_f32 v24, v24, v25, v27
	v_div_fixup_f32 v21, v24, v21, 1.0
	v_div_scale_f32 v24, s[22:23], v20, v20, 1.0
	v_rcp_f32_e32 v25, v24
	s_nop 0
	v_fma_f32 v26, -v24, v25, 1.0
	v_fmac_f32_e32 v25, v26, v25
	v_div_scale_f32 v26, vcc, 1.0, v20, 1.0
	v_mul_f32_e32 v27, v26, v25
	v_fma_f32 v28, -v24, v27, v26
	v_fmac_f32_e32 v27, v28, v25
	v_fma_f32 v24, -v24, v27, v26
	v_div_fmas_f32 v24, v24, v25, v27
	v_div_fixup_f32 v20, v24, v20, 1.0
	v_cvt_pk_bf16_f32 v70, v20, v21
	v_mul_f32_e32 v20, 0xbfb8aa3b, v22
	v_mul_f32_e32 v21, 0xbfb8aa3b, v23
	v_exp_f32_e32 v20, v20
	v_exp_f32_e32 v21, v21
	s_nop 0
	v_pk_add_f32 v[20:21], v[20:21], 1.0 op_sel_hi:[1,0]
	s_nop 0
	v_div_scale_f32 v22, s[22:23], v21, v21, 1.0
	v_rcp_f32_e32 v23, v22
	s_nop 0
	v_fma_f32 v24, -v22, v23, 1.0
	v_fmac_f32_e32 v23, v24, v23
	v_div_scale_f32 v24, vcc, 1.0, v21, 1.0
	v_mul_f32_e32 v25, v24, v23
	v_fma_f32 v26, -v22, v25, v24
	v_fmac_f32_e32 v25, v26, v23
	v_fma_f32 v22, -v22, v25, v24
	v_div_fmas_f32 v22, v22, v23, v25
	v_div_fixup_f32 v21, v22, v21, 1.0
; __device__ __forceinline__ float sigmoidf_(float x) { return 1.f / (1.f + __expf(-x)); }
; __device__ __forceinline__ void phase_merge(const Params& P, u16* sA, u16* sB) {
;     ...
;       for (int mi = 0; mi < 4; mi++)
; #pragma unroll
;         for (int ni = 0; ni < 4; ni++) {
;           f32x4 g = ag[mi][ni];
;           gp[mi][ni] = u32x2{pk2bf(sigmoidf_(g[0]), sigmoidf_(g[1])), pk2bf(sigmoidf_(g[2]), sigmoidf_(g[3]))};
;         }
	v_div_scale_f32 v22, s[22:23], v20, v20, 1.0
	v_rcp_f32_e32 v23, v22
	s_nop 0
	v_fma_f32 v24, -v22, v23, 1.0
	v_fmac_f32_e32 v23, v24, v23
	v_div_scale_f32 v24, vcc, 1.0, v20, 1.0
	v_mul_f32_e32 v25, v24, v23
	v_fma_f32 v26, -v22, v25, v24
	v_fmac_f32_e32 v25, v26, v23
	v_fma_f32 v22, -v22, v25, v24
	v_div_fmas_f32 v22, v22, v23, v25
	v_div_fixup_f32 v20, v22, v20, 1.0
	v_cvt_pk_bf16_f32 v71, v20, v21
	v_div_scale_f32 v20, s[22:23], v17, v17, 1.0
	v_rcp_f32_e32 v21, v20
	s_nop 0
	v_fma_f32 v22, -v20, v21, 1.0
	v_fmac_f32_e32 v21, v22, v21
	v_div_scale_f32 v22, vcc, 1.0, v17, 1.0
	v_mul_f32_e32 v23, v22, v21
	v_fma_f32 v24, -v20, v23, v22
	v_fmac_f32_e32 v23, v24, v21
	v_fma_f32 v20, -v20, v23, v22
	v_div_fmas_f32 v20, v20, v21, v23
	v_div_fixup_f32 v17, v20, v17, 1.0
	v_div_scale_f32 v20, s[22:23], v16, v16, 1.0
	v_rcp_f32_e32 v21, v20
	s_nop 0
	v_fma_f32 v22, -v20, v21, 1.0
	v_fmac_f32_e32 v21, v22, v21
	v_div_scale_f32 v22, vcc, 1.0, v16, 1.0
	v_mul_f32_e32 v23, v22, v21
	v_fma_f32 v24, -v20, v23, v22
	v_fmac_f32_e32 v23, v24, v21
	v_fma_f32 v20, -v20, v23, v22
	v_div_fmas_f32 v20, v20, v21, v23
	v_div_fixup_f32 v16, v20, v16, 1.0
	v_cvt_pk_bf16_f32 v72, v16, v17
	v_mul_f32_e32 v16, 0xbfb8aa3b, v18
	v_mul_f32_e32 v17, 0xbfb8aa3b, v19
	v_exp_f32_e32 v16, v16
	v_exp_f32_e32 v17, v17
	s_nop 0
	v_pk_add_f32 v[16:17], v[16:17], 1.0 op_sel_hi:[1,0]
	s_nop 0
	v_div_scale_f32 v18, s[22:23], v17, v17, 1.0
	v_rcp_f32_e32 v19, v18
	s_nop 0
	v_fma_f32 v20, -v18, v19, 1.0
	v_fmac_f32_e32 v19, v20, v19
	v_div_scale_f32 v20, vcc, 1.0, v17, 1.0
	v_mul_f32_e32 v21, v20, v19
	v_fma_f32 v22, -v18, v21, v20
	v_fmac_f32_e32 v21, v22, v19
	v_fma_f32 v18, -v18, v21, v20
	v_div_fmas_f32 v18, v18, v19, v21
	v_div_fixup_f32 v17, v18, v17, 1.0
	v_div_scale_f32 v18, s[22:23], v16, v16, 1.0
	v_rcp_f32_e32 v19, v18
	s_nop 0
	v_fma_f32 v20, -v18, v19, 1.0
	v_fmac_f32_e32 v19, v20, v19
	v_div_scale_f32 v20, vcc, 1.0, v16, 1.0
	v_mul_f32_e32 v21, v20, v19
	v_fma_f32 v22, -v18, v21, v20
	v_fmac_f32_e32 v21, v22, v19
	v_fma_f32 v18, -v18, v21, v20
	v_div_fmas_f32 v18, v18, v19, v21
	v_div_fixup_f32 v16, v18, v16, 1.0
	v_cvt_pk_bf16_f32 v73, v16, v17
	v_div_scale_f32 v16, s[22:23], v13, v13, 1.0
	v_rcp_f32_e32 v17, v16
	s_nop 0
	v_fma_f32 v18, -v16, v17, 1.0
	v_fmac_f32_e32 v17, v18, v17
	v_div_scale_f32 v18, vcc, 1.0, v13, 1.0
	v_mul_f32_e32 v19, v18, v17
	v_fma_f32 v20, -v16, v19, v18
	v_fmac_f32_e32 v19, v20, v17
	v_fma_f32 v16, -v16, v19, v18
	v_div_fmas_f32 v16, v16, v17, v19
	v_div_fixup_f32 v13, v16, v13, 1.0
	v_div_scale_f32 v16, s[22:23], v12, v12, 1.0
	v_rcp_f32_e32 v17, v16
	s_nop 0
	v_fma_f32 v18, -v16, v17, 1.0
	v_fmac_f32_e32 v17, v18, v17
	v_div_scale_f32 v18, vcc, 1.0, v12, 1.0
	v_mul_f32_e32 v19, v18, v17
	v_fma_f32 v20, -v16, v19, v18
	v_fmac_f32_e32 v19, v20, v17
	v_fma_f32 v16, -v16, v19, v18
	v_div_fmas_f32 v16, v16, v17, v19
	v_div_fixup_f32 v12, v16, v12, 1.0
	v_cvt_pk_bf16_f32 v74, v12, v13
	v_mul_f32_e32 v12, 0xbfb8aa3b, v14
	v_mul_f32_e32 v13, 0xbfb8aa3b, v15
	v_exp_f32_e32 v12, v12
	v_exp_f32_e32 v13, v13
	s_nop 0
	v_pk_add_f32 v[12:13], v[12:13], 1.0 op_sel_hi:[1,0]
	s_nop 0
	v_div_scale_f32 v14, s[22:23], v13, v13, 1.0
	v_rcp_f32_e32 v15, v14
	s_nop 0
	v_fma_f32 v16, -v14, v15, 1.0
	v_fmac_f32_e32 v15, v16, v15
	v_div_scale_f32 v16, vcc, 1.0, v13, 1.0
	v_mul_f32_e32 v17, v16, v15
	v_fma_f32 v18, -v14, v17, v16
	v_fmac_f32_e32 v17, v18, v15
	v_fma_f32 v14, -v14, v17, v16
	v_div_fmas_f32 v14, v14, v15, v17
	v_div_fixup_f32 v13, v14, v13, 1.0
	v_div_scale_f32 v14, s[22:23], v12, v12, 1.0
	v_rcp_f32_e32 v15, v14
	s_nop 0
	v_fma_f32 v16, -v14, v15, 1.0
	v_fmac_f32_e32 v15, v16, v15
	v_div_scale_f32 v16, vcc, 1.0, v12, 1.0
	v_mul_f32_e32 v17, v16, v15
	v_fma_f32 v18, -v14, v17, v16
	v_fmac_f32_e32 v17, v18, v15
	v_fma_f32 v14, -v14, v17, v16
	v_div_fmas_f32 v14, v14, v15, v17
	v_div_fixup_f32 v12, v14, v12, 1.0
	v_cvt_pk_bf16_f32 v75, v12, v13
	v_div_scale_f32 v12, s[22:23], v9, v9, 1.0
	v_rcp_f32_e32 v13, v12
	s_nop 0
	v_fma_f32 v14, -v12, v13, 1.0
	v_fmac_f32_e32 v13, v14, v13
	v_div_scale_f32 v14, vcc, 1.0, v9, 1.0
	v_mul_f32_e32 v15, v14, v13
	v_fma_f32 v16, -v12, v15, v14
	v_fmac_f32_e32 v15, v16, v13
	v_fma_f32 v12, -v12, v15, v14
	v_div_fmas_f32 v12, v12, v13, v15
	v_div_fixup_f32 v9, v12, v9, 1.0
	v_div_scale_f32 v12, s[22:23], v8, v8, 1.0
	v_rcp_f32_e32 v13, v12
	s_nop 0
	v_fma_f32 v14, -v12, v13, 1.0
	v_fmac_f32_e32 v13, v14, v13
	v_div_scale_f32 v14, vcc, 1.0, v8, 1.0
	v_mul_f32_e32 v15, v14, v13
	v_fma_f32 v16, -v12, v15, v14
	v_fmac_f32_e32 v15, v16, v13
	v_fma_f32 v12, -v12, v15, v14
	v_div_fmas_f32 v12, v12, v13, v15
	v_div_fixup_f32 v8, v12, v8, 1.0
	v_cvt_pk_bf16_f32 v76, v8, v9
	v_mul_f32_e32 v8, 0xbfb8aa3b, v10
	v_mul_f32_e32 v9, 0xbfb8aa3b, v11
	v_exp_f32_e32 v8, v8
	v_exp_f32_e32 v9, v9
	s_nop 0
	v_pk_add_f32 v[8:9], v[8:9], 1.0 op_sel_hi:[1,0]
	s_nop 0
	v_div_scale_f32 v10, s[22:23], v9, v9, 1.0
	v_rcp_f32_e32 v11, v10
	s_nop 0
	v_fma_f32 v12, -v10, v11, 1.0
	v_fmac_f32_e32 v11, v12, v11
	v_div_scale_f32 v12, vcc, 1.0, v9, 1.0
	v_mul_f32_e32 v13, v12, v11
	v_fma_f32 v14, -v10, v13, v12
	v_fmac_f32_e32 v13, v14, v11
	v_fma_f32 v10, -v10, v13, v12
	v_div_fmas_f32 v10, v10, v11, v13
	v_div_fixup_f32 v9, v10, v9, 1.0
	v_div_scale_f32 v10, s[22:23], v8, v8, 1.0
	v_rcp_f32_e32 v11, v10
	s_nop 0
	v_fma_f32 v12, -v10, v11, 1.0
	v_fmac_f32_e32 v11, v12, v11
	v_div_scale_f32 v12, vcc, 1.0, v8, 1.0
	v_mul_f32_e32 v13, v12, v11
	v_fma_f32 v14, -v10, v13, v12
	v_fmac_f32_e32 v13, v14, v11
	v_fma_f32 v10, -v10, v13, v12
	v_div_fmas_f32 v10, v10, v11, v13
	v_div_fixup_f32 v8, v10, v8, 1.0
	v_cvt_pk_bf16_f32 v77, v8, v9
; __device__ __forceinline__ float sigmoidf_(float x) { return 1.f / (1.f + __expf(-x)); }
; #define GLOAD(ra, rb, koff)                                                        \
;   {                                                                                \
;     _Pragma("unroll") for (int j = 0; j < 4; j++) ra[j] = *(const u32x4*)(pa + j * sa32 + (koff));   \
;     _Pragma("unroll") for (int j = 0; j < NB_; j++) rb[j] = *(const u32x4*)(pbv[j] + (koff));         \
;   }
; template <int NT, bool PRE> ...
;     ...
;   const int wsw = ((tid & 7) ^ ((tid >> 4) & 7)) * 8;
;   const int rsw = (lane & 15) >> 1;
;     ...
;   if (!PRE) {
;     GLOAD(ra0, rb0, 0);
;     GLOAD(ra1, rb1, 64);
;   }
;   __syncthreads();
;   for (int k0 = 0; k0 < K; k0 += 128) {
;     LSTORE(ra0, rb0, 0);
;     __syncthreads();
; __device__ __forceinline__ void phase_merge(const Params& P, u16* sA, u16* sB) {
;     ...
;       for (int mi = 0; mi < 4; mi++)
; #pragma unroll
;         for (int ni = 0; ni < 4; ni++) {
;           f32x4 g = ag[mi][ni];
;           gp[mi][ni] = u32x2{pk2bf(sigmoidf_(g[0]), sigmoidf_(g[1])), pk2bf(sigmoidf_(g[2]), sigmoidf_(g[3]))};
;         }
;     }
;     f32x4 macc[4];
; #pragma unroll
;     for (int mi = 0; mi < 4; mi++) macc[mi] = f32x4{0.f, 0.f, 0.f, 0.f};
; #pragma unroll
;     for (int i = 0; i < 4; i++) {
;       f32x4 ap[4][1];
;       zero_acc<1>(ap);
;       gemm_main<1>(Y + i * 256, 1024, (const u16*)(ws + O_WB) + (size_t)i * 1024 * 256, 256, 256, m0, n0, ap, sA, sB);
	v_div_scale_f32 v8, s[22:23], v5, v5, 1.0
	v_rcp_f32_e32 v9, v8
	s_nop 0
	v_fma_f32 v10, -v8, v9, 1.0
	v_fmac_f32_e32 v9, v10, v9
	v_div_scale_f32 v10, vcc, 1.0, v5, 1.0
	v_mul_f32_e32 v11, v10, v9
	v_fma_f32 v12, -v8, v11, v10
	v_fmac_f32_e32 v11, v12, v9
	v_fma_f32 v8, -v8, v11, v10
	v_div_fmas_f32 v8, v8, v9, v11
	v_div_fixup_f32 v5, v8, v5, 1.0
	v_div_scale_f32 v8, s[22:23], v4, v4, 1.0
	v_rcp_f32_e32 v9, v8
	s_nop 0
	v_fma_f32 v10, -v8, v9, 1.0
	v_fmac_f32_e32 v9, v10, v9
	v_div_scale_f32 v10, vcc, 1.0, v4, 1.0
	v_mul_f32_e32 v11, v10, v9
	v_fma_f32 v12, -v8, v11, v10
	v_fmac_f32_e32 v11, v12, v9
	v_fma_f32 v8, -v8, v11, v10
	v_div_fmas_f32 v8, v8, v9, v11
	v_div_fixup_f32 v4, v8, v4, 1.0
	v_cvt_pk_bf16_f32 v78, v4, v5
	v_mul_f32_e32 v4, 0xbfb8aa3b, v6
	v_mul_f32_e32 v5, 0xbfb8aa3b, v7
	v_exp_f32_e32 v4, v4
	v_exp_f32_e32 v5, v5
	s_nop 0
	v_pk_add_f32 v[4:5], v[4:5], 1.0 op_sel_hi:[1,0]
	s_nop 0
	v_div_scale_f32 v6, s[22:23], v5, v5, 1.0
	v_rcp_f32_e32 v7, v6
	s_nop 0
	v_fma_f32 v8, -v6, v7, 1.0
	v_fmac_f32_e32 v7, v8, v7
	v_div_scale_f32 v8, vcc, 1.0, v5, 1.0
	v_mul_f32_e32 v9, v8, v7
	v_fma_f32 v10, -v6, v9, v8
	v_fmac_f32_e32 v9, v10, v7
	v_fma_f32 v6, -v6, v9, v8
	v_div_fmas_f32 v6, v6, v7, v9
	v_div_fixup_f32 v5, v6, v5, 1.0
	v_div_scale_f32 v6, s[22:23], v4, v4, 1.0
	v_rcp_f32_e32 v7, v6
	s_nop 0
	v_fma_f32 v8, -v6, v7, 1.0
	v_fmac_f32_e32 v7, v8, v7
	v_div_scale_f32 v8, vcc, 1.0, v4, 1.0
	v_mul_f32_e32 v9, v8, v7
	v_fma_f32 v10, -v6, v9, v8
	v_fmac_f32_e32 v9, v10, v7
	v_fma_f32 v6, -v6, v9, v8
	v_div_fmas_f32 v6, v6, v7, v9
	v_div_fixup_f32 v4, v6, v4, 1.0
	v_cvt_pk_bf16_f32 v79, v4, v5
	v_div_scale_f32 v4, s[22:23], v1, v1, 1.0
	v_rcp_f32_e32 v5, v4
	s_nop 0
	v_fma_f32 v6, -v4, v5, 1.0
	v_fmac_f32_e32 v5, v6, v5
	v_div_scale_f32 v6, vcc, 1.0, v1, 1.0
	v_mul_f32_e32 v7, v6, v5
	v_fma_f32 v8, -v4, v7, v6
	v_fmac_f32_e32 v7, v8, v5
	v_fma_f32 v4, -v4, v7, v6
	v_div_fmas_f32 v4, v4, v5, v7
	v_div_fixup_f32 v1, v4, v1, 1.0
	v_div_scale_f32 v4, s[22:23], v0, v0, 1.0
	v_rcp_f32_e32 v5, v4
	s_nop 0
	v_fma_f32 v6, -v4, v5, 1.0
	v_fmac_f32_e32 v5, v6, v5
	v_div_scale_f32 v6, vcc, 1.0, v0, 1.0
	v_mul_f32_e32 v7, v6, v5
	v_fma_f32 v8, -v4, v7, v6
	v_fmac_f32_e32 v7, v8, v5
	v_fma_f32 v4, -v4, v7, v6
	v_div_fmas_f32 v4, v4, v5, v7
	v_div_fixup_f32 v0, v4, v0, 1.0
	v_cvt_pk_bf16_f32 v80, v0, v1
	v_mul_f32_e32 v0, 0xbfb8aa3b, v2
	v_mul_f32_e32 v1, 0xbfb8aa3b, v3
	v_exp_f32_e32 v0, v0
	v_exp_f32_e32 v1, v1
	s_nop 0
	v_pk_add_f32 v[0:1], v[0:1], 1.0 op_sel_hi:[1,0]
	s_nop 0
	v_div_scale_f32 v2, s[22:23], v1, v1, 1.0
	v_rcp_f32_e32 v3, v2
	s_nop 0
	v_fma_f32 v4, -v2, v3, 1.0
	v_fmac_f32_e32 v3, v4, v3
	v_div_scale_f32 v4, vcc, 1.0, v1, 1.0
	v_mul_f32_e32 v5, v4, v3
	v_fma_f32 v6, -v2, v5, v4
	v_fmac_f32_e32 v5, v6, v3
	v_fma_f32 v2, -v2, v5, v4
	v_div_fmas_f32 v2, v2, v3, v5
	v_div_fixup_f32 v1, v2, v1, 1.0
	v_div_scale_f32 v2, s[22:23], v0, v0, 1.0
	v_rcp_f32_e32 v3, v2
	s_movk_i32 s22, 0xff80
	v_and_or_b32 v118, v83, s22, v85
	v_bfe_u32 v83, v82, 4, 2
	v_fma_f32 v4, -v2, v3, 1.0
	v_fmac_f32_e32 v3, v4, v3
	v_div_scale_f32 v4, vcc, 1.0, v0, 1.0
	v_mul_f32_e32 v5, v4, v3
	v_fma_f32 v6, -v2, v5, v4
	v_fmac_f32_e32 v5, v6, v3
	v_fma_f32 v2, -v2, v5, v4
	v_div_fmas_f32 v2, v2, v3, v5
	v_ashrrev_i32_e32 v4, 3, v82
	v_div_fixup_f32 v0, v2, v0, 1.0
	v_add_u32_e32 v2, s20, v4
	v_ashrrev_i32_e32 v3, 31, v2
	v_cvt_pk_bf16_f32 v81, v0, v1
	v_lshl_add_u64 v[0:1], s[4:5], 0, v[130:131]
	v_lshlrev_b64 v[2:3], 9, v[2:3]
	v_lshl_add_u64 v[40:41], v[0:1], 0, v[2:3]
	v_add_u32_e32 v0, s19, v4
	v_ashrrev_i32_e32 v1, 31, v0
	v_lshlrev_b64 v[0:1], 11, v[0:1]
	v_lshl_add_u64 v[0:1], s[0:1], 0, v[0:1]
	v_lshl_add_u64 v[42:43], v[0:1], 0, v[130:131]
	v_add_co_u32_e32 v44, vcc, s33, v42
	global_load_dwordx4 v[20:23], v[42:43], off
	s_nop 0
	v_addc_co_u32_e32 v45, vcc, 0, v43, vcc
	v_add_co_u32_e32 v46, vcc, s56, v42
	global_load_dwordx4 v[24:27], v[44:45], off
	s_nop 0
	v_addc_co_u32_e32 v47, vcc, 0, v43, vcc
	global_load_dwordx4 v[28:31], v[46:47], off
	v_add_co_u32_e32 v48, vcc, s57, v42
	v_lshlrev_b32_e32 v85, 5, v82
	s_nop 0
	v_addc_co_u32_e32 v49, vcc, 0, v43, vcc
	global_load_dwordx4 v[32:35], v[48:49], off
	global_load_dwordx4 v[36:39], v[40:41], off
	global_load_dwordx4 v[0:3], v[42:43], off offset:128
	global_load_dwordx4 v[4:7], v[44:45], off offset:128
	global_load_dwordx4 v[8:11], v[46:47], off offset:128
	global_load_dwordx4 v[12:15], v[48:49], off offset:128
	global_load_dwordx4 v[16:19], v[40:41], off offset:128
	s_barrier
	s_waitcnt vmcnt(9)
	ds_write_b128 v118, v[20:23]
	s_waitcnt vmcnt(8)
	ds_write_b128 v118, v[24:27] offset:4096
	s_waitcnt vmcnt(7)
	ds_write_b128 v118, v[28:31] offset:8192
	s_waitcnt vmcnt(6)
	ds_write_b128 v118, v[32:35] offset:12288
	s_waitcnt vmcnt(5)
	ds_write_b128 v118, v[36:39] offset:16384
	s_waitcnt lgkmcnt(0)
	s_barrier
; #define GLOAD(ra, rb, koff)                                                        \
;   {                                                                                \
;     _Pragma("unroll") for (int j = 0; j < 4; j++) ra[j] = *(const u32x4*)(pa + j * sa32 + (koff));   \
;     _Pragma("unroll") for (int j = 0; j < NB_; j++) rb[j] = *(const u32x4*)(pbv[j] + (koff));         \
;   }
; template <int NT, bool PRE> ...
;     ...
;   const int wsw = ((tid & 7) ^ ((tid >> 4) & 7)) * 8;
;   const int rsw = (lane & 15) >> 1;
;     ...
;   if (!PRE) {
;     GLOAD(ra0, rb0, 0);
;     GLOAD(ra1, rb1, 64);
;   }
;   __syncthreads();
;   for (int k0 = 0; k0 < K; k0 += 128) {
;     LSTORE(ra0, rb0, 0);
;     __syncthreads();
;     GLOAD(ra0, rb0, min(k0 + 128, K - 128));
;     __builtin_amdgcn_sched_barrier(0);
;     COMPUTE(0);
;     LSTORE(ra1, rb1, 1);
;     __syncthreads();
;     GLOAD(ra1, rb1, min(k0 + 192, K - 64));
;     __builtin_amdgcn_sched_barrier(0);
;     COMPUTE(1);
;   }
	global_load_dwordx4 v[20:23], v[42:43], off offset:256
	global_load_dwordx4 v[24:27], v[44:45], off offset:256
	global_load_dwordx4 v[28:31], v[46:47], off offset:256
	global_load_dwordx4 v[32:35], v[48:49], off offset:256
	global_load_dwordx4 v[36:39], v[40:41], off offset:256
	v_lshlrev_b32_e32 v82, 6, v82
	v_bitop3_b32 v83, v83, v87, 4 bitop3:0x36
	v_and_or_b32 v85, v85, s21, v86
	v_and_b32_e32 v82, 0xffffe000, v82
	v_lshlrev_b32_e32 v83, 4, v83
	v_or3_b32 v119, v84, v82, v86
	v_or_b32_e32 v120, v85, v84
	v_or3_b32 v121, v83, v82, v86
	v_or_b32_e32 v122, v85, v83
	ds_read_b128 v[82:85], v119
	ds_read_b128 v[86:89], v119 offset:2048
	ds_read_b128 v[90:93], v119 offset:4096
	ds_read_b128 v[94:97], v119 offset:6144
	ds_read_b128 v[98:101], v120 offset:16384
	s_setprio 1
	s_waitcnt lgkmcnt(0)
	v_mfma_f32_16x16x32_bf16 v[82:85], v[98:101], v[82:85], 0
	v_mfma_f32_16x16x32_bf16 v[86:89], v[98:101], v[86:89], 0
	v_mfma_f32_16x16x32_bf16 v[90:93], v[98:101], v[90:93], 0
	v_mfma_f32_16x16x32_bf16 v[94:97], v[98:101], v[94:97], 0
	s_setprio 0
	ds_read_b128 v[98:101], v121
	ds_read_b128 v[102:105], v121 offset:2048
	ds_read_b128 v[106:109], v121 offset:4096
	ds_read_b128 v[110:113], v121 offset:6144
	ds_read_b128 v[114:117], v122 offset:16384
	s_setprio 1
	s_waitcnt lgkmcnt(0)
	v_mfma_f32_16x16x32_bf16 v[82:85], v[114:117], v[98:101], v[82:85]
	v_mfma_f32_16x16x32_bf16 v[86:89], v[114:117], v[102:105], v[86:89]
	v_mfma_f32_16x16x32_bf16 v[90:93], v[114:117], v[106:109], v[90:93]
	v_mfma_f32_16x16x32_bf16 v[94:97], v[114:117], v[110:113], v[94:97]
	s_setprio 0
	s_waitcnt vmcnt(9)
	ds_write_b128 v118, v[0:3] offset:32768
	s_waitcnt vmcnt(8)
	ds_write_b128 v118, v[4:7] offset:36864
	s_waitcnt vmcnt(7)
	ds_write_b128 v118, v[8:11] offset:40960
	s_waitcnt vmcnt(6)
	ds_write_b128 v118, v[12:15] offset:45056
	s_waitcnt vmcnt(5)
	ds_write_b128 v118, v[16:19] offset:49152
	s_waitcnt lgkmcnt(0)
	s_barrier
	global_load_dwordx4 v[0:3], v[44:45], off offset:384
	global_load_dwordx4 v[4:7], v[46:47], off offset:384
	global_load_dwordx4 v[8:11], v[48:49], off offset:384
	global_load_dwordx4 v[12:15], v[42:43], off offset:384
	global_load_dwordx4 v[16:19], v[40:41], off offset:384
	ds_read_b128 v[40:43], v119 offset:32768
	ds_read_b128 v[44:47], v119 offset:34816
	ds_read_b128 v[98:101], v119 offset:36864
	ds_read_b128 v[102:105], v119 offset:38912
	ds_read_b128 v[106:109], v120 offset:49152
	s_setprio 1
	s_waitcnt lgkmcnt(0)
	v_mfma_f32_16x16x32_bf16 v[40:43], v[106:109], v[40:43], v[82:85]
	v_mfma_f32_16x16x32_bf16 v[44:47], v[106:109], v[44:47], v[86:89]
	v_mfma_f32_16x16x32_bf16 v[82:85], v[106:109], v[98:101], v[90:93]
	v_mfma_f32_16x16x32_bf16 v[86:89], v[106:109], v[102:105], v[94:97]
	s_setprio 0
	s_nop 0
	ds_read_b128 v[90:93], v121 offset:32768
	ds_read_b128 v[94:97], v121 offset:34816
	ds_read_b128 v[98:101], v121 offset:36864
	ds_read_b128 v[102:105], v121 offset:38912
	ds_read_b128 v[106:109], v122 offset:49152
	s_setprio 1
	s_waitcnt lgkmcnt(0)
	v_mfma_f32_16x16x32_bf16 v[40:43], v[106:109], v[90:93], v[40:43]
	v_mfma_f32_16x16x32_bf16 v[44:47], v[106:109], v[94:97], v[44:47]
	v_mfma_f32_16x16x32_bf16 v[82:85], v[106:109], v[98:101], v[82:85]
	v_mfma_f32_16x16x32_bf16 v[86:89], v[106:109], v[102:105], v[86:89]
	s_setprio 0
	s_waitcnt vmcnt(9)
	ds_write_b128 v118, v[20:23]
	s_waitcnt vmcnt(8)
	ds_write_b128 v118, v[24:27] offset:4096
	s_waitcnt vmcnt(7)
	ds_write_b128 v118, v[28:31] offset:8192
	s_waitcnt vmcnt(6)
	ds_write_b128 v118, v[32:35] offset:12288
	s_waitcnt vmcnt(5)
	ds_write_b128 v118, v[36:39] offset:16384
	s_waitcnt lgkmcnt(0)
	s_barrier
	ds_read_b128 v[20:23], v119
	ds_read_b128 v[24:27], v119 offset:2048
	ds_read_b128 v[28:31], v119 offset:4096
	ds_read_b128 v[32:35], v119 offset:6144
	ds_read_b128 v[36:39], v120 offset:16384
	s_setprio 1
	s_waitcnt lgkmcnt(0)
	v_mfma_f32_16x16x32_bf16 v[20:23], v[36:39], v[20:23], v[40:43]
	v_mfma_f32_16x16x32_bf16 v[24:27], v[36:39], v[24:27], v[44:47]
	v_mfma_f32_16x16x32_bf16 v[28:31], v[36:39], v[28:31], v[82:85]
	v_mfma_f32_16x16x32_bf16 v[32:35], v[36:39], v[32:35], v[86:89]
	s_setprio 0
	ds_read_b128 v[36:39], v121
	ds_read_b128 v[40:43], v121 offset:2048
	ds_read_b128 v[44:47], v121 offset:4096
	ds_read_b128 v[82:85], v121 offset:6144
	ds_read_b128 v[86:89], v122 offset:16384
	s_setprio 1
	s_waitcnt lgkmcnt(0)
	v_mfma_f32_16x16x32_bf16 v[20:23], v[86:89], v[36:39], v[20:23]
	v_mfma_f32_16x16x32_bf16 v[24:27], v[86:89], v[40:43], v[24:27]
	v_mfma_f32_16x16x32_bf16 v[28:31], v[86:89], v[44:47], v[28:31]
	v_mfma_f32_16x16x32_bf16 v[32:35], v[86:89], v[82:85], v[32:35]
	s_setprio 0
	s_waitcnt vmcnt(1)
	ds_write_b128 v118, v[12:15] offset:32768
	ds_write_b128 v118, v[0:3] offset:36864
	ds_write_b128 v118, v[4:7] offset:40960
	ds_write_b128 v118, v[8:11] offset:45056
	s_waitcnt vmcnt(0)
	ds_write_b128 v118, v[16:19] offset:49152
	s_waitcnt lgkmcnt(0)
	s_barrier
; #define GLOAD(ra, rb, koff)                                                        \
;   {                                                                                \
;     _Pragma("unroll") for (int j = 0; j < 4; j++) ra[j] = *(const u32x4*)(pa + j * sa32 + (koff));   \
;     _Pragma("unroll") for (int j = 0; j < NB_; j++) rb[j] = *(const u32x4*)(pbv[j] + (koff));         \
;   }
; template <int NT, bool PRE> ...
;     ...
;   if (!PRE) {
;     GLOAD(ra0, rb0, 0);
;     GLOAD(ra1, rb1, 64);
;   }
;   __syncthreads();
;   for (int k0 = 0; k0 < K; k0 += 128) {
;     LSTORE(ra0, rb0, 0);
;     __syncthreads();
;     GLOAD(ra0, rb0, min(k0 + 128, K - 128));
;     __builtin_amdgcn_sched_barrier(0);
;     COMPUTE(0);
;     LSTORE(ra1, rb1, 1);
;     __syncthreads();
;     GLOAD(ra1, rb1, min(k0 + 192, K - 64));
;     __builtin_amdgcn_sched_barrier(0);
;     COMPUTE(1);
;   }
; template <int NT>
; __device__ __forceinline__ void gemm_main(const u16* __restrict__ A, int lda, const u16* __restrict__ Bt, int ldb,
;                                           int K, int m0, int n0, f32x4 (&acc)[4][NT], u16* sA, u16* sB) {
;   const int tid = TID();
;   const u16* pa = A + (size_t)(m0 + (tid >> 3)) * lda + (tid & 7) * 8;
;   const u16* pbv[NT];
; #pragma unroll
;   for (int j = 0; j < NT; j++) pbv[j] = Bt + (size_t)(n0 + (tid >> 3) + 32 * j) * ldb + (tid & 7) * 8;
;   gemm_core<NT>(pa, (size_t)32 * lda, pbv, K, acc, sA, sB, tid);
	ds_read_b128 v[0:3], v119 offset:32768
	ds_read_b128 v[4:7], v119 offset:34816
	ds_read_b128 v[8:11], v119 offset:36864
	ds_read_b128 v[12:15], v119 offset:38912
	ds_read_b128 v[16:19], v120 offset:49152
	s_setprio 1
	s_waitcnt lgkmcnt(0)
	v_mfma_f32_16x16x32_bf16 v[0:3], v[16:19], v[0:3], v[20:23]
	v_mfma_f32_16x16x32_bf16 v[4:7], v[16:19], v[4:7], v[24:27]
	v_mfma_f32_16x16x32_bf16 v[20:23], v[16:19], v[8:11], v[28:31]
	v_mfma_f32_16x16x32_bf16 v[16:19], v[16:19], v[12:15], v[32:35]
	s_setprio 0
	ds_read_b128 v[8:11], v121 offset:32768
	ds_read_b128 v[24:27], v121 offset:34816
	ds_read_b128 v[28:31], v121 offset:36864
	ds_read_b128 v[32:35], v121 offset:38912
	ds_read_b128 v[36:39], v122 offset:49152
	s_setprio 1
	s_waitcnt lgkmcnt(0)
	v_mfma_f32_16x16x32_bf16 v[12:15], v[36:39], v[8:11], v[0:3]
	v_mfma_f32_16x16x32_bf16 v[8:11], v[36:39], v[24:27], v[4:7]
	v_mfma_f32_16x16x32_bf16 v[4:7], v[36:39], v[28:31], v[20:23]
	v_mfma_f32_16x16x32_bf16 v[0:3], v[36:39], v[32:35], v[16:19]
	s_setprio 0
	v_mov_b32_e32 v90, v169
	s_nop 0
	v_ashrrev_i32_e32 v20, 3, v90
	v_lshlrev_b32_e32 v36, 4, v90
	v_add_u32_e32 v18, s20, v20
	v_and_b32_e32 v130, 0x70, v36
	v_ashrrev_i32_e32 v19, 31, v18
	v_lshl_add_u64 v[16:17], s[8:9], 0, v[130:131]
	v_lshlrev_b64 v[18:19], 9, v[18:19]
	v_lshl_add_u64 v[48:49], v[16:17], 0, v[18:19]
	v_add_u32_e32 v16, s19, v20
	v_ashrrev_i32_e32 v17, 31, v16
	v_lshlrev_b64 v[16:17], 11, v[16:17]
	v_lshl_add_u64 v[16:17], s[6:7], 0, v[16:17]
	v_lshl_add_u64 v[126:127], v[16:17], 0, v[130:131]
	v_add_co_u32_e32 v136, vcc, s33, v126
	global_load_dwordx4 v[16:19], v[126:127], off
	s_nop 0
	v_addc_co_u32_e32 v137, vcc, 0, v127, vcc
	v_add_co_u32_e32 v138, vcc, s56, v126
	global_load_dwordx4 v[20:23], v[136:137], off
	s_nop 0
	v_addc_co_u32_e32 v139, vcc, 0, v127, vcc
	global_load_dwordx4 v[24:27], v[138:139], off
	global_load_dwordx4 v[28:31], v[48:49], off
	v_add_co_u32_e32 v140, vcc, s57, v126
	v_lshrrev_b32_e32 v91, 4, v90
	s_nop 0
	v_addc_co_u32_e32 v141, vcc, 0, v127, vcc
	global_load_dwordx4 v[32:35], v[140:141], off
	v_xor_b32_e32 v37, v91, v90
	v_lshlrev_b32_e32 v37, 4, v37
	v_and_b32_e32 v37, 0x70, v37
	v_and_or_b32 v130, v36, s22, v37
	global_load_dwordx4 v[36:39], v[48:49], off offset:128
	global_load_dwordx4 v[40:43], v[126:127], off offset:128
	global_load_dwordx4 v[44:47], v[136:137], off offset:128
	global_load_dwordx4 v[82:85], v[138:139], off offset:128
	global_load_dwordx4 v[86:89], v[140:141], off offset:128
	s_barrier
	v_and_b32_e32 v92, 15, v90
	v_bfe_u32 v93, v90, 1, 3
	v_bfe_u32 v94, v90, 4, 2
	v_lshlrev_b32_e32 v95, 5, v90
	v_lshlrev_b32_e32 v92, 7, v92
	v_bitop3_b32 v91, v91, v93, 3 bitop3:0x6c
	v_lshlrev_b32_e32 v90, 6, v90
	v_and_or_b32 v95, v95, s21, v92
	v_lshlrev_b32_e32 v91, 4, v91
	v_and_b32_e32 v90, 0xffffe000, v90
	v_or3_b32 v142, v91, v90, v92
	v_or_b32_e32 v143, v95, v91
	v_bitop3_b32 v91, v94, v93, 4 bitop3:0x36
	v_lshlrev_b32_e32 v91, 4, v91
	v_or3_b32 v144, v91, v90, v92
	v_or_b32_e32 v145, v95, v91
	s_waitcnt vmcnt(6)
	ds_write_b128 v130, v[28:31] offset:16384
	ds_write_b128 v130, v[16:19]
	ds_write_b128 v130, v[20:23] offset:4096
	ds_write_b128 v130, v[24:27] offset:8192
	s_waitcnt vmcnt(5)
	ds_write_b128 v130, v[32:35] offset:12288
	s_waitcnt lgkmcnt(0)
	s_barrier
	global_load_dwordx4 v[16:19], v[136:137], off offset:256
	global_load_dwordx4 v[20:23], v[138:139], off offset:256
	global_load_dwordx4 v[24:27], v[140:141], off offset:256
	global_load_dwordx4 v[28:31], v[126:127], off offset:256
	global_load_dwordx4 v[32:35], v[48:49], off offset:256
	ds_read_b128 v[90:93], v142
	ds_read_b128 v[94:97], v142 offset:2048
	ds_read_b128 v[98:101], v142 offset:4096
	ds_read_b128 v[102:105], v142 offset:6144
	ds_read_b128 v[106:109], v143 offset:16384
	s_setprio 1
	s_waitcnt lgkmcnt(0)
	v_mfma_f32_16x16x32_bf16 v[90:93], v[106:109], v[90:93], 0
	v_mfma_f32_16x16x32_bf16 v[94:97], v[106:109], v[94:97], 0
	v_mfma_f32_16x16x32_bf16 v[98:101], v[106:109], v[98:101], 0
	v_mfma_f32_16x16x32_bf16 v[102:105], v[106:109], v[102:105], 0
	s_setprio 0
	ds_read_b128 v[106:109], v144
	ds_read_b128 v[110:113], v144 offset:2048
	ds_read_b128 v[114:117], v144 offset:4096
	ds_read_b128 v[118:121], v144 offset:6144
	ds_read_b128 v[122:125], v145 offset:16384
	s_setprio 1
	s_waitcnt lgkmcnt(0)
	v_mfma_f32_16x16x32_bf16 v[90:93], v[122:125], v[106:109], v[90:93]
	v_mfma_f32_16x16x32_bf16 v[94:97], v[122:125], v[110:113], v[94:97]
	v_mfma_f32_16x16x32_bf16 v[98:101], v[122:125], v[114:117], v[98:101]
	v_mfma_f32_16x16x32_bf16 v[102:105], v[122:125], v[118:121], v[102:105]
	s_setprio 0
	s_waitcnt vmcnt(8)
	ds_write_b128 v130, v[40:43] offset:32768
	s_waitcnt vmcnt(7)
	ds_write_b128 v130, v[44:47] offset:36864
	s_waitcnt vmcnt(6)
	ds_write_b128 v130, v[82:85] offset:40960
	s_waitcnt vmcnt(5)
	ds_write_b128 v130, v[86:89] offset:45056
	ds_write_b128 v130, v[36:39] offset:49152
	s_waitcnt lgkmcnt(0)
	s_barrier
; #define GLOAD(ra, rb, koff)                                                        \
;   {                                                                                \
;     _Pragma("unroll") for (int j = 0; j < 4; j++) ra[j] = *(const u32x4*)(pa + j * sa32 + (koff));   \
;     _Pragma("unroll") for (int j = 0; j < NB_; j++) rb[j] = *(const u32x4*)(pbv[j] + (koff));         \
;   }
; template <int NT, bool PRE> ...
;     ...
;   if (!PRE) {
;     GLOAD(ra0, rb0, 0);
;     GLOAD(ra1, rb1, 64);
;   }
;   __syncthreads();
;   for (int k0 = 0; k0 < K; k0 += 128) {
;     LSTORE(ra0, rb0, 0);
;     __syncthreads();
;     GLOAD(ra0, rb0, min(k0 + 128, K - 128));
;     __builtin_amdgcn_sched_barrier(0);
;     COMPUTE(0);
;     LSTORE(ra1, rb1, 1);
;     __syncthreads();
;     GLOAD(ra1, rb1, min(k0 + 192, K - 64));
;     __builtin_amdgcn_sched_barrier(0);
;     COMPUTE(1);
;   }
; template <int NT>
; __device__ __forceinline__ void gemm_main(const u16* __restrict__ A, int lda, const u16* __restrict__ Bt, int ldb,
;                                           int K, int m0, int n0, f32x4 (&acc)[4][NT], u16* sA, u16* sB) {
;   const int tid = TID();
;   const u16* pa = A + (size_t)(m0 + (tid >> 3)) * lda + (tid & 7) * 8;
;   const u16* pbv[NT];
; #pragma unroll
;   for (int j = 0; j < NT; j++) pbv[j] = Bt + (size_t)(n0 + (tid >> 3) + 32 * j) * ldb + (tid & 7) * 8;
;   gemm_core<NT>(pa, (size_t)32 * lda, pbv, K, acc, sA, sB, tid);
	global_load_dwordx4 v[36:39], v[136:137], off offset:384
	global_load_dwordx4 v[40:43], v[138:139], off offset:384
	global_load_dwordx4 v[44:47], v[140:141], off offset:384
	global_load_dwordx4 v[82:85], v[126:127], off offset:384
	global_load_dwordx4 v[86:89], v[48:49], off offset:384
	ds_read_b128 v[106:109], v142 offset:32768
	ds_read_b128 v[110:113], v142 offset:34816
	ds_read_b128 v[114:117], v142 offset:36864
	ds_read_b128 v[118:121], v142 offset:38912
	ds_read_b128 v[122:125], v143 offset:49152
	s_setprio 1
	s_waitcnt lgkmcnt(0)
	v_mfma_f32_16x16x32_bf16 v[90:93], v[122:125], v[106:109], v[90:93]
	v_mfma_f32_16x16x32_bf16 v[94:97], v[122:125], v[110:113], v[94:97]
	v_mfma_f32_16x16x32_bf16 v[98:101], v[122:125], v[114:117], v[98:101]
	v_mfma_f32_16x16x32_bf16 v[102:105], v[122:125], v[118:121], v[102:105]
	s_setprio 0
	ds_read_b128 v[106:109], v144 offset:32768
	ds_read_b128 v[110:113], v144 offset:34816
	ds_read_b128 v[114:117], v144 offset:36864
	ds_read_b128 v[118:121], v144 offset:38912
	ds_read_b128 v[122:125], v145 offset:49152
	s_setprio 1
	s_waitcnt lgkmcnt(0)
	v_mfma_f32_16x16x32_bf16 v[90:93], v[122:125], v[106:109], v[90:93]
	v_mfma_f32_16x16x32_bf16 v[94:97], v[122:125], v[110:113], v[94:97]
	v_mfma_f32_16x16x32_bf16 v[98:101], v[122:125], v[114:117], v[98:101]
	v_mfma_f32_16x16x32_bf16 v[102:105], v[122:125], v[118:121], v[102:105]
	s_setprio 0
	s_waitcnt vmcnt(6)
	ds_write_b128 v130, v[28:31]
	ds_write_b128 v130, v[16:19] offset:4096
	ds_write_b128 v130, v[20:23] offset:8192
	ds_write_b128 v130, v[24:27] offset:12288
	s_waitcnt vmcnt(5)
	ds_write_b128 v130, v[32:35] offset:16384
	s_waitcnt lgkmcnt(0)
	s_barrier
	ds_read_b128 v[16:19], v142
	ds_read_b128 v[20:23], v142 offset:2048
	ds_read_b128 v[24:27], v142 offset:4096
	ds_read_b128 v[28:31], v142 offset:6144
	ds_read_b128 v[32:35], v143 offset:16384
	s_setprio 1
	s_waitcnt lgkmcnt(0)
	v_mfma_f32_16x16x32_bf16 v[16:19], v[32:35], v[16:19], v[90:93]
	v_mfma_f32_16x16x32_bf16 v[20:23], v[32:35], v[20:23], v[94:97]
	v_mfma_f32_16x16x32_bf16 v[24:27], v[32:35], v[24:27], v[98:101]
	v_mfma_f32_16x16x32_bf16 v[28:31], v[32:35], v[28:31], v[102:105]
	s_setprio 0
	ds_read_b128 v[32:35], v144
	ds_read_b128 v[90:93], v144 offset:2048
	ds_read_b128 v[94:97], v144 offset:4096
	ds_read_b128 v[98:101], v144 offset:6144
	ds_read_b128 v[102:105], v145 offset:16384
	s_setprio 1
	s_waitcnt lgkmcnt(0)
	v_mfma_f32_16x16x32_bf16 v[16:19], v[102:105], v[32:35], v[16:19]
	v_mfma_f32_16x16x32_bf16 v[20:23], v[102:105], v[90:93], v[20:23]
	v_mfma_f32_16x16x32_bf16 v[24:27], v[102:105], v[94:97], v[24:27]
	v_mfma_f32_16x16x32_bf16 v[28:31], v[102:105], v[98:101], v[28:31]
	s_setprio 0
	s_waitcnt vmcnt(1)
	ds_write_b128 v130, v[82:85] offset:32768
	ds_write_b128 v130, v[36:39] offset:36864
	ds_write_b128 v130, v[40:43] offset:40960
	ds_write_b128 v130, v[44:47] offset:45056
	s_waitcnt vmcnt(0)
	ds_write_b128 v130, v[86:89] offset:49152
	s_waitcnt lgkmcnt(0)
	s_barrier
	ds_read_b128 v[32:35], v142 offset:32768
	ds_read_b128 v[36:39], v142 offset:34816
	ds_read_b128 v[40:43], v142 offset:36864
	ds_read_b128 v[44:47], v142 offset:38912
	ds_read_b128 v[82:85], v143 offset:49152
	s_setprio 1
	s_waitcnt lgkmcnt(0)
	v_mfma_f32_16x16x32_bf16 v[16:19], v[82:85], v[32:35], v[16:19]
	v_mfma_f32_16x16x32_bf16 v[20:23], v[82:85], v[36:39], v[20:23]
	v_mfma_f32_16x16x32_bf16 v[32:35], v[82:85], v[40:43], v[24:27]
	v_mfma_f32_16x16x32_bf16 v[36:39], v[82:85], v[44:47], v[28:31]
	s_setprio 0
	s_nop 0
	ds_read_b128 v[24:27], v144 offset:32768
	ds_read_b128 v[40:43], v144 offset:34816
	ds_read_b128 v[44:47], v144 offset:36864
	ds_read_b128 v[82:85], v144 offset:38912
	ds_read_b128 v[86:89], v145 offset:49152
	s_setprio 1
	s_waitcnt lgkmcnt(0)
	v_mfma_f32_16x16x32_bf16 v[28:31], v[86:89], v[24:27], v[16:19]
	v_mfma_f32_16x16x32_bf16 v[24:27], v[86:89], v[40:43], v[20:23]
	v_mfma_f32_16x16x32_bf16 v[20:23], v[86:89], v[44:47], v[32:35]
	v_mfma_f32_16x16x32_bf16 v[16:19], v[86:89], v[82:85], v[36:39]
	s_setprio 0
	v_mov_b32_e32 v106, v169
	s_nop 0
	v_ashrrev_i32_e32 v36, 3, v106
	v_lshlrev_b32_e32 v86, 4, v106
	v_add_u32_e32 v34, s20, v36
	v_and_b32_e32 v130, 0x70, v86
	v_ashrrev_i32_e32 v35, 31, v34
	v_lshl_add_u64 v[32:33], s[12:13], 0, v[130:131]
	v_lshlrev_b64 v[34:35], 9, v[34:35]
	v_lshl_add_u64 v[48:49], v[32:33], 0, v[34:35]
	v_add_u32_e32 v32, s19, v36
	v_ashrrev_i32_e32 v33, 31, v32
	v_lshlrev_b64 v[32:33], 11, v[32:33]
	v_lshl_add_u64 v[32:33], s[10:11], 0, v[32:33]
	v_lshl_add_u64 v[126:127], v[32:33], 0, v[130:131]
	v_add_co_u32_e32 v144, vcc, s33, v126
	global_load_dwordx4 v[32:35], v[126:127], off
	s_nop 0
	v_addc_co_u32_e32 v145, vcc, 0, v127, vcc
	v_add_co_u32_e32 v166, vcc, s56, v126
	global_load_dwordx4 v[36:39], v[144:145], off
	s_nop 0
	v_addc_co_u32_e32 v167, vcc, 0, v127, vcc
	global_load_dwordx4 v[40:43], v[166:167], off
	global_load_dwordx4 v[44:47], v[48:49], off
	v_add_co_u32_e32 v198, vcc, s57, v126
	v_lshrrev_b32_e32 v107, 4, v106
	s_nop 0
	v_addc_co_u32_e32 v199, vcc, 0, v127, vcc
	global_load_dwordx4 v[82:85], v[198:199], off
	v_xor_b32_e32 v87, v107, v106
	v_lshlrev_b32_e32 v87, 4, v87
	v_and_b32_e32 v87, 0x70, v87
	v_and_or_b32 v130, v86, s22, v87
	global_load_dwordx4 v[86:89], v[48:49], off offset:128
	global_load_dwordx4 v[90:93], v[126:127], off offset:128
	global_load_dwordx4 v[94:97], v[144:145], off offset:128
	global_load_dwordx4 v[98:101], v[166:167], off offset:128
	global_load_dwordx4 v[102:105], v[198:199], off offset:128
	s_barrier
; #define GLOAD(ra, rb, koff)                                                        \
;   {                                                                                \
;     _Pragma("unroll") for (int j = 0; j < 4; j++) ra[j] = *(const u32x4*)(pa + j * sa32 + (koff));   \
;     _Pragma("unroll") for (int j = 0; j < NB_; j++) rb[j] = *(const u32x4*)(pbv[j] + (koff));         \
;   }
; template <int NT, bool PRE> ...
;     ...
;   if (!PRE) {
;     GLOAD(ra0, rb0, 0);
;     GLOAD(ra1, rb1, 64);
;   }
;   __syncthreads();
;   for (int k0 = 0; k0 < K; k0 += 128) {
;     LSTORE(ra0, rb0, 0);
;     __syncthreads();
;     GLOAD(ra0, rb0, min(k0 + 128, K - 128));
;     __builtin_amdgcn_sched_barrier(0);
;     COMPUTE(0);
;     LSTORE(ra1, rb1, 1);
;     __syncthreads();
;     GLOAD(ra1, rb1, min(k0 + 192, K - 64));
;     __builtin_amdgcn_sched_barrier(0);
;     COMPUTE(1);
;   }
	v_and_b32_e32 v108, 15, v106
	v_bfe_u32 v109, v106, 1, 3
	v_bfe_u32 v110, v106, 4, 2
	v_lshlrev_b32_e32 v111, 5, v106
	v_lshlrev_b32_e32 v108, 7, v108
	v_bitop3_b32 v107, v107, v109, 3 bitop3:0x6c
	v_lshlrev_b32_e32 v106, 6, v106
	v_and_or_b32 v111, v111, s21, v108
	v_lshlrev_b32_e32 v107, 4, v107
	v_and_b32_e32 v106, 0xffffe000, v106
	v_or3_b32 v157, v107, v106, v108
	v_or_b32_e32 v168, v111, v107
	v_bitop3_b32 v107, v110, v109, 4 bitop3:0x36
	v_lshlrev_b32_e32 v107, 4, v107
	v_or3_b32 v197, v107, v106, v108
	v_or_b32_e32 v200, v111, v107
	s_waitcnt vmcnt(6)
	ds_write_b128 v130, v[44:47] offset:16384
	ds_write_b128 v130, v[32:35]
	ds_write_b128 v130, v[36:39] offset:4096
	ds_write_b128 v130, v[40:43] offset:8192
	s_waitcnt vmcnt(5)
	ds_write_b128 v130, v[82:85] offset:12288
	s_waitcnt lgkmcnt(0)
	s_barrier
	global_load_dwordx4 v[32:35], v[144:145], off offset:256
	global_load_dwordx4 v[36:39], v[166:167], off offset:256
	global_load_dwordx4 v[40:43], v[198:199], off offset:256
	global_load_dwordx4 v[44:47], v[126:127], off offset:256
	global_load_dwordx4 v[82:85], v[48:49], off offset:256
	ds_read_b128 v[106:109], v157
	ds_read_b128 v[110:113], v157 offset:2048
	ds_read_b128 v[114:117], v157 offset:4096
	ds_read_b128 v[118:121], v157 offset:6144
	ds_read_b128 v[122:125], v168 offset:16384
	s_setprio 1
	s_waitcnt lgkmcnt(0)
	v_mfma_f32_16x16x32_bf16 v[106:109], v[122:125], v[106:109], 0
	v_mfma_f32_16x16x32_bf16 v[110:113], v[122:125], v[110:113], 0
	v_mfma_f32_16x16x32_bf16 v[114:117], v[122:125], v[114:117], 0
	v_mfma_f32_16x16x32_bf16 v[118:121], v[122:125], v[118:121], 0
	s_setprio 0
	ds_read_b128 v[122:125], v197
	ds_read_b128 v[136:139], v197 offset:2048
	ds_read_b128 v[140:143], v197 offset:4096
	ds_read_b128 v[158:161], v197 offset:6144
	ds_read_b128 v[162:165], v200 offset:16384
	s_setprio 1
	s_waitcnt lgkmcnt(0)
	v_mfma_f32_16x16x32_bf16 v[106:109], v[162:165], v[122:125], v[106:109]
	v_mfma_f32_16x16x32_bf16 v[110:113], v[162:165], v[136:139], v[110:113]
	v_mfma_f32_16x16x32_bf16 v[114:117], v[162:165], v[140:143], v[114:117]
	v_mfma_f32_16x16x32_bf16 v[118:121], v[162:165], v[158:161], v[118:121]
	s_setprio 0
	s_waitcnt vmcnt(8)
	ds_write_b128 v130, v[90:93] offset:32768
	s_waitcnt vmcnt(7)
	ds_write_b128 v130, v[94:97] offset:36864
	s_waitcnt vmcnt(6)
	ds_write_b128 v130, v[98:101] offset:40960
	s_waitcnt vmcnt(5)
	ds_write_b128 v130, v[102:105] offset:45056
	ds_write_b128 v130, v[86:89] offset:49152
	s_waitcnt lgkmcnt(0)
	s_barrier
	global_load_dwordx4 v[86:89], v[144:145], off offset:384
	global_load_dwordx4 v[90:93], v[166:167], off offset:384
	global_load_dwordx4 v[94:97], v[198:199], off offset:384
	global_load_dwordx4 v[98:101], v[126:127], off offset:384
	global_load_dwordx4 v[102:105], v[48:49], off offset:384
	ds_read_b128 v[122:125], v157 offset:32768
	ds_read_b128 v[136:139], v157 offset:34816
	ds_read_b128 v[140:143], v157 offset:36864
	ds_read_b128 v[158:161], v157 offset:38912
	ds_read_b128 v[162:165], v168 offset:49152
	s_setprio 1
	s_waitcnt lgkmcnt(0)
	v_mfma_f32_16x16x32_bf16 v[106:109], v[162:165], v[122:125], v[106:109]
	v_mfma_f32_16x16x32_bf16 v[110:113], v[162:165], v[136:139], v[110:113]
	v_mfma_f32_16x16x32_bf16 v[114:117], v[162:165], v[140:143], v[114:117]
	v_mfma_f32_16x16x32_bf16 v[118:121], v[162:165], v[158:161], v[118:121]
	s_setprio 0
	ds_read_b128 v[122:125], v197 offset:32768
	ds_read_b128 v[136:139], v197 offset:34816
	ds_read_b128 v[140:143], v197 offset:36864
	ds_read_b128 v[158:161], v197 offset:38912
	ds_read_b128 v[162:165], v200 offset:49152
	s_setprio 1
	s_waitcnt lgkmcnt(0)
	v_mfma_f32_16x16x32_bf16 v[106:109], v[162:165], v[122:125], v[106:109]
	v_mfma_f32_16x16x32_bf16 v[110:113], v[162:165], v[136:139], v[110:113]
	v_mfma_f32_16x16x32_bf16 v[114:117], v[162:165], v[140:143], v[114:117]
	v_mfma_f32_16x16x32_bf16 v[118:121], v[162:165], v[158:161], v[118:121]
	s_setprio 0
	s_waitcnt vmcnt(6)
	ds_write_b128 v130, v[44:47]
	ds_write_b128 v130, v[32:35] offset:4096
	ds_write_b128 v130, v[36:39] offset:8192
	ds_write_b128 v130, v[40:43] offset:12288
	s_waitcnt vmcnt(5)
	ds_write_b128 v130, v[82:85] offset:16384
	s_waitcnt lgkmcnt(0)
	s_barrier
	ds_read_b128 v[32:35], v157
	ds_read_b128 v[36:39], v157 offset:2048
	ds_read_b128 v[40:43], v157 offset:4096
	ds_read_b128 v[44:47], v157 offset:6144
	ds_read_b128 v[82:85], v168 offset:16384
	s_setprio 1
	s_waitcnt lgkmcnt(0)
	v_mfma_f32_16x16x32_bf16 v[32:35], v[82:85], v[32:35], v[106:109]
	v_mfma_f32_16x16x32_bf16 v[36:39], v[82:85], v[36:39], v[110:113]
	v_mfma_f32_16x16x32_bf16 v[40:43], v[82:85], v[40:43], v[114:117]
	v_mfma_f32_16x16x32_bf16 v[44:47], v[82:85], v[44:47], v[118:121]
	s_setprio 0
	ds_read_b128 v[82:85], v197
	ds_read_b128 v[106:109], v197 offset:2048
	ds_read_b128 v[110:113], v197 offset:4096
	ds_read_b128 v[114:117], v197 offset:6144
	ds_read_b128 v[118:121], v200 offset:16384
	s_setprio 1
	s_waitcnt lgkmcnt(0)
	v_mfma_f32_16x16x32_bf16 v[32:35], v[118:121], v[82:85], v[32:35]
	v_mfma_f32_16x16x32_bf16 v[36:39], v[118:121], v[106:109], v[36:39]
	v_mfma_f32_16x16x32_bf16 v[40:43], v[118:121], v[110:113], v[40:43]
	v_mfma_f32_16x16x32_bf16 v[44:47], v[118:121], v[114:117], v[44:47]
	s_setprio 0
	s_waitcnt vmcnt(1)
	ds_write_b128 v130, v[98:101] offset:32768
	ds_write_b128 v130, v[86:89] offset:36864
	ds_write_b128 v130, v[90:93] offset:40960
	ds_write_b128 v130, v[94:97] offset:45056
	s_waitcnt vmcnt(0)
	ds_write_b128 v130, v[102:105] offset:49152
	s_waitcnt lgkmcnt(0)
	s_barrier
; #define GLOAD(ra, rb, koff)                                                        \
;   {                                                                                \
;     _Pragma("unroll") for (int j = 0; j < 4; j++) ra[j] = *(const u32x4*)(pa + j * sa32 + (koff));   \
;     _Pragma("unroll") for (int j = 0; j < NB_; j++) rb[j] = *(const u32x4*)(pbv[j] + (koff));         \
;   }
; template <int NT, bool PRE> ...
;     ...
;   if (!PRE) {
;     GLOAD(ra0, rb0, 0);
;     GLOAD(ra1, rb1, 64);
;   }
;   __syncthreads();
;   for (int k0 = 0; k0 < K; k0 += 128) {
;     LSTORE(ra0, rb0, 0);
;     __syncthreads();
;     GLOAD(ra0, rb0, min(k0 + 128, K - 128));
;     __builtin_amdgcn_sched_barrier(0);
;     COMPUTE(0);
;     LSTORE(ra1, rb1, 1);
;     __syncthreads();
;     GLOAD(ra1, rb1, min(k0 + 192, K - 64));
;     __builtin_amdgcn_sched_barrier(0);
;     COMPUTE(1);
;   }
; template <int NT>
; __device__ __forceinline__ void gemm_main(const u16* __restrict__ A, int lda, const u16* __restrict__ Bt, int ldb,
;                                           int K, int m0, int n0, f32x4 (&acc)[4][NT], u16* sA, u16* sB) {
;   const int tid = TID();
;   const u16* pa = A + (size_t)(m0 + (tid >> 3)) * lda + (tid & 7) * 8;
;   const u16* pbv[NT];
; #pragma unroll
;   for (int j = 0; j < NT; j++) pbv[j] = Bt + (size_t)(n0 + (tid >> 3) + 32 * j) * ldb + (tid & 7) * 8;
;   gemm_core<NT>(pa, (size_t)32 * lda, pbv, K, acc, sA, sB, tid);
	ds_read_b128 v[82:85], v157 offset:32768
	ds_read_b128 v[86:89], v157 offset:34816
	ds_read_b128 v[90:93], v157 offset:36864
	ds_read_b128 v[94:97], v157 offset:38912
	ds_read_b128 v[98:101], v168 offset:49152
	s_setprio 1
	s_waitcnt lgkmcnt(0)
	v_mfma_f32_16x16x32_bf16 v[32:35], v[98:101], v[82:85], v[32:35]
	v_mfma_f32_16x16x32_bf16 v[36:39], v[98:101], v[86:89], v[36:39]
	v_mfma_f32_16x16x32_bf16 v[82:85], v[98:101], v[90:93], v[40:43]
	v_mfma_f32_16x16x32_bf16 v[86:89], v[98:101], v[94:97], v[44:47]
	s_setprio 0
	s_nop 0
	ds_read_b128 v[40:43], v197 offset:32768
	ds_read_b128 v[90:93], v197 offset:34816
	ds_read_b128 v[94:97], v197 offset:36864
	ds_read_b128 v[98:101], v197 offset:38912
	ds_read_b128 v[102:105], v200 offset:49152
	s_setprio 1
	s_waitcnt lgkmcnt(0)
	v_mfma_f32_16x16x32_bf16 v[44:47], v[102:105], v[40:43], v[32:35]
	v_mfma_f32_16x16x32_bf16 v[40:43], v[102:105], v[90:93], v[36:39]
	v_mfma_f32_16x16x32_bf16 v[36:39], v[102:105], v[94:97], v[82:85]
	v_mfma_f32_16x16x32_bf16 v[32:35], v[102:105], v[98:101], v[86:89]
	s_setprio 0
	v_mov_b32_e32 v122, v169
	s_nop 0
	v_ashrrev_i32_e32 v84, 3, v122
	v_lshlrev_b32_e32 v102, 4, v122
	v_add_u32_e32 v82, s20, v84
	v_and_b32_e32 v130, 0x70, v102
	v_ashrrev_i32_e32 v83, 31, v82
	v_lshl_add_u64 v[48:49], s[16:17], 0, v[130:131]
	v_lshlrev_b64 v[82:83], 9, v[82:83]
	v_lshl_add_u64 v[48:49], v[48:49], 0, v[82:83]
	v_add_u32_e32 v82, s19, v84
	v_ashrrev_i32_e32 v83, 31, v82
	v_lshlrev_b64 v[82:83], 11, v[82:83]
	v_lshl_add_u64 v[82:83], s[14:15], 0, v[82:83]
	v_lshl_add_u64 v[126:127], v[82:83], 0, v[130:131]
	v_add_co_u32_e32 v144, vcc, s33, v126
	global_load_dwordx4 v[82:85], v[126:127], off
	s_nop 0
	v_addc_co_u32_e32 v145, vcc, 0, v127, vcc
	v_add_co_u32_e32 v166, vcc, s56, v126
	global_load_dwordx4 v[86:89], v[144:145], off
	s_nop 0
	v_addc_co_u32_e32 v167, vcc, 0, v127, vcc
	global_load_dwordx4 v[90:93], v[166:167], off
	global_load_dwordx4 v[94:97], v[48:49], off
	v_add_co_u32_e32 v214, vcc, s57, v126
	v_lshrrev_b32_e32 v123, 4, v122
	s_nop 0
	v_addc_co_u32_e32 v215, vcc, 0, v127, vcc
	global_load_dwordx4 v[98:101], v[214:215], off
	v_xor_b32_e32 v103, v123, v122
	v_lshlrev_b32_e32 v103, 4, v103
	v_and_b32_e32 v103, 0x70, v103
	v_and_or_b32 v130, v102, s22, v103
	global_load_dwordx4 v[102:105], v[48:49], off offset:128
	global_load_dwordx4 v[106:109], v[126:127], off offset:128
	global_load_dwordx4 v[110:113], v[144:145], off offset:128
	global_load_dwordx4 v[114:117], v[166:167], off offset:128
	global_load_dwordx4 v[118:121], v[214:215], off offset:128
	s_barrier
	v_and_b32_e32 v124, 15, v122
	v_bfe_u32 v125, v122, 1, 3
	v_bfe_u32 v136, v122, 4, 2
	v_lshlrev_b32_e32 v137, 5, v122
	v_lshlrev_b32_e32 v124, 7, v124
	v_bitop3_b32 v123, v123, v125, 3 bitop3:0x6c
	v_lshlrev_b32_e32 v122, 6, v122
	v_and_or_b32 v137, v137, s21, v124
	v_lshlrev_b32_e32 v123, 4, v123
	v_and_b32_e32 v122, 0xffffe000, v122
	v_or3_b32 v157, v123, v122, v124
	v_or_b32_e32 v168, v137, v123
	v_bitop3_b32 v123, v136, v125, 4 bitop3:0x36
	v_lshlrev_b32_e32 v123, 4, v123
	v_or3_b32 v197, v123, v122, v124
	v_or_b32_e32 v216, v137, v123
	s_waitcnt vmcnt(6)
	ds_write_b128 v130, v[94:97] offset:16384
	ds_write_b128 v130, v[82:85]
	ds_write_b128 v130, v[86:89] offset:4096
	ds_write_b128 v130, v[90:93] offset:8192
	s_waitcnt vmcnt(5)
	ds_write_b128 v130, v[98:101] offset:12288
	s_waitcnt lgkmcnt(0)
	s_barrier
	global_load_dwordx4 v[82:85], v[144:145], off offset:256
	global_load_dwordx4 v[86:89], v[166:167], off offset:256
	global_load_dwordx4 v[90:93], v[214:215], off offset:256
	global_load_dwordx4 v[94:97], v[126:127], off offset:256
	global_load_dwordx4 v[98:101], v[48:49], off offset:256
	ds_read_b128 v[122:125], v157
	ds_read_b128 v[136:139], v157 offset:2048
	ds_read_b128 v[140:143], v157 offset:4096
	ds_read_b128 v[158:161], v157 offset:6144
	ds_read_b128 v[162:165], v168 offset:16384
	s_setprio 1
	s_waitcnt lgkmcnt(0)
	v_mfma_f32_16x16x32_bf16 v[122:125], v[162:165], v[122:125], 0
	v_mfma_f32_16x16x32_bf16 v[136:139], v[162:165], v[136:139], 0
	v_mfma_f32_16x16x32_bf16 v[140:143], v[162:165], v[140:143], 0
	v_mfma_f32_16x16x32_bf16 v[158:161], v[162:165], v[158:161], 0
	s_setprio 0
	ds_read_b128 v[162:165], v197
	ds_read_b128 v[198:201], v197 offset:2048
	ds_read_b128 v[202:205], v197 offset:4096
	ds_read_b128 v[206:209], v197 offset:6144
	ds_read_b128 v[210:213], v216 offset:16384
	s_setprio 1
	s_waitcnt lgkmcnt(0)
	v_mfma_f32_16x16x32_bf16 v[122:125], v[210:213], v[162:165], v[122:125]
	v_mfma_f32_16x16x32_bf16 v[136:139], v[210:213], v[198:201], v[136:139]
	v_mfma_f32_16x16x32_bf16 v[140:143], v[210:213], v[202:205], v[140:143]
	v_mfma_f32_16x16x32_bf16 v[158:161], v[210:213], v[206:209], v[158:161]
	s_setprio 0
	s_waitcnt vmcnt(8)
	ds_write_b128 v130, v[106:109] offset:32768
	s_waitcnt vmcnt(7)
	ds_write_b128 v130, v[110:113] offset:36864
	s_waitcnt vmcnt(6)
	ds_write_b128 v130, v[114:117] offset:40960
	s_waitcnt vmcnt(5)
	ds_write_b128 v130, v[118:121] offset:45056
	ds_write_b128 v130, v[102:105] offset:49152
	s_waitcnt lgkmcnt(0)
	s_barrier
; #define GLOAD(ra, rb, koff)                                                        \
;   {                                                                                \
;     _Pragma("unroll") for (int j = 0; j < 4; j++) ra[j] = *(const u32x4*)(pa + j * sa32 + (koff));   \
;     _Pragma("unroll") for (int j = 0; j < NB_; j++) rb[j] = *(const u32x4*)(pbv[j] + (koff));         \
;   }
; template <int NT, bool PRE> ...
;     ...
;   if (!PRE) {
;     GLOAD(ra0, rb0, 0);
;     GLOAD(ra1, rb1, 64);
;   }
;   __syncthreads();
;   for (int k0 = 0; k0 < K; k0 += 128) {
;     LSTORE(ra0, rb0, 0);
;     __syncthreads();
;     GLOAD(ra0, rb0, min(k0 + 128, K - 128));
;     __builtin_amdgcn_sched_barrier(0);
;     COMPUTE(0);
;     LSTORE(ra1, rb1, 1);
;     __syncthreads();
;     GLOAD(ra1, rb1, min(k0 + 192, K - 64));
;     __builtin_amdgcn_sched_barrier(0);
;     COMPUTE(1);
;   }
	global_load_dwordx4 v[102:105], v[144:145], off offset:384
	global_load_dwordx4 v[106:109], v[166:167], off offset:384
	global_load_dwordx4 v[110:113], v[214:215], off offset:384
	global_load_dwordx4 v[114:117], v[126:127], off offset:384
	global_load_dwordx4 v[118:121], v[48:49], off offset:384
	ds_read_b128 v[162:165], v157 offset:32768
	ds_read_b128 v[198:201], v157 offset:34816
	ds_read_b128 v[202:205], v157 offset:36864
	ds_read_b128 v[206:209], v157 offset:38912
	ds_read_b128 v[210:213], v168 offset:49152
	s_setprio 1
	s_waitcnt lgkmcnt(0)
	v_mfma_f32_16x16x32_bf16 v[122:125], v[210:213], v[162:165], v[122:125]
	v_mfma_f32_16x16x32_bf16 v[136:139], v[210:213], v[198:201], v[136:139]
	v_mfma_f32_16x16x32_bf16 v[140:143], v[210:213], v[202:205], v[140:143]
	v_mfma_f32_16x16x32_bf16 v[158:161], v[210:213], v[206:209], v[158:161]
	s_setprio 0
	ds_read_b128 v[162:165], v197 offset:32768
	ds_read_b128 v[198:201], v197 offset:34816
	ds_read_b128 v[202:205], v197 offset:36864
	ds_read_b128 v[206:209], v197 offset:38912
	ds_read_b128 v[210:213], v216 offset:49152
	s_setprio 1
	s_waitcnt lgkmcnt(0)
	v_mfma_f32_16x16x32_bf16 v[122:125], v[210:213], v[162:165], v[122:125]
	v_mfma_f32_16x16x32_bf16 v[136:139], v[210:213], v[198:201], v[136:139]
	v_mfma_f32_16x16x32_bf16 v[140:143], v[210:213], v[202:205], v[140:143]
	v_mfma_f32_16x16x32_bf16 v[158:161], v[210:213], v[206:209], v[158:161]
	s_setprio 0
	s_waitcnt vmcnt(6)
	ds_write_b128 v130, v[94:97]
	ds_write_b128 v130, v[82:85] offset:4096
	ds_write_b128 v130, v[86:89] offset:8192
	ds_write_b128 v130, v[90:93] offset:12288
	s_waitcnt vmcnt(5)
	ds_write_b128 v130, v[98:101] offset:16384
	s_waitcnt lgkmcnt(0)
	s_barrier
	ds_read_b128 v[82:85], v157
	ds_read_b128 v[86:89], v157 offset:2048
	ds_read_b128 v[90:93], v157 offset:4096
	ds_read_b128 v[94:97], v157 offset:6144
	ds_read_b128 v[98:101], v168 offset:16384
	s_setprio 1
	s_waitcnt lgkmcnt(0)
	v_mfma_f32_16x16x32_bf16 v[82:85], v[98:101], v[82:85], v[122:125]
	v_mfma_f32_16x16x32_bf16 v[86:89], v[98:101], v[86:89], v[136:139]
	v_mfma_f32_16x16x32_bf16 v[90:93], v[98:101], v[90:93], v[140:143]
	v_mfma_f32_16x16x32_bf16 v[94:97], v[98:101], v[94:97], v[158:161]
	s_setprio 0
	ds_read_b128 v[98:101], v197
	ds_read_b128 v[122:125], v197 offset:2048
	ds_read_b128 v[136:139], v197 offset:4096
	ds_read_b128 v[140:143], v197 offset:6144
	ds_read_b128 v[158:161], v216 offset:16384
	s_setprio 1
	s_waitcnt lgkmcnt(0)
	v_mfma_f32_16x16x32_bf16 v[82:85], v[158:161], v[98:101], v[82:85]
	v_mfma_f32_16x16x32_bf16 v[86:89], v[158:161], v[122:125], v[86:89]
	v_mfma_f32_16x16x32_bf16 v[90:93], v[158:161], v[136:139], v[90:93]
	v_mfma_f32_16x16x32_bf16 v[94:97], v[158:161], v[140:143], v[94:97]
	s_setprio 0
	s_waitcnt vmcnt(1)
	ds_write_b128 v130, v[114:117] offset:32768
	ds_write_b128 v130, v[102:105] offset:36864
	ds_write_b128 v130, v[106:109] offset:40960
	ds_write_b128 v130, v[110:113] offset:45056
	s_waitcnt vmcnt(0)
	ds_write_b128 v130, v[118:121] offset:49152
	s_waitcnt lgkmcnt(0)
	s_barrier
; __device__ __forceinline__ float bf2f(u16 h) { return __uint_as_float(((unsigned)h) << 16); }
; __device__ __forceinline__ void phase_merge(const Params& P, u16* sA, u16* sB) {
;     ...
; #pragma unroll
;       for (int mi = 0; mi < 4; mi++) {
;         u32x2 q = gp[mi][i];
;         macc[mi][0] += bf2f(q[0] & 0xffff) * ap[mi][0][0];
;         macc[mi][1] += bf2f(q[0] >> 16) * ap[mi][0][1];
;         macc[mi][2] += bf2f(q[1] & 0xffff) * ap[mi][0][2];
;         macc[mi][3] += bf2f(q[1] >> 16) * ap[mi][0][3];
;       }
;     }
;     const int col = n0 + ((tq >> 6) & 1) * 16 + ((tq & 63) >> 4) * 4;
; #pragma unroll
;     for (int mi = 0; mi < 4; mi++) {
;       int row = m0 + ((tq >> 6) >> 1) * 64 + mi * 16 + (tq & 15);
;       *(uint2*)(MM + (size_t)row * 1024 + col) = pack4(macc[mi]);
;     }
	ds_read_b128 v[98:101], v157 offset:32768
	ds_read_b128 v[102:105], v157 offset:34816
	ds_read_b128 v[106:109], v157 offset:36864
	ds_read_b128 v[110:113], v157 offset:38912
	ds_read_b128 v[114:117], v168 offset:49152
	s_setprio 1
	s_waitcnt lgkmcnt(0)
	v_mfma_f32_16x16x32_bf16 v[82:85], v[114:117], v[98:101], v[82:85]
	v_mfma_f32_16x16x32_bf16 v[86:89], v[114:117], v[102:105], v[86:89]
	v_mfma_f32_16x16x32_bf16 v[90:93], v[114:117], v[106:109], v[90:93]
	v_mfma_f32_16x16x32_bf16 v[94:97], v[114:117], v[110:113], v[94:97]
	s_setprio 0
	ds_read_b128 v[98:101], v197 offset:32768
	ds_read_b128 v[102:105], v197 offset:34816
	ds_read_b128 v[106:109], v197 offset:36864
	ds_read_b128 v[110:113], v197 offset:38912
	ds_read_b128 v[114:117], v216 offset:49152
	s_setprio 1
	s_waitcnt lgkmcnt(0)
	v_mfma_f32_16x16x32_bf16 v[82:85], v[114:117], v[98:101], v[82:85]
	v_mfma_f32_16x16x32_bf16 v[86:89], v[114:117], v[102:105], v[86:89]
	v_mfma_f32_16x16x32_bf16 v[90:93], v[114:117], v[106:109], v[90:93]
	v_mfma_f32_16x16x32_bf16 v[94:97], v[114:117], v[110:113], v[94:97]
	s_setprio 0
	v_and_b32_e32 v49, 0xffff0000, v60
	v_lshlrev_b32_e32 v48, 16, v60
	v_pk_fma_f32 v[12:13], v[12:13], v[48:49], 0 op_sel_hi:[1,1,0]
	v_and_b32_e32 v49, 0xffff0000, v56
	v_lshlrev_b32_e32 v48, 16, v56
	v_pk_fma_f32 v[12:13], v[28:29], v[48:49], v[12:13]
	v_and_b32_e32 v29, 0xffff0000, v52
	v_lshlrev_b32_e32 v28, 16, v52
	v_pk_fma_f32 v[12:13], v[44:45], v[28:29], v[12:13]
	v_and_b32_e32 v29, 0xffff0000, v54
	v_lshlrev_b32_e32 v28, 16, v54
	v_pk_fma_f32 v[12:13], v[82:83], v[28:29], v[12:13]
	v_and_b32_e32 v29, 0xffff0000, v61
	v_lshlrev_b32_e32 v28, 16, v61
	v_pk_fma_f32 v[14:15], v[14:15], v[28:29], 0 op_sel_hi:[1,1,0]
	v_and_b32_e32 v29, 0xffff0000, v57
	v_lshlrev_b32_e32 v28, 16, v57
	v_pk_fma_f32 v[14:15], v[30:31], v[28:29], v[14:15]
	v_and_b32_e32 v29, 0xffff0000, v53
	v_lshlrev_b32_e32 v28, 16, v53
	v_pk_fma_f32 v[14:15], v[46:47], v[28:29], v[14:15]
	v_and_b32_e32 v29, 0xffff0000, v50
	v_lshlrev_b32_e32 v28, 16, v50
	v_pk_fma_f32 v[14:15], v[84:85], v[28:29], v[14:15]
	v_and_b32_e32 v29, 0xffff0000, v51
	v_lshlrev_b32_e32 v28, 16, v51
	v_pk_fma_f32 v[8:9], v[8:9], v[28:29], 0 op_sel_hi:[1,1,0]
	v_and_b32_e32 v29, 0xffff0000, v58
	v_lshlrev_b32_e32 v28, 16, v58
	v_pk_fma_f32 v[8:9], v[24:25], v[28:29], v[8:9]
	v_and_b32_e32 v25, 0xffff0000, v62
	v_lshlrev_b32_e32 v24, 16, v62
	v_pk_fma_f32 v[8:9], v[40:41], v[24:25], v[8:9]
	v_and_b32_e32 v25, 0xffff0000, v64
	v_lshlrev_b32_e32 v24, 16, v64
	v_pk_fma_f32 v[8:9], v[86:87], v[24:25], v[8:9]
	v_and_b32_e32 v25, 0xffff0000, v55
	v_lshlrev_b32_e32 v24, 16, v55
	v_pk_fma_f32 v[10:11], v[10:11], v[24:25], 0 op_sel_hi:[1,1,0]
	v_and_b32_e32 v25, 0xffff0000, v59
	v_lshlrev_b32_e32 v24, 16, v59
	v_pk_fma_f32 v[10:11], v[26:27], v[24:25], v[10:11]
	v_and_b32_e32 v25, 0xffff0000, v63
	v_lshlrev_b32_e32 v24, 16, v63
	v_pk_fma_f32 v[10:11], v[42:43], v[24:25], v[10:11]
	v_and_b32_e32 v25, 0xffff0000, v65
	v_lshlrev_b32_e32 v24, 16, v65
	v_pk_fma_f32 v[10:11], v[88:89], v[24:25], v[10:11]
	v_and_b32_e32 v25, 0xffff0000, v66
	v_lshlrev_b32_e32 v24, 16, v66
	v_pk_fma_f32 v[4:5], v[4:5], v[24:25], 0 op_sel_hi:[1,1,0]
	v_and_b32_e32 v25, 0xffff0000, v68
	v_lshlrev_b32_e32 v24, 16, v68
	v_pk_fma_f32 v[4:5], v[20:21], v[24:25], v[4:5]
	v_and_b32_e32 v21, 0xffff0000, v70
	v_lshlrev_b32_e32 v20, 16, v70
	v_pk_fma_f32 v[4:5], v[36:37], v[20:21], v[4:5]
	v_and_b32_e32 v21, 0xffff0000, v72
	v_lshlrev_b32_e32 v20, 16, v72
	v_pk_fma_f32 v[4:5], v[90:91], v[20:21], v[4:5]
	v_and_b32_e32 v21, 0xffff0000, v67
	v_lshlrev_b32_e32 v20, 16, v67
	v_pk_fma_f32 v[6:7], v[6:7], v[20:21], 0 op_sel_hi:[1,1,0]
	v_and_b32_e32 v21, 0xffff0000, v69
	v_lshlrev_b32_e32 v20, 16, v69
	v_pk_fma_f32 v[6:7], v[22:23], v[20:21], v[6:7]
	v_and_b32_e32 v21, 0xffff0000, v71
	v_lshlrev_b32_e32 v20, 16, v71
	v_pk_fma_f32 v[6:7], v[38:39], v[20:21], v[6:7]
	v_and_b32_e32 v21, 0xffff0000, v73
	v_lshlrev_b32_e32 v20, 16, v73
	v_pk_fma_f32 v[6:7], v[92:93], v[20:21], v[6:7]
	v_and_b32_e32 v21, 0xffff0000, v74
	v_lshlrev_b32_e32 v20, 16, v74
	v_pk_fma_f32 v[0:1], v[0:1], v[20:21], 0 op_sel_hi:[1,1,0]
	v_and_b32_e32 v21, 0xffff0000, v76
	v_lshlrev_b32_e32 v20, 16, v76
	v_pk_fma_f32 v[0:1], v[16:17], v[20:21], v[0:1]
	v_and_b32_e32 v17, 0xffff0000, v78
	v_lshlrev_b32_e32 v16, 16, v78
	v_pk_fma_f32 v[0:1], v[32:33], v[16:17], v[0:1]
	v_and_b32_e32 v17, 0xffff0000, v80
	v_lshlrev_b32_e32 v16, 16, v80
	v_pk_fma_f32 v[0:1], v[94:95], v[16:17], v[0:1]
	v_and_b32_e32 v17, 0xffff0000, v75
	v_lshlrev_b32_e32 v16, 16, v75
	v_pk_fma_f32 v[2:3], v[2:3], v[16:17], 0 op_sel_hi:[1,1,0]
	v_and_b32_e32 v17, 0xffff0000, v77
	v_lshlrev_b32_e32 v16, 16, v77
	v_pk_fma_f32 v[2:3], v[18:19], v[16:17], v[2:3]
	v_and_b32_e32 v17, 0xffff0000, v79
	v_lshlrev_b32_e32 v16, 16, v79
	v_pk_fma_f32 v[2:3], v[34:35], v[16:17], v[2:3]
	v_and_b32_e32 v17, 0xffff0000, v81
	v_lshlrev_b32_e32 v16, 16, v81
	v_pk_fma_f32 v[2:3], v[96:97], v[16:17], v[2:3]
	v_or_b32_e32 v16, s20, v149
	v_add_u32_e32 v18, s19, v150
	v_ashrrev_i32_e32 v17, 31, v16
	v_ashrrev_i32_e32 v19, 31, v18
	v_lshl_add_u64 v[16:17], v[16:17], 1, s[2:3]
	v_cvt_pk_bf16_f32 v12, v12, v13
	v_cvt_pk_bf16_f32 v13, v14, v15
	v_lshlrev_b64 v[14:15], 11, v[18:19]
	v_lshl_add_u64 v[14:15], v[16:17], 0, v[14:15]
	global_store_dwordx2 v[14:15], v[12:13], off
	v_or_b32_e32 v12, 16, v18
	v_ashrrev_i32_e32 v13, 31, v12
	v_cvt_pk_bf16_f32 v8, v8, v9
	v_cvt_pk_bf16_f32 v9, v10, v11
	v_lshlrev_b64 v[10:11], 11, v[12:13]
	v_lshl_add_u64 v[10:11], v[16:17], 0, v[10:11]
	global_store_dwordx2 v[10:11], v[8:9], off
	v_or_b32_e32 v8, 32, v18
	v_ashrrev_i32_e32 v9, 31, v8
	v_cvt_pk_bf16_f32 v4, v4, v5
	v_cvt_pk_bf16_f32 v5, v6, v7
	v_lshlrev_b64 v[6:7], 11, v[8:9]
	v_lshl_add_u64 v[6:7], v[16:17], 0, v[6:7]
	global_store_dwordx2 v[6:7], v[4:5], off
	v_or_b32_e32 v4, 48, v18
	v_ashrrev_i32_e32 v5, 31, v4
	v_cvt_pk_bf16_f32 v0, v0, v1
	v_cvt_pk_bf16_f32 v1, v2, v3
	v_lshlrev_b64 v[2:3], 11, v[4:5]
	s_add_i32 s18, s18, s90
	v_lshl_add_u64 v[2:3], v[16:17], 0, v[2:3]
	s_cmpk_lt_i32 s18, 0x1080
	global_store_dwordx2 v[2:3], v[0:1], off
	s_cbranch_scc1 .LBB0_1988

; #define GLOAD(ra, rb, koff)                                                        \
;   {                                                                                \
;     _Pragma("unroll") for (int j = 0; j < 4; j++) ra[j] = *(const u32x4*)(pa + j * sa32 + (koff));   \
;     _Pragma("unroll") for (int j = 0; j < NB_; j++) rb[j] = *(const u32x4*)(pbv[j] + (koff));         \
;   }
; template <int NT, bool PRE> ...
;     ...
;   if (!PRE) {
;     GLOAD(ra0, rb0, 0);
;     GLOAD(ra1, rb1, 64);
;   }
;   __syncthreads();
;   for (int k0 = 0; k0 < K; k0 += 128) {
;     LSTORE(ra0, rb0, 0);
;     __syncthreads();
;     GLOAD(ra0, rb0, min(k0 + 128, K - 128));
;     __builtin_amdgcn_sched_barrier(0);
;     COMPUTE(0);
;     LSTORE(ra1, rb1, 1);
;     __syncthreads();
;     GLOAD(ra1, rb1, min(k0 + 192, K - 64));
;     __builtin_amdgcn_sched_barrier(0);
;     COMPUTE(1);
;   }
.LBB0_2043:
	s_add_i32 s5, s4, 0x100
	s_min_u32 s5, s5, 0x380
	s_lshl_b32 s54, s5, 1
	ds_read_b128 v[156:159], v152
	ds_read_b128 v[202:205], v153 offset:16384
	ds_read_b128 v[206:209], v153 offset:18432
	ds_read_b128 v[210:213], v153 offset:20480
	ds_read_b128 v[214:217], v153 offset:22528
	ds_read_b128 v[160:163], v152 offset:2048
	ds_read_b128 v[164:167], v152 offset:4096
	ds_read_b128 v[198:201], v152 offset:6144
	ds_read_b128 v[218:221], v154
	ds_read_b128 v[222:225], v154 offset:2048
	ds_read_b128 v[226:229], v154 offset:4096
	ds_read_b128 v[230:233], v154 offset:6144
	ds_read_b128 v[234:237], v155 offset:16384
	ds_read_b128 v[238:241], v155 offset:18432
	ds_read_b128 v[242:245], v155 offset:20480
	v_lshl_add_u64 v[8:9], v[142:143], 0, s[54:55]
	v_add_co_u32_e32 v16, vcc, s33, v8
	v_lshl_add_u64 v[0:1], v[134:135], 0, s[54:55]
	s_nop 0
	v_addc_co_u32_e32 v17, vcc, 0, v9, vcc
	v_add_co_u32_e32 v32, vcc, s56, v8
	v_lshl_add_u64 v[2:3], v[136:137], 0, s[54:55]
	s_nop 0
	v_addc_co_u32_e32 v33, vcc, 0, v9, vcc
	v_add_co_u32_e32 v48, vcc, s57, v8
	v_lshl_add_u64 v[4:5], v[138:139], 0, s[54:55]
	v_lshl_add_u64 v[10:11], v[140:141], 0, s[54:55]
	v_addc_co_u32_e32 v49, vcc, 0, v9, vcc
	s_addk_i32 s4, 0x80
	s_setprio 1
	global_load_dwordx4 v[20:23], v[0:1], off
	s_nop 0
	global_load_dwordx4 v[0:3], v[2:3], off
	s_waitcnt lgkmcnt(13)
	v_mfma_f32_16x16x32_bf16 v[124:127], v[202:205], v[156:159], v[124:127]
	s_waitcnt lgkmcnt(12)
	v_mfma_f32_16x16x32_bf16 v[116:119], v[206:209], v[156:159], v[116:119]
	s_waitcnt lgkmcnt(11)
	v_mfma_f32_16x16x32_bf16 v[112:115], v[210:213], v[156:159], v[112:115]
	s_waitcnt lgkmcnt(10)
	v_mfma_f32_16x16x32_bf16 v[108:111], v[214:217], v[156:159], v[108:111]
	ds_read_b128 v[156:159], v155 offset:22528
	global_load_dwordx4 v[4:7], v[4:5], off
	s_nop 0
	global_load_dwordx4 v[52:55], v[10:11], off
	s_waitcnt lgkmcnt(10)
	v_mfma_f32_16x16x32_bf16 v[120:123], v[202:205], v[160:163], v[120:123]
	v_mfma_f32_16x16x32_bf16 v[104:107], v[206:209], v[160:163], v[104:107]
	v_mfma_f32_16x16x32_bf16 v[96:99], v[210:213], v[160:163], v[96:99]
	v_mfma_f32_16x16x32_bf16 v[92:95], v[214:217], v[160:163], v[92:95]
	global_load_dwordx4 v[8:11], v[8:9], off
	s_nop 0
	global_load_dwordx4 v[16:19], v[16:17], off
	s_waitcnt lgkmcnt(9)
	v_mfma_f32_16x16x32_bf16 v[100:103], v[202:205], v[164:167], v[100:103]
	v_mfma_f32_16x16x32_bf16 v[88:91], v[206:209], v[164:167], v[88:91]
	v_mfma_f32_16x16x32_bf16 v[84:87], v[210:213], v[164:167], v[84:87]
	v_mfma_f32_16x16x32_bf16 v[76:79], v[214:217], v[164:167], v[76:79]
	global_load_dwordx4 v[32:35], v[32:33], off
	s_nop 0
	global_load_dwordx4 v[48:51], v[48:49], off
	s_waitcnt lgkmcnt(8)
	v_mfma_f32_16x16x32_bf16 v[80:83], v[202:205], v[198:201], v[80:83]
	v_mfma_f32_16x16x32_bf16 v[72:75], v[206:209], v[198:201], v[72:75]
	v_mfma_f32_16x16x32_bf16 v[68:71], v[210:213], v[198:201], v[68:71]
	v_mfma_f32_16x16x32_bf16 v[64:67], v[214:217], v[198:201], v[64:67]
	s_waitcnt lgkmcnt(3)
	s_waitcnt vmcnt(14)
	ds_write_b128 v150, v[28:31] offset:49152
	ds_write_b128 v150, v[36:39] offset:53248
	v_mfma_f32_16x16x32_bf16 v[124:127], v[234:237], v[218:221], v[124:127]
	v_mfma_f32_16x16x32_bf16 v[120:123], v[234:237], v[222:225], v[120:123]
	v_mfma_f32_16x16x32_bf16 v[100:103], v[234:237], v[226:229], v[100:103]
	v_mfma_f32_16x16x32_bf16 v[80:83], v[234:237], v[230:233], v[80:83]
	s_waitcnt lgkmcnt(4)
	s_waitcnt vmcnt(11)
	ds_write_b128 v150, v[44:47] offset:57344
	ds_write_b128 v150, v[12:15] offset:32768
	v_mfma_f32_16x16x32_bf16 v[116:119], v[238:241], v[218:221], v[116:119]
	v_mfma_f32_16x16x32_bf16 v[104:107], v[238:241], v[222:225], v[104:107]
	v_mfma_f32_16x16x32_bf16 v[88:91], v[238:241], v[226:229], v[88:91]
	v_mfma_f32_16x16x32_bf16 v[72:75], v[238:241], v[230:233], v[72:75]
	s_waitcnt lgkmcnt(5)
	s_waitcnt vmcnt(9)
	ds_write_b128 v150, v[24:27] offset:36864
	ds_write_b128 v150, v[40:43] offset:40960
	v_mfma_f32_16x16x32_bf16 v[112:115], v[242:245], v[218:221], v[112:115]
	v_mfma_f32_16x16x32_bf16 v[96:99], v[242:245], v[222:225], v[96:99]
	v_mfma_f32_16x16x32_bf16 v[84:87], v[242:245], v[226:229], v[84:87]
	v_mfma_f32_16x16x32_bf16 v[68:71], v[242:245], v[230:233], v[68:71]
	s_waitcnt lgkmcnt(6)
	s_waitcnt vmcnt(8)
	ds_write_b128 v150, v[56:59] offset:45056
	ds_write_b128 v150, v[60:63] offset:61440
	v_mfma_f32_16x16x32_bf16 v[108:111], v[156:159], v[218:221], v[108:111]
	v_mfma_f32_16x16x32_bf16 v[92:95], v[156:159], v[222:225], v[92:95]
	v_mfma_f32_16x16x32_bf16 v[76:79], v[156:159], v[226:229], v[76:79]
	v_mfma_f32_16x16x32_bf16 v[64:67], v[156:159], v[230:233], v[64:67]
	s_setprio 0
	s_waitcnt lgkmcnt(0)
	s_barrier
; #define GLOAD(ra, rb, koff)                                                        \
;   {                                                                                \
;     _Pragma("unroll") for (int j = 0; j < 4; j++) ra[j] = *(const u32x4*)(pa + j * sa32 + (koff));   \
;     _Pragma("unroll") for (int j = 0; j < NB_; j++) rb[j] = *(const u32x4*)(pbv[j] + (koff));         \
;   }
; template <int NT, bool PRE> ...
;     ...
;   if (!PRE) {
;     GLOAD(ra0, rb0, 0);
;     GLOAD(ra1, rb1, 64);
;   }
;   __syncthreads();
;   for (int k0 = 0; k0 < K; k0 += 128) {
;     LSTORE(ra0, rb0, 0);
;     __syncthreads();
;     GLOAD(ra0, rb0, min(k0 + 128, K - 128));
;     __builtin_amdgcn_sched_barrier(0);
;     COMPUTE(0);
;     LSTORE(ra1, rb1, 1);
;     __syncthreads();
;     GLOAD(ra1, rb1, min(k0 + 192, K - 64));
;     __builtin_amdgcn_sched_barrier(0);
;     COMPUTE(1);
;   }
	s_min_u32 s5, s4, 0x300
	s_lshl_b32 s54, s5, 1
	ds_read_b128 v[156:159], v152 offset:32768
	ds_read_b128 v[202:205], v153 offset:49152
	ds_read_b128 v[206:209], v153 offset:51200
	ds_read_b128 v[210:213], v153 offset:53248
	ds_read_b128 v[214:217], v153 offset:55296
	ds_read_b128 v[160:163], v152 offset:34816
	ds_read_b128 v[164:167], v152 offset:36864
	ds_read_b128 v[198:201], v152 offset:38912
	ds_read_b128 v[218:221], v154 offset:32768
	ds_read_b128 v[222:225], v154 offset:34816
	ds_read_b128 v[226:229], v154 offset:36864
	ds_read_b128 v[230:233], v154 offset:38912
	ds_read_b128 v[234:237], v155 offset:49152
	ds_read_b128 v[238:241], v155 offset:51200
	ds_read_b128 v[242:245], v155 offset:53248
	v_lshl_add_u64 v[12:13], v[142:143], 0, s[54:55]
	v_add_co_u32_e32 v42, vcc, s33, v12
	v_lshl_add_u64 v[14:15], v[134:135], 0, s[54:55]
	s_nop 0
	v_addc_co_u32_e32 v43, vcc, 0, v13, vcc
	v_add_co_u32_e32 v56, vcc, s56, v12
	v_lshl_add_u64 v[24:25], v[136:137], 0, s[54:55]
	s_nop 0
	v_addc_co_u32_e32 v57, vcc, 0, v13, vcc
	v_add_co_u32_e32 v58, vcc, s57, v12
	v_lshl_add_u64 v[26:27], v[138:139], 0, s[54:55]
	v_lshl_add_u64 v[40:41], v[140:141], 0, s[54:55]
	v_addc_co_u32_e32 v59, vcc, 0, v13, vcc
	s_setprio 1
	global_load_dwordx4 v[28:31], v[14:15], off offset:384
	s_nop 0
	global_load_dwordx4 v[36:39], v[24:25], off offset:384
	s_waitcnt lgkmcnt(13)
	v_mfma_f32_16x16x32_bf16 v[124:127], v[202:205], v[156:159], v[124:127]
	s_waitcnt lgkmcnt(12)
	v_mfma_f32_16x16x32_bf16 v[116:119], v[206:209], v[156:159], v[116:119]
	s_waitcnt lgkmcnt(11)
	v_mfma_f32_16x16x32_bf16 v[112:115], v[210:213], v[156:159], v[112:115]
	s_waitcnt lgkmcnt(10)
	v_mfma_f32_16x16x32_bf16 v[108:111], v[214:217], v[156:159], v[108:111]
	ds_read_b128 v[156:159], v155 offset:55296
	global_load_dwordx4 v[44:47], v[26:27], off offset:384
	s_nop 0
	global_load_dwordx4 v[60:63], v[40:41], off offset:384
	s_waitcnt lgkmcnt(10)
	v_mfma_f32_16x16x32_bf16 v[120:123], v[202:205], v[160:163], v[120:123]
	v_mfma_f32_16x16x32_bf16 v[104:107], v[206:209], v[160:163], v[104:107]
	v_mfma_f32_16x16x32_bf16 v[96:99], v[210:213], v[160:163], v[96:99]
	v_mfma_f32_16x16x32_bf16 v[92:95], v[214:217], v[160:163], v[92:95]
	global_load_dwordx4 v[12:15], v[12:13], off offset:384
	s_nop 0
	global_load_dwordx4 v[24:27], v[42:43], off offset:384
	s_waitcnt lgkmcnt(9)
	v_mfma_f32_16x16x32_bf16 v[100:103], v[202:205], v[164:167], v[100:103]
	v_mfma_f32_16x16x32_bf16 v[88:91], v[206:209], v[164:167], v[88:91]
	v_mfma_f32_16x16x32_bf16 v[84:87], v[210:213], v[164:167], v[84:87]
	v_mfma_f32_16x16x32_bf16 v[76:79], v[214:217], v[164:167], v[76:79]
	global_load_dwordx4 v[40:43], v[56:57], off offset:384
	s_nop 0
	global_load_dwordx4 v[56:59], v[58:59], off offset:384
	s_waitcnt lgkmcnt(8)
	v_mfma_f32_16x16x32_bf16 v[80:83], v[202:205], v[198:201], v[80:83]
	v_mfma_f32_16x16x32_bf16 v[72:75], v[206:209], v[198:201], v[72:75]
	v_mfma_f32_16x16x32_bf16 v[68:71], v[210:213], v[198:201], v[68:71]
	v_mfma_f32_16x16x32_bf16 v[64:67], v[214:217], v[198:201], v[64:67]
	s_waitcnt lgkmcnt(3)
	s_waitcnt vmcnt(14)
	ds_write_b128 v150, v[20:23] offset:16384
	ds_write_b128 v150, v[0:3] offset:20480
	v_mfma_f32_16x16x32_bf16 v[124:127], v[234:237], v[218:221], v[124:127]
	v_mfma_f32_16x16x32_bf16 v[120:123], v[234:237], v[222:225], v[120:123]
	v_mfma_f32_16x16x32_bf16 v[100:103], v[234:237], v[226:229], v[100:103]
	v_mfma_f32_16x16x32_bf16 v[80:83], v[234:237], v[230:233], v[80:83]
	s_waitcnt lgkmcnt(4)
	s_waitcnt vmcnt(12)
	ds_write_b128 v150, v[4:7] offset:24576
	ds_write_b128 v150, v[52:55] offset:28672
	v_mfma_f32_16x16x32_bf16 v[116:119], v[238:241], v[218:221], v[116:119]
	v_mfma_f32_16x16x32_bf16 v[104:107], v[238:241], v[222:225], v[104:107]
	v_mfma_f32_16x16x32_bf16 v[88:91], v[238:241], v[226:229], v[88:91]
	v_mfma_f32_16x16x32_bf16 v[72:75], v[238:241], v[230:233], v[72:75]
	s_waitcnt lgkmcnt(5)
	s_waitcnt vmcnt(10)
	ds_write_b128 v150, v[8:11]
	ds_write_b128 v150, v[16:19] offset:4096
	v_mfma_f32_16x16x32_bf16 v[112:115], v[242:245], v[218:221], v[112:115]
	v_mfma_f32_16x16x32_bf16 v[96:99], v[242:245], v[222:225], v[96:99]
	v_mfma_f32_16x16x32_bf16 v[84:87], v[242:245], v[226:229], v[84:87]
	v_mfma_f32_16x16x32_bf16 v[68:71], v[242:245], v[230:233], v[68:71]
	s_waitcnt lgkmcnt(6)
	s_waitcnt vmcnt(8)
	ds_write_b128 v150, v[32:35] offset:8192
	ds_write_b128 v150, v[48:51] offset:12288
	v_mfma_f32_16x16x32_bf16 v[108:111], v[156:159], v[218:221], v[108:111]
	v_mfma_f32_16x16x32_bf16 v[92:95], v[156:159], v[222:225], v[92:95]
	v_mfma_f32_16x16x32_bf16 v[76:79], v[156:159], v[226:229], v[76:79]
	v_mfma_f32_16x16x32_bf16 v[64:67], v[156:159], v[230:233], v[64:67]
	s_setprio 0
	s_waitcnt lgkmcnt(0)
	s_barrier
	s_cmpk_lt_u32 s4, 0x300
	s_cbranch_scc1 .LBB0_2043
; #define GLOAD(ra, rb, koff)                                                        \
;   {                                                                                \
;     _Pragma("unroll") for (int j = 0; j < 4; j++) ra[j] = *(const u32x4*)(pa + j * sa32 + (koff));   \
;     _Pragma("unroll") for (int j = 0; j < NB_; j++) rb[j] = *(const u32x4*)(pbv[j] + (koff));         \
;   }
; template <int NT, bool PRE> ...
;     ...
;   if (!PRE) {
;     GLOAD(ra0, rb0, 0);
;     GLOAD(ra1, rb1, 64);
;   }
;   __syncthreads();
;   for (int k0 = 0; k0 < K; k0 += 128) {
;     LSTORE(ra0, rb0, 0);
;     __syncthreads();
;     GLOAD(ra0, rb0, min(k0 + 128, K - 128));
;     __builtin_amdgcn_sched_barrier(0);
;     COMPUTE(0);
;     LSTORE(ra1, rb1, 1);
;     __syncthreads();
;     GLOAD(ra1, rb1, min(k0 + 192, K - 64));
;     __builtin_amdgcn_sched_barrier(0);
;     COMPUTE(1);
;   }
	ds_read_b128 v[156:159], v152
	ds_read_b128 v[202:205], v153 offset:16384
	ds_read_b128 v[206:209], v153 offset:18432
	ds_read_b128 v[210:213], v153 offset:20480
	ds_read_b128 v[214:217], v153 offset:22528
	ds_read_b128 v[160:163], v152 offset:2048
	ds_read_b128 v[164:167], v152 offset:4096
	ds_read_b128 v[198:201], v152 offset:6144
	ds_read_b128 v[218:221], v154
	ds_read_b128 v[222:225], v154 offset:2048
	ds_read_b128 v[226:229], v154 offset:4096
	ds_read_b128 v[230:233], v154 offset:6144
	ds_read_b128 v[234:237], v155 offset:16384
	ds_read_b128 v[238:241], v155 offset:18432
	ds_read_b128 v[242:245], v155 offset:20480
	s_addk_i32 s4, 0x80
	s_setprio 1
	s_waitcnt lgkmcnt(13)
	v_mfma_f32_16x16x32_bf16 v[124:127], v[202:205], v[156:159], v[124:127]
	s_waitcnt lgkmcnt(12)
	v_mfma_f32_16x16x32_bf16 v[116:119], v[206:209], v[156:159], v[116:119]
	s_waitcnt lgkmcnt(11)
	v_mfma_f32_16x16x32_bf16 v[112:115], v[210:213], v[156:159], v[112:115]
	s_waitcnt lgkmcnt(10)
	v_mfma_f32_16x16x32_bf16 v[108:111], v[214:217], v[156:159], v[108:111]
	ds_read_b128 v[156:159], v155 offset:22528
	s_waitcnt lgkmcnt(10)
	v_mfma_f32_16x16x32_bf16 v[120:123], v[202:205], v[160:163], v[120:123]
	v_mfma_f32_16x16x32_bf16 v[104:107], v[206:209], v[160:163], v[104:107]
	v_mfma_f32_16x16x32_bf16 v[96:99], v[210:213], v[160:163], v[96:99]
	v_mfma_f32_16x16x32_bf16 v[92:95], v[214:217], v[160:163], v[92:95]
	s_waitcnt lgkmcnt(9)
	v_mfma_f32_16x16x32_bf16 v[100:103], v[202:205], v[164:167], v[100:103]
	v_mfma_f32_16x16x32_bf16 v[88:91], v[206:209], v[164:167], v[88:91]
	v_mfma_f32_16x16x32_bf16 v[84:87], v[210:213], v[164:167], v[84:87]
	v_mfma_f32_16x16x32_bf16 v[76:79], v[214:217], v[164:167], v[76:79]
	s_waitcnt lgkmcnt(8)
	v_mfma_f32_16x16x32_bf16 v[80:83], v[202:205], v[198:201], v[80:83]
	v_mfma_f32_16x16x32_bf16 v[72:75], v[206:209], v[198:201], v[72:75]
	v_mfma_f32_16x16x32_bf16 v[68:71], v[210:213], v[198:201], v[68:71]
	v_mfma_f32_16x16x32_bf16 v[64:67], v[214:217], v[198:201], v[64:67]
	s_waitcnt lgkmcnt(3)
	s_waitcnt vmcnt(6)
	ds_write_b128 v150, v[28:31] offset:49152
	ds_write_b128 v150, v[36:39] offset:53248
	v_mfma_f32_16x16x32_bf16 v[124:127], v[234:237], v[218:221], v[124:127]
	v_mfma_f32_16x16x32_bf16 v[120:123], v[234:237], v[222:225], v[120:123]
	v_mfma_f32_16x16x32_bf16 v[100:103], v[234:237], v[226:229], v[100:103]
	v_mfma_f32_16x16x32_bf16 v[80:83], v[234:237], v[230:233], v[80:83]
	s_waitcnt lgkmcnt(4)
	s_waitcnt vmcnt(3)
	ds_write_b128 v150, v[44:47] offset:57344
	ds_write_b128 v150, v[12:15] offset:32768
	v_mfma_f32_16x16x32_bf16 v[116:119], v[238:241], v[218:221], v[116:119]
	v_mfma_f32_16x16x32_bf16 v[104:107], v[238:241], v[222:225], v[104:107]
	v_mfma_f32_16x16x32_bf16 v[88:91], v[238:241], v[226:229], v[88:91]
	v_mfma_f32_16x16x32_bf16 v[72:75], v[238:241], v[230:233], v[72:75]
	s_waitcnt lgkmcnt(5)
	s_waitcnt vmcnt(1)
	ds_write_b128 v150, v[24:27] offset:36864
	ds_write_b128 v150, v[40:43] offset:40960
	v_mfma_f32_16x16x32_bf16 v[112:115], v[242:245], v[218:221], v[112:115]
	v_mfma_f32_16x16x32_bf16 v[96:99], v[242:245], v[222:225], v[96:99]
	v_mfma_f32_16x16x32_bf16 v[84:87], v[242:245], v[226:229], v[84:87]
	v_mfma_f32_16x16x32_bf16 v[68:71], v[242:245], v[230:233], v[68:71]
	s_waitcnt lgkmcnt(6)
	s_waitcnt vmcnt(0)
	ds_write_b128 v150, v[56:59] offset:45056
	ds_write_b128 v150, v[60:63] offset:61440
	v_mfma_f32_16x16x32_bf16 v[108:111], v[156:159], v[218:221], v[108:111]
	v_mfma_f32_16x16x32_bf16 v[92:95], v[156:159], v[222:225], v[92:95]
	v_mfma_f32_16x16x32_bf16 v[76:79], v[156:159], v[226:229], v[76:79]
	v_mfma_f32_16x16x32_bf16 v[64:67], v[156:159], v[230:233], v[64:67]
	s_setprio 0
	s_waitcnt lgkmcnt(0)
	s_barrier
; #define GLOAD(ra, rb, koff)                                                        \
;   {                                                                                \
;     _Pragma("unroll") for (int j = 0; j < 4; j++) ra[j] = *(const u32x4*)(pa + j * sa32 + (koff));   \
;     _Pragma("unroll") for (int j = 0; j < NB_; j++) rb[j] = *(const u32x4*)(pbv[j] + (koff));         \
;   }
; template <int NT, bool PRE> ...
;     ...
;   if (!PRE) {
;     GLOAD(ra0, rb0, 0);
;     GLOAD(ra1, rb1, 64);
;   }
;   __syncthreads();
;   for (int k0 = 0; k0 < K; k0 += 128) {
;     LSTORE(ra0, rb0, 0);
;     __syncthreads();
;     GLOAD(ra0, rb0, min(k0 + 128, K - 128));
;     __builtin_amdgcn_sched_barrier(0);
;     COMPUTE(0);
;     LSTORE(ra1, rb1, 1);
;     __syncthreads();
;     GLOAD(ra1, rb1, min(k0 + 192, K - 64));
;     __builtin_amdgcn_sched_barrier(0);
;     COMPUTE(1);
;   }
; template <int EPI>
; __device__ __forceinline__ void phase_gemm(const Params& P, const u16* A, int lda, const u16* Bt, int K, int N, u16* sA, u16* sB) {
;     ...
;     for (; t < Tfull; t += G) {
;       const int m0 = (t % 132) * 128, n0 = (t / 132) * 128;
;       f32x4 acc[4][4];
;       zero_acc<4>(acc);
;       gemm_core_r<4, true>(pa, (size_t)32 * lda, pbv, K, acc, sA, sB, tq, ra0, rb0, ra1, rb1);
;       if (t + G < Tfull) {
;         PG_PTRS(t + G);
;         gemm_preload<4>(pa, (size_t)32 * lda, pbv, ra0, rb0, ra1, rb1);
	ds_read_b128 v[156:159], v152 offset:32768
	ds_read_b128 v[202:205], v153 offset:49152
	ds_read_b128 v[206:209], v153 offset:51200
	ds_read_b128 v[210:213], v153 offset:53248
	ds_read_b128 v[214:217], v153 offset:55296
	ds_read_b128 v[160:163], v152 offset:34816
	ds_read_b128 v[164:167], v152 offset:36864
	ds_read_b128 v[198:201], v152 offset:38912
	ds_read_b128 v[218:221], v154 offset:32768
	ds_read_b128 v[222:225], v154 offset:34816
	ds_read_b128 v[226:229], v154 offset:36864
	ds_read_b128 v[230:233], v154 offset:38912
	ds_read_b128 v[234:237], v155 offset:49152
	ds_read_b128 v[238:241], v155 offset:51200
	ds_read_b128 v[242:245], v155 offset:53248
	s_setprio 1
	s_waitcnt lgkmcnt(13)
	v_mfma_f32_16x16x32_bf16 v[124:127], v[202:205], v[156:159], v[124:127]
	s_waitcnt lgkmcnt(12)
	v_mfma_f32_16x16x32_bf16 v[116:119], v[206:209], v[156:159], v[116:119]
	s_waitcnt lgkmcnt(11)
	v_mfma_f32_16x16x32_bf16 v[112:115], v[210:213], v[156:159], v[112:115]
	s_waitcnt lgkmcnt(10)
	v_mfma_f32_16x16x32_bf16 v[108:111], v[214:217], v[156:159], v[108:111]
	ds_read_b128 v[156:159], v155 offset:55296
	s_waitcnt lgkmcnt(10)
	v_mfma_f32_16x16x32_bf16 v[120:123], v[202:205], v[160:163], v[120:123]
	v_mfma_f32_16x16x32_bf16 v[104:107], v[206:209], v[160:163], v[104:107]
	v_mfma_f32_16x16x32_bf16 v[96:99], v[210:213], v[160:163], v[96:99]
	v_mfma_f32_16x16x32_bf16 v[92:95], v[214:217], v[160:163], v[92:95]
	s_waitcnt lgkmcnt(9)
	v_mfma_f32_16x16x32_bf16 v[100:103], v[202:205], v[164:167], v[100:103]
	v_mfma_f32_16x16x32_bf16 v[88:91], v[206:209], v[164:167], v[88:91]
	v_mfma_f32_16x16x32_bf16 v[84:87], v[210:213], v[164:167], v[84:87]
	v_mfma_f32_16x16x32_bf16 v[76:79], v[214:217], v[164:167], v[76:79]
	s_waitcnt lgkmcnt(8)
	v_mfma_f32_16x16x32_bf16 v[80:83], v[202:205], v[198:201], v[80:83]
	v_mfma_f32_16x16x32_bf16 v[72:75], v[206:209], v[198:201], v[72:75]
	v_mfma_f32_16x16x32_bf16 v[68:71], v[210:213], v[198:201], v[68:71]
	v_mfma_f32_16x16x32_bf16 v[64:67], v[214:217], v[198:201], v[64:67]
	s_waitcnt lgkmcnt(3)
	v_mfma_f32_16x16x32_bf16 v[124:127], v[234:237], v[218:221], v[124:127]
	v_mfma_f32_16x16x32_bf16 v[120:123], v[234:237], v[222:225], v[120:123]
	v_mfma_f32_16x16x32_bf16 v[100:103], v[234:237], v[226:229], v[100:103]
	v_mfma_f32_16x16x32_bf16 v[80:83], v[234:237], v[230:233], v[80:83]
	s_waitcnt lgkmcnt(2)
	v_mfma_f32_16x16x32_bf16 v[116:119], v[238:241], v[218:221], v[116:119]
	v_mfma_f32_16x16x32_bf16 v[104:107], v[238:241], v[222:225], v[104:107]
	v_mfma_f32_16x16x32_bf16 v[88:91], v[238:241], v[226:229], v[88:91]
	v_mfma_f32_16x16x32_bf16 v[72:75], v[238:241], v[230:233], v[72:75]
	s_waitcnt lgkmcnt(1)
	v_mfma_f32_16x16x32_bf16 v[112:115], v[242:245], v[218:221], v[112:115]
	v_mfma_f32_16x16x32_bf16 v[96:99], v[242:245], v[222:225], v[96:99]
	v_mfma_f32_16x16x32_bf16 v[84:87], v[242:245], v[226:229], v[84:87]
	v_mfma_f32_16x16x32_bf16 v[68:71], v[242:245], v[230:233], v[68:71]
	s_waitcnt lgkmcnt(0)
	v_mfma_f32_16x16x32_bf16 v[108:111], v[156:159], v[218:221], v[108:111]
	v_mfma_f32_16x16x32_bf16 v[92:95], v[156:159], v[222:225], v[92:95]
	v_mfma_f32_16x16x32_bf16 v[76:79], v[156:159], v[226:229], v[76:79]
	v_mfma_f32_16x16x32_bf16 v[64:67], v[156:159], v[230:233], v[64:67]
	s_setprio 0
	s_waitcnt lgkmcnt(0)
	s_add_i32 s7, s6, s90
	s_cmp_ge_i32 s7, s16
	s_cselect_b64 s[4:5], -1, 0
	s_and_b64 vcc, exec, s[4:5]
	s_cbranch_vccnz .LBB0_2041
	s_cmp_lg_u32 s90, 0x200
	s_cbranch_scc1 .Lrm_wop_orig
	s_and_b32 s54, s7, 7
	s_lshl_b32 s54, s54, 6
	s_bfe_u32 s8, s7, 0x60003
	s_or_b32 s54, s54, s8
	s_andn2_b32 s8, s7, 0x1ff
	s_or_b32 s54, s54, s8
	s_cmp_lt_u32 s54, 0
	s_cbranch_scc0 .Lrm_wop_b
	s_lshr_b32 s8, s54, 3
	s_mul_hi_u32 s8, s8, 0x3e0f83e1
	s_lshr_b32 s8, s8, 5
	s_mul_i32 s9, s8, 1056
	s_sub_i32 s54, s54, s9
	s_lshl_b32 s8, s8, 3
	s_and_b32 s9, s54, 7
	s_add_i32 s8, s8, s9
	s_lshr_b32 s9, s54, 3
	s_branch .Lrm_wop_done

; #define GLOAD(ra, rb, koff)                                                        \
;   {                                                                                \
;     _Pragma("unroll") for (int j = 0; j < 4; j++) ra[j] = *(const u32x4*)(pa + j * sa32 + (koff));   \
;     _Pragma("unroll") for (int j = 0; j < NB_; j++) rb[j] = *(const u32x4*)(pbv[j] + (koff));         \
;   }
; template <int NT, bool PRE> ...
;     ...
;   if (!PRE) {
;     GLOAD(ra0, rb0, 0);
;     GLOAD(ra1, rb1, 64);
;   }
;   __syncthreads();
;   for (int k0 = 0; k0 < K; k0 += 128) {
;     LSTORE(ra0, rb0, 0);
;     __syncthreads();
;     GLOAD(ra0, rb0, min(k0 + 128, K - 128));
;     __builtin_amdgcn_sched_barrier(0);
;     COMPUTE(0);
;     LSTORE(ra1, rb1, 1);
;     __syncthreads();
;     GLOAD(ra1, rb1, min(k0 + 192, K - 64));
;     __builtin_amdgcn_sched_barrier(0);
;     COMPUTE(1);
;   }
.LBB0_2230:
	s_add_i32 s5, s4, 0x100
	s_min_u32 s5, s5, 0x380
	s_lshl_b32 s54, s5, 1
	ds_read_b128 v[156:159], v152
	ds_read_b128 v[202:205], v153 offset:16384
	ds_read_b128 v[206:209], v153 offset:18432
	ds_read_b128 v[210:213], v153 offset:20480
	ds_read_b128 v[214:217], v153 offset:22528
	ds_read_b128 v[160:163], v152 offset:2048
	ds_read_b128 v[164:167], v152 offset:4096
	ds_read_b128 v[198:201], v152 offset:6144
	ds_read_b128 v[218:221], v154
	ds_read_b128 v[222:225], v154 offset:2048
	ds_read_b128 v[226:229], v154 offset:4096
	ds_read_b128 v[230:233], v154 offset:6144
	ds_read_b128 v[234:237], v155 offset:16384
	ds_read_b128 v[238:241], v155 offset:18432
	ds_read_b128 v[242:245], v155 offset:20480
	v_lshl_add_u64 v[8:9], v[142:143], 0, s[54:55]
	v_add_co_u32_e32 v16, vcc, s33, v8
	v_lshl_add_u64 v[0:1], v[134:135], 0, s[54:55]
	s_nop 0
	v_addc_co_u32_e32 v17, vcc, 0, v9, vcc
	v_add_co_u32_e32 v32, vcc, s56, v8
	v_lshl_add_u64 v[2:3], v[136:137], 0, s[54:55]
	s_nop 0
	v_addc_co_u32_e32 v33, vcc, 0, v9, vcc
	v_add_co_u32_e32 v48, vcc, s57, v8
	v_lshl_add_u64 v[4:5], v[138:139], 0, s[54:55]
	v_lshl_add_u64 v[10:11], v[140:141], 0, s[54:55]
	v_addc_co_u32_e32 v49, vcc, 0, v9, vcc
	s_addk_i32 s4, 0x80
	s_setprio 1
	global_load_dwordx4 v[20:23], v[0:1], off
	s_nop 0
	global_load_dwordx4 v[0:3], v[2:3], off
	s_waitcnt lgkmcnt(13)
	v_mfma_f32_16x16x32_bf16 v[124:127], v[202:205], v[156:159], v[124:127]
	s_waitcnt lgkmcnt(12)
	v_mfma_f32_16x16x32_bf16 v[112:115], v[206:209], v[156:159], v[112:115]
	s_waitcnt lgkmcnt(11)
	v_mfma_f32_16x16x32_bf16 v[96:99], v[210:213], v[156:159], v[96:99]
	s_waitcnt lgkmcnt(10)
	v_mfma_f32_16x16x32_bf16 v[80:83], v[214:217], v[156:159], v[80:83]
	ds_read_b128 v[156:159], v155 offset:22528
	global_load_dwordx4 v[4:7], v[4:5], off
	s_nop 0
	global_load_dwordx4 v[52:55], v[10:11], off
	s_waitcnt lgkmcnt(10)
	v_mfma_f32_16x16x32_bf16 v[120:123], v[202:205], v[160:163], v[120:123]
	v_mfma_f32_16x16x32_bf16 v[104:107], v[206:209], v[160:163], v[104:107]
	v_mfma_f32_16x16x32_bf16 v[88:91], v[210:213], v[160:163], v[88:91]
	v_mfma_f32_16x16x32_bf16 v[72:75], v[214:217], v[160:163], v[72:75]
	global_load_dwordx4 v[8:11], v[8:9], off
	s_nop 0
	global_load_dwordx4 v[16:19], v[16:17], off
	s_waitcnt lgkmcnt(9)
	v_mfma_f32_16x16x32_bf16 v[116:119], v[202:205], v[164:167], v[116:119]
	v_mfma_f32_16x16x32_bf16 v[100:103], v[206:209], v[164:167], v[100:103]
	v_mfma_f32_16x16x32_bf16 v[84:87], v[210:213], v[164:167], v[84:87]
	v_mfma_f32_16x16x32_bf16 v[68:71], v[214:217], v[164:167], v[68:71]
	global_load_dwordx4 v[32:35], v[32:33], off
	s_nop 0
	global_load_dwordx4 v[48:51], v[48:49], off
	s_waitcnt lgkmcnt(8)
	v_mfma_f32_16x16x32_bf16 v[108:111], v[202:205], v[198:201], v[108:111]
	v_mfma_f32_16x16x32_bf16 v[92:95], v[206:209], v[198:201], v[92:95]
	v_mfma_f32_16x16x32_bf16 v[76:79], v[210:213], v[198:201], v[76:79]
	v_mfma_f32_16x16x32_bf16 v[64:67], v[214:217], v[198:201], v[64:67]
	s_waitcnt lgkmcnt(3)
	s_waitcnt vmcnt(14)
	ds_write_b128 v150, v[28:31] offset:49152
	ds_write_b128 v150, v[36:39] offset:53248
	v_mfma_f32_16x16x32_bf16 v[124:127], v[234:237], v[218:221], v[124:127]
	v_mfma_f32_16x16x32_bf16 v[120:123], v[234:237], v[222:225], v[120:123]
	v_mfma_f32_16x16x32_bf16 v[116:119], v[234:237], v[226:229], v[116:119]
	v_mfma_f32_16x16x32_bf16 v[108:111], v[234:237], v[230:233], v[108:111]
	s_waitcnt lgkmcnt(4)
	s_waitcnt vmcnt(11)
	ds_write_b128 v150, v[44:47] offset:57344
	ds_write_b128 v150, v[12:15] offset:32768
	v_mfma_f32_16x16x32_bf16 v[112:115], v[238:241], v[218:221], v[112:115]
	v_mfma_f32_16x16x32_bf16 v[104:107], v[238:241], v[222:225], v[104:107]
	v_mfma_f32_16x16x32_bf16 v[100:103], v[238:241], v[226:229], v[100:103]
	v_mfma_f32_16x16x32_bf16 v[92:95], v[238:241], v[230:233], v[92:95]
	s_waitcnt lgkmcnt(5)
	s_waitcnt vmcnt(9)
	ds_write_b128 v150, v[24:27] offset:36864
	ds_write_b128 v150, v[40:43] offset:40960
	v_mfma_f32_16x16x32_bf16 v[96:99], v[242:245], v[218:221], v[96:99]
	v_mfma_f32_16x16x32_bf16 v[88:91], v[242:245], v[222:225], v[88:91]
	v_mfma_f32_16x16x32_bf16 v[84:87], v[242:245], v[226:229], v[84:87]
	v_mfma_f32_16x16x32_bf16 v[76:79], v[242:245], v[230:233], v[76:79]
	s_waitcnt lgkmcnt(6)
	s_waitcnt vmcnt(8)
	ds_write_b128 v150, v[56:59] offset:45056
	ds_write_b128 v150, v[60:63] offset:61440
	v_mfma_f32_16x16x32_bf16 v[80:83], v[156:159], v[218:221], v[80:83]
	v_mfma_f32_16x16x32_bf16 v[72:75], v[156:159], v[222:225], v[72:75]
	v_mfma_f32_16x16x32_bf16 v[68:71], v[156:159], v[226:229], v[68:71]
	v_mfma_f32_16x16x32_bf16 v[64:67], v[156:159], v[230:233], v[64:67]
	s_setprio 0
	s_waitcnt lgkmcnt(0)
	s_barrier
; #define GLOAD(ra, rb, koff)                                                        \
;   {                                                                                \
;     _Pragma("unroll") for (int j = 0; j < 4; j++) ra[j] = *(const u32x4*)(pa + j * sa32 + (koff));   \
;     _Pragma("unroll") for (int j = 0; j < NB_; j++) rb[j] = *(const u32x4*)(pbv[j] + (koff));         \
;   }
; template <int NT, bool PRE> ...
;     ...
;   if (!PRE) {
;     GLOAD(ra0, rb0, 0);
;     GLOAD(ra1, rb1, 64);
;   }
;   __syncthreads();
;   for (int k0 = 0; k0 < K; k0 += 128) {
;     LSTORE(ra0, rb0, 0);
;     __syncthreads();
;     GLOAD(ra0, rb0, min(k0 + 128, K - 128));
;     __builtin_amdgcn_sched_barrier(0);
;     COMPUTE(0);
;     LSTORE(ra1, rb1, 1);
;     __syncthreads();
;     GLOAD(ra1, rb1, min(k0 + 192, K - 64));
;     __builtin_amdgcn_sched_barrier(0);
;     COMPUTE(1);
;   }
	s_min_u32 s5, s4, 0x300
	s_lshl_b32 s54, s5, 1
	ds_read_b128 v[156:159], v152 offset:32768
	ds_read_b128 v[202:205], v153 offset:49152
	ds_read_b128 v[206:209], v153 offset:51200
	ds_read_b128 v[210:213], v153 offset:53248
	ds_read_b128 v[214:217], v153 offset:55296
	ds_read_b128 v[160:163], v152 offset:34816
	ds_read_b128 v[164:167], v152 offset:36864
	ds_read_b128 v[198:201], v152 offset:38912
	ds_read_b128 v[218:221], v154 offset:32768
	ds_read_b128 v[222:225], v154 offset:34816
	ds_read_b128 v[226:229], v154 offset:36864
	ds_read_b128 v[230:233], v154 offset:38912
	ds_read_b128 v[234:237], v155 offset:49152
	ds_read_b128 v[238:241], v155 offset:51200
	ds_read_b128 v[242:245], v155 offset:53248
	v_lshl_add_u64 v[12:13], v[142:143], 0, s[54:55]
	v_add_co_u32_e32 v42, vcc, s33, v12
	v_lshl_add_u64 v[14:15], v[134:135], 0, s[54:55]
	s_nop 0
	v_addc_co_u32_e32 v43, vcc, 0, v13, vcc
	v_add_co_u32_e32 v56, vcc, s56, v12
	v_lshl_add_u64 v[24:25], v[136:137], 0, s[54:55]
	s_nop 0
	v_addc_co_u32_e32 v57, vcc, 0, v13, vcc
	v_add_co_u32_e32 v58, vcc, s57, v12
	v_lshl_add_u64 v[26:27], v[138:139], 0, s[54:55]
	v_lshl_add_u64 v[40:41], v[140:141], 0, s[54:55]
	v_addc_co_u32_e32 v59, vcc, 0, v13, vcc
	s_setprio 1
	global_load_dwordx4 v[28:31], v[14:15], off offset:384
	s_nop 0
	global_load_dwordx4 v[36:39], v[24:25], off offset:384
	s_waitcnt lgkmcnt(13)
	v_mfma_f32_16x16x32_bf16 v[124:127], v[202:205], v[156:159], v[124:127]
	s_waitcnt lgkmcnt(12)
	v_mfma_f32_16x16x32_bf16 v[112:115], v[206:209], v[156:159], v[112:115]
	s_waitcnt lgkmcnt(11)
	v_mfma_f32_16x16x32_bf16 v[96:99], v[210:213], v[156:159], v[96:99]
	s_waitcnt lgkmcnt(10)
	v_mfma_f32_16x16x32_bf16 v[80:83], v[214:217], v[156:159], v[80:83]
	ds_read_b128 v[156:159], v155 offset:55296
	global_load_dwordx4 v[44:47], v[26:27], off offset:384
	s_nop 0
	global_load_dwordx4 v[60:63], v[40:41], off offset:384
	s_waitcnt lgkmcnt(10)
	v_mfma_f32_16x16x32_bf16 v[120:123], v[202:205], v[160:163], v[120:123]
	v_mfma_f32_16x16x32_bf16 v[104:107], v[206:209], v[160:163], v[104:107]
	v_mfma_f32_16x16x32_bf16 v[88:91], v[210:213], v[160:163], v[88:91]
	v_mfma_f32_16x16x32_bf16 v[72:75], v[214:217], v[160:163], v[72:75]
	global_load_dwordx4 v[12:15], v[12:13], off offset:384
	s_nop 0
	global_load_dwordx4 v[24:27], v[42:43], off offset:384
	s_waitcnt lgkmcnt(9)
	v_mfma_f32_16x16x32_bf16 v[116:119], v[202:205], v[164:167], v[116:119]
	v_mfma_f32_16x16x32_bf16 v[100:103], v[206:209], v[164:167], v[100:103]
	v_mfma_f32_16x16x32_bf16 v[84:87], v[210:213], v[164:167], v[84:87]
	v_mfma_f32_16x16x32_bf16 v[68:71], v[214:217], v[164:167], v[68:71]
	global_load_dwordx4 v[40:43], v[56:57], off offset:384
	s_nop 0
	global_load_dwordx4 v[56:59], v[58:59], off offset:384
	s_waitcnt lgkmcnt(8)
	v_mfma_f32_16x16x32_bf16 v[108:111], v[202:205], v[198:201], v[108:111]
	v_mfma_f32_16x16x32_bf16 v[92:95], v[206:209], v[198:201], v[92:95]
	v_mfma_f32_16x16x32_bf16 v[76:79], v[210:213], v[198:201], v[76:79]
	v_mfma_f32_16x16x32_bf16 v[64:67], v[214:217], v[198:201], v[64:67]
	s_waitcnt lgkmcnt(3)
	s_waitcnt vmcnt(14)
	ds_write_b128 v150, v[20:23] offset:16384
	ds_write_b128 v150, v[0:3] offset:20480
	v_mfma_f32_16x16x32_bf16 v[124:127], v[234:237], v[218:221], v[124:127]
	v_mfma_f32_16x16x32_bf16 v[120:123], v[234:237], v[222:225], v[120:123]
	v_mfma_f32_16x16x32_bf16 v[116:119], v[234:237], v[226:229], v[116:119]
	v_mfma_f32_16x16x32_bf16 v[108:111], v[234:237], v[230:233], v[108:111]
	s_waitcnt lgkmcnt(4)
	s_waitcnt vmcnt(12)
	ds_write_b128 v150, v[4:7] offset:24576
	ds_write_b128 v150, v[52:55] offset:28672
	v_mfma_f32_16x16x32_bf16 v[112:115], v[238:241], v[218:221], v[112:115]
	v_mfma_f32_16x16x32_bf16 v[104:107], v[238:241], v[222:225], v[104:107]
	v_mfma_f32_16x16x32_bf16 v[100:103], v[238:241], v[226:229], v[100:103]
	v_mfma_f32_16x16x32_bf16 v[92:95], v[238:241], v[230:233], v[92:95]
	s_waitcnt lgkmcnt(5)
	s_waitcnt vmcnt(10)
	ds_write_b128 v150, v[8:11]
	ds_write_b128 v150, v[16:19] offset:4096
	v_mfma_f32_16x16x32_bf16 v[96:99], v[242:245], v[218:221], v[96:99]
	v_mfma_f32_16x16x32_bf16 v[88:91], v[242:245], v[222:225], v[88:91]
	v_mfma_f32_16x16x32_bf16 v[84:87], v[242:245], v[226:229], v[84:87]
	v_mfma_f32_16x16x32_bf16 v[76:79], v[242:245], v[230:233], v[76:79]
	s_waitcnt lgkmcnt(6)
	s_waitcnt vmcnt(8)
	ds_write_b128 v150, v[32:35] offset:8192
	ds_write_b128 v150, v[48:51] offset:12288
	v_mfma_f32_16x16x32_bf16 v[80:83], v[156:159], v[218:221], v[80:83]
	v_mfma_f32_16x16x32_bf16 v[72:75], v[156:159], v[222:225], v[72:75]
	v_mfma_f32_16x16x32_bf16 v[68:71], v[156:159], v[226:229], v[68:71]
	v_mfma_f32_16x16x32_bf16 v[64:67], v[156:159], v[230:233], v[64:67]
	s_setprio 0
	s_waitcnt lgkmcnt(0)
	s_barrier
	s_cmpk_lt_u32 s4, 0x300
	s_cbranch_scc1 .LBB0_2230
; #define GLOAD(ra, rb, koff)                                                        \
;   {                                                                                \
;     _Pragma("unroll") for (int j = 0; j < 4; j++) ra[j] = *(const u32x4*)(pa + j * sa32 + (koff));   \
;     _Pragma("unroll") for (int j = 0; j < NB_; j++) rb[j] = *(const u32x4*)(pbv[j] + (koff));         \
;   }
; template <int NT, bool PRE> ...
;     ...
;   if (!PRE) {
;     GLOAD(ra0, rb0, 0);
;     GLOAD(ra1, rb1, 64);
;   }
;   __syncthreads();
;   for (int k0 = 0; k0 < K; k0 += 128) {
;     LSTORE(ra0, rb0, 0);
;     __syncthreads();
;     GLOAD(ra0, rb0, min(k0 + 128, K - 128));
;     __builtin_amdgcn_sched_barrier(0);
;     COMPUTE(0);
;     LSTORE(ra1, rb1, 1);
;     __syncthreads();
;     GLOAD(ra1, rb1, min(k0 + 192, K - 64));
;     __builtin_amdgcn_sched_barrier(0);
;     COMPUTE(1);
;   }
	ds_read_b128 v[156:159], v152
	ds_read_b128 v[202:205], v153 offset:16384
	ds_read_b128 v[206:209], v153 offset:18432
	ds_read_b128 v[210:213], v153 offset:20480
	ds_read_b128 v[214:217], v153 offset:22528
	ds_read_b128 v[160:163], v152 offset:2048
	ds_read_b128 v[164:167], v152 offset:4096
	ds_read_b128 v[198:201], v152 offset:6144
	ds_read_b128 v[218:221], v154
	ds_read_b128 v[222:225], v154 offset:2048
	ds_read_b128 v[226:229], v154 offset:4096
	ds_read_b128 v[230:233], v154 offset:6144
	ds_read_b128 v[234:237], v155 offset:16384
	ds_read_b128 v[238:241], v155 offset:18432
	ds_read_b128 v[242:245], v155 offset:20480
	s_addk_i32 s4, 0x80
	s_setprio 1
	s_waitcnt lgkmcnt(13)
	v_mfma_f32_16x16x32_bf16 v[124:127], v[202:205], v[156:159], v[124:127]
	s_waitcnt lgkmcnt(12)
	v_mfma_f32_16x16x32_bf16 v[112:115], v[206:209], v[156:159], v[112:115]
	s_waitcnt lgkmcnt(11)
	v_mfma_f32_16x16x32_bf16 v[96:99], v[210:213], v[156:159], v[96:99]
	s_waitcnt lgkmcnt(10)
	v_mfma_f32_16x16x32_bf16 v[80:83], v[214:217], v[156:159], v[80:83]
	ds_read_b128 v[156:159], v155 offset:22528
	s_waitcnt lgkmcnt(10)
	v_mfma_f32_16x16x32_bf16 v[120:123], v[202:205], v[160:163], v[120:123]
	v_mfma_f32_16x16x32_bf16 v[104:107], v[206:209], v[160:163], v[104:107]
	v_mfma_f32_16x16x32_bf16 v[88:91], v[210:213], v[160:163], v[88:91]
	v_mfma_f32_16x16x32_bf16 v[72:75], v[214:217], v[160:163], v[72:75]
	s_waitcnt lgkmcnt(9)
	v_mfma_f32_16x16x32_bf16 v[116:119], v[202:205], v[164:167], v[116:119]
	v_mfma_f32_16x16x32_bf16 v[100:103], v[206:209], v[164:167], v[100:103]
	v_mfma_f32_16x16x32_bf16 v[84:87], v[210:213], v[164:167], v[84:87]
	v_mfma_f32_16x16x32_bf16 v[68:71], v[214:217], v[164:167], v[68:71]
	s_waitcnt lgkmcnt(8)
	v_mfma_f32_16x16x32_bf16 v[108:111], v[202:205], v[198:201], v[108:111]
	v_mfma_f32_16x16x32_bf16 v[92:95], v[206:209], v[198:201], v[92:95]
	v_mfma_f32_16x16x32_bf16 v[76:79], v[210:213], v[198:201], v[76:79]
	v_mfma_f32_16x16x32_bf16 v[64:67], v[214:217], v[198:201], v[64:67]
	s_waitcnt lgkmcnt(3)
	s_waitcnt vmcnt(6)
	ds_write_b128 v150, v[28:31] offset:49152
	ds_write_b128 v150, v[36:39] offset:53248
	v_mfma_f32_16x16x32_bf16 v[124:127], v[234:237], v[218:221], v[124:127]
	v_mfma_f32_16x16x32_bf16 v[120:123], v[234:237], v[222:225], v[120:123]
	v_mfma_f32_16x16x32_bf16 v[116:119], v[234:237], v[226:229], v[116:119]
	v_mfma_f32_16x16x32_bf16 v[108:111], v[234:237], v[230:233], v[108:111]
	s_waitcnt lgkmcnt(4)
	s_waitcnt vmcnt(3)
	ds_write_b128 v150, v[44:47] offset:57344
	ds_write_b128 v150, v[12:15] offset:32768
	v_mfma_f32_16x16x32_bf16 v[112:115], v[238:241], v[218:221], v[112:115]
	v_mfma_f32_16x16x32_bf16 v[104:107], v[238:241], v[222:225], v[104:107]
	v_mfma_f32_16x16x32_bf16 v[100:103], v[238:241], v[226:229], v[100:103]
	v_mfma_f32_16x16x32_bf16 v[92:95], v[238:241], v[230:233], v[92:95]
	s_waitcnt lgkmcnt(5)
	s_waitcnt vmcnt(1)
	ds_write_b128 v150, v[24:27] offset:36864
	ds_write_b128 v150, v[40:43] offset:40960
	v_mfma_f32_16x16x32_bf16 v[96:99], v[242:245], v[218:221], v[96:99]
	v_mfma_f32_16x16x32_bf16 v[88:91], v[242:245], v[222:225], v[88:91]
	v_mfma_f32_16x16x32_bf16 v[84:87], v[242:245], v[226:229], v[84:87]
	v_mfma_f32_16x16x32_bf16 v[76:79], v[242:245], v[230:233], v[76:79]
	s_waitcnt lgkmcnt(6)
	s_waitcnt vmcnt(0)
	ds_write_b128 v150, v[56:59] offset:45056
	ds_write_b128 v150, v[60:63] offset:61440
	v_mfma_f32_16x16x32_bf16 v[80:83], v[156:159], v[218:221], v[80:83]
	v_mfma_f32_16x16x32_bf16 v[72:75], v[156:159], v[222:225], v[72:75]
	v_mfma_f32_16x16x32_bf16 v[68:71], v[156:159], v[226:229], v[68:71]
	v_mfma_f32_16x16x32_bf16 v[64:67], v[156:159], v[230:233], v[64:67]
	s_setprio 0
	s_waitcnt lgkmcnt(0)
	s_barrier
; #define GLOAD(ra, rb, koff)                                                        \
;   {                                                                                \
;     _Pragma("unroll") for (int j = 0; j < 4; j++) ra[j] = *(const u32x4*)(pa + j * sa32 + (koff));   \
;     _Pragma("unroll") for (int j = 0; j < NB_; j++) rb[j] = *(const u32x4*)(pbv[j] + (koff));         \
;   }
; template <int NT, bool PRE> ...
;     ...
;   if (!PRE) {
;     GLOAD(ra0, rb0, 0);
;     GLOAD(ra1, rb1, 64);
;   }
;   __syncthreads();
;   for (int k0 = 0; k0 < K; k0 += 128) {
;     LSTORE(ra0, rb0, 0);
;     __syncthreads();
;     GLOAD(ra0, rb0, min(k0 + 128, K - 128));
;     __builtin_amdgcn_sched_barrier(0);
;     COMPUTE(0);
;     LSTORE(ra1, rb1, 1);
;     __syncthreads();
;     GLOAD(ra1, rb1, min(k0 + 192, K - 64));
;     __builtin_amdgcn_sched_barrier(0);
;     COMPUTE(1);
;   }
; template <int EPI>
; __device__ __forceinline__ void phase_gemm(const Params& P, const u16* A, int lda, const u16* Bt, int K, int N, u16* sA, u16* sB) {
;     ...
;     for (; t < Tfull; t += G) {
;       const int m0 = (t % 132) * 128, n0 = (t / 132) * 128;
;       f32x4 acc[4][4];
;       zero_acc<4>(acc);
;       gemm_core_r<4, true>(pa, (size_t)32 * lda, pbv, K, acc, sA, sB, tq, ra0, rb0, ra1, rb1);
;       if (t + G < Tfull) {
;         PG_PTRS(t + G);
;         gemm_preload<4>(pa, (size_t)32 * lda, pbv, ra0, rb0, ra1, rb1);
	ds_read_b128 v[156:159], v152 offset:32768
	ds_read_b128 v[202:205], v153 offset:49152
	ds_read_b128 v[206:209], v153 offset:51200
	ds_read_b128 v[210:213], v153 offset:53248
	ds_read_b128 v[214:217], v153 offset:55296
	ds_read_b128 v[160:163], v152 offset:34816
	ds_read_b128 v[164:167], v152 offset:36864
	ds_read_b128 v[198:201], v152 offset:38912
	ds_read_b128 v[218:221], v154 offset:32768
	ds_read_b128 v[222:225], v154 offset:34816
	ds_read_b128 v[226:229], v154 offset:36864
	ds_read_b128 v[230:233], v154 offset:38912
	ds_read_b128 v[234:237], v155 offset:49152
	ds_read_b128 v[238:241], v155 offset:51200
	ds_read_b128 v[242:245], v155 offset:53248
	s_setprio 1
	s_waitcnt lgkmcnt(13)
	v_mfma_f32_16x16x32_bf16 v[124:127], v[202:205], v[156:159], v[124:127]
	s_waitcnt lgkmcnt(12)
	v_mfma_f32_16x16x32_bf16 v[112:115], v[206:209], v[156:159], v[112:115]
	s_waitcnt lgkmcnt(11)
	v_mfma_f32_16x16x32_bf16 v[96:99], v[210:213], v[156:159], v[96:99]
	s_waitcnt lgkmcnt(10)
	v_mfma_f32_16x16x32_bf16 v[80:83], v[214:217], v[156:159], v[80:83]
	ds_read_b128 v[156:159], v155 offset:55296
	s_waitcnt lgkmcnt(10)
	v_mfma_f32_16x16x32_bf16 v[120:123], v[202:205], v[160:163], v[120:123]
	v_mfma_f32_16x16x32_bf16 v[104:107], v[206:209], v[160:163], v[104:107]
	v_mfma_f32_16x16x32_bf16 v[88:91], v[210:213], v[160:163], v[88:91]
	v_mfma_f32_16x16x32_bf16 v[72:75], v[214:217], v[160:163], v[72:75]
	s_waitcnt lgkmcnt(9)
	v_mfma_f32_16x16x32_bf16 v[116:119], v[202:205], v[164:167], v[116:119]
	v_mfma_f32_16x16x32_bf16 v[100:103], v[206:209], v[164:167], v[100:103]
	v_mfma_f32_16x16x32_bf16 v[84:87], v[210:213], v[164:167], v[84:87]
	v_mfma_f32_16x16x32_bf16 v[68:71], v[214:217], v[164:167], v[68:71]
	s_waitcnt lgkmcnt(8)
	v_mfma_f32_16x16x32_bf16 v[108:111], v[202:205], v[198:201], v[108:111]
	v_mfma_f32_16x16x32_bf16 v[92:95], v[206:209], v[198:201], v[92:95]
	v_mfma_f32_16x16x32_bf16 v[76:79], v[210:213], v[198:201], v[76:79]
	v_mfma_f32_16x16x32_bf16 v[64:67], v[214:217], v[198:201], v[64:67]
	s_waitcnt lgkmcnt(3)
	v_mfma_f32_16x16x32_bf16 v[124:127], v[234:237], v[218:221], v[124:127]
	v_mfma_f32_16x16x32_bf16 v[120:123], v[234:237], v[222:225], v[120:123]
	v_mfma_f32_16x16x32_bf16 v[116:119], v[234:237], v[226:229], v[116:119]
	v_mfma_f32_16x16x32_bf16 v[108:111], v[234:237], v[230:233], v[108:111]
	s_waitcnt lgkmcnt(2)
	v_mfma_f32_16x16x32_bf16 v[112:115], v[238:241], v[218:221], v[112:115]
	v_mfma_f32_16x16x32_bf16 v[104:107], v[238:241], v[222:225], v[104:107]
	v_mfma_f32_16x16x32_bf16 v[100:103], v[238:241], v[226:229], v[100:103]
	v_mfma_f32_16x16x32_bf16 v[92:95], v[238:241], v[230:233], v[92:95]
	s_waitcnt lgkmcnt(1)
	v_mfma_f32_16x16x32_bf16 v[96:99], v[242:245], v[218:221], v[96:99]
	v_mfma_f32_16x16x32_bf16 v[88:91], v[242:245], v[222:225], v[88:91]
	v_mfma_f32_16x16x32_bf16 v[84:87], v[242:245], v[226:229], v[84:87]
	v_mfma_f32_16x16x32_bf16 v[76:79], v[242:245], v[230:233], v[76:79]
	s_waitcnt lgkmcnt(0)
	v_mfma_f32_16x16x32_bf16 v[80:83], v[156:159], v[218:221], v[80:83]
	v_mfma_f32_16x16x32_bf16 v[72:75], v[156:159], v[222:225], v[72:75]
	v_mfma_f32_16x16x32_bf16 v[68:71], v[156:159], v[226:229], v[68:71]
	v_mfma_f32_16x16x32_bf16 v[64:67], v[156:159], v[230:233], v[64:67]
	s_setprio 0
	s_waitcnt lgkmcnt(0)
	s_add_i32 s7, s6, s90
	s_cmp_ge_i32 s7, s19
	s_cselect_b64 s[4:5], -1, 0
	s_and_b64 vcc, exec, s[4:5]
	s_cbranch_vccnz .LBB0_2228
	s_cmp_lg_u32 s90, 0x200
	s_cbranch_scc1 .Lrm_w1p_orig
	s_and_b32 s54, s7, 7
	s_lshl_b32 s54, s54, 6
	s_bfe_u32 s8, s7, 0x60003
	s_or_b32 s54, s54, s8
	s_andn2_b32 s8, s7, 0x1ff
	s_or_b32 s54, s54, s8
	s_cmp_lt_u32 s54, 3168
	s_cbranch_scc0 .Lrm_w1p_b
	s_lshr_b32 s8, s54, 3
	s_mul_hi_u32 s8, s8, 0x3e0f83e1
	s_lshr_b32 s8, s8, 5
	s_mul_i32 s9, s8, 1056
	s_sub_i32 s54, s54, s9
	s_lshl_b32 s8, s8, 3
	s_and_b32 s9, s54, 7
	s_add_i32 s8, s8, s9
	s_lshr_b32 s9, s54, 3
	s_branch .Lrm_w1p_done

; #define GLOAD(ra, rb, koff)                                                        \
;   {                                                                                \
;     _Pragma("unroll") for (int j = 0; j < 4; j++) ra[j] = *(const u32x4*)(pa + j * sa32 + (koff));   \
;     _Pragma("unroll") for (int j = 0; j < NB_; j++) rb[j] = *(const u32x4*)(pbv[j] + (koff));         \
;   }
; template <int NT, bool PRE> ...
;     ...
;   if (!PRE) {
;     GLOAD(ra0, rb0, 0);
;     GLOAD(ra1, rb1, 64);
;   }
;   __syncthreads();
;   for (int k0 = 0; k0 < K; k0 += 128) {
;     LSTORE(ra0, rb0, 0);
;     __syncthreads();
;     GLOAD(ra0, rb0, min(k0 + 128, K - 128));
;     __builtin_amdgcn_sched_barrier(0);
;     COMPUTE(0);
;     LSTORE(ra1, rb1, 1);
;     __syncthreads();
;     GLOAD(ra1, rb1, min(k0 + 192, K - 64));
;     __builtin_amdgcn_sched_barrier(0);
;     COMPUTE(1);
;   }
.LBB0_2289:
	s_add_i32 s5, s4, 0x100
	s_min_u32 s5, s5, 0xf80
	s_lshl_b32 s54, s5, 1
	ds_read_b128 v[156:159], v152
	ds_read_b128 v[202:205], v153 offset:16384
	ds_read_b128 v[206:209], v153 offset:18432
	ds_read_b128 v[210:213], v153 offset:20480
	ds_read_b128 v[214:217], v153 offset:22528
	ds_read_b128 v[160:163], v152 offset:2048
	ds_read_b128 v[164:167], v152 offset:4096
	ds_read_b128 v[198:201], v152 offset:6144
	ds_read_b128 v[218:221], v154
	ds_read_b128 v[222:225], v154 offset:2048
	ds_read_b128 v[226:229], v154 offset:4096
	ds_read_b128 v[230:233], v154 offset:6144
	ds_read_b128 v[234:237], v155 offset:16384
	ds_read_b128 v[238:241], v155 offset:18432
	ds_read_b128 v[242:245], v155 offset:20480
	v_lshl_add_u64 v[8:9], v[142:143], 0, s[54:55]
	v_add_co_u32_e32 v16, vcc, s19, v8
	v_lshl_add_u64 v[0:1], v[134:135], 0, s[54:55]
	s_nop 0
	v_addc_co_u32_e32 v17, vcc, 0, v9, vcc
	v_add_co_u32_e32 v32, vcc, s20, v8
	v_lshl_add_u64 v[2:3], v[136:137], 0, s[54:55]
	s_nop 0
	v_addc_co_u32_e32 v33, vcc, 0, v9, vcc
	v_add_co_u32_e32 v48, vcc, s21, v8
	v_lshl_add_u64 v[4:5], v[138:139], 0, s[54:55]
	v_lshl_add_u64 v[10:11], v[140:141], 0, s[54:55]
	v_addc_co_u32_e32 v49, vcc, 0, v9, vcc
	s_addk_i32 s4, 0x80
	s_setprio 1
	global_load_dwordx4 v[20:23], v[0:1], off
	s_nop 0
	global_load_dwordx4 v[0:3], v[2:3], off
	s_waitcnt lgkmcnt(13)
	v_mfma_f32_16x16x32_bf16 v[124:127], v[202:205], v[156:159], v[124:127]
	s_waitcnt lgkmcnt(12)
	v_mfma_f32_16x16x32_bf16 v[116:119], v[206:209], v[156:159], v[116:119]
	s_waitcnt lgkmcnt(11)
	v_mfma_f32_16x16x32_bf16 v[112:115], v[210:213], v[156:159], v[112:115]
	s_waitcnt lgkmcnt(10)
	v_mfma_f32_16x16x32_bf16 v[108:111], v[214:217], v[156:159], v[108:111]
	ds_read_b128 v[156:159], v155 offset:22528
	global_load_dwordx4 v[4:7], v[4:5], off
	s_nop 0
	global_load_dwordx4 v[52:55], v[10:11], off
	s_waitcnt lgkmcnt(10)
	v_mfma_f32_16x16x32_bf16 v[120:123], v[202:205], v[160:163], v[120:123]
	v_mfma_f32_16x16x32_bf16 v[104:107], v[206:209], v[160:163], v[104:107]
	v_mfma_f32_16x16x32_bf16 v[96:99], v[210:213], v[160:163], v[96:99]
	v_mfma_f32_16x16x32_bf16 v[92:95], v[214:217], v[160:163], v[92:95]
	global_load_dwordx4 v[8:11], v[8:9], off
	s_nop 0
	global_load_dwordx4 v[16:19], v[16:17], off
	s_waitcnt lgkmcnt(9)
	v_mfma_f32_16x16x32_bf16 v[100:103], v[202:205], v[164:167], v[100:103]
	v_mfma_f32_16x16x32_bf16 v[88:91], v[206:209], v[164:167], v[88:91]
	v_mfma_f32_16x16x32_bf16 v[84:87], v[210:213], v[164:167], v[84:87]
	v_mfma_f32_16x16x32_bf16 v[76:79], v[214:217], v[164:167], v[76:79]
	global_load_dwordx4 v[32:35], v[32:33], off
	s_nop 0
	global_load_dwordx4 v[48:51], v[48:49], off
	s_waitcnt lgkmcnt(8)
	v_mfma_f32_16x16x32_bf16 v[80:83], v[202:205], v[198:201], v[80:83]
	v_mfma_f32_16x16x32_bf16 v[72:75], v[206:209], v[198:201], v[72:75]
	v_mfma_f32_16x16x32_bf16 v[68:71], v[210:213], v[198:201], v[68:71]
	v_mfma_f32_16x16x32_bf16 v[64:67], v[214:217], v[198:201], v[64:67]
	s_waitcnt lgkmcnt(3)
	s_waitcnt vmcnt(14)
	ds_write_b128 v150, v[28:31] offset:49152
	ds_write_b128 v150, v[36:39] offset:53248
	v_mfma_f32_16x16x32_bf16 v[124:127], v[234:237], v[218:221], v[124:127]
	v_mfma_f32_16x16x32_bf16 v[120:123], v[234:237], v[222:225], v[120:123]
	v_mfma_f32_16x16x32_bf16 v[100:103], v[234:237], v[226:229], v[100:103]
	v_mfma_f32_16x16x32_bf16 v[80:83], v[234:237], v[230:233], v[80:83]
	s_waitcnt lgkmcnt(4)
	s_waitcnt vmcnt(11)
	ds_write_b128 v150, v[44:47] offset:57344
	ds_write_b128 v150, v[12:15] offset:32768
	v_mfma_f32_16x16x32_bf16 v[116:119], v[238:241], v[218:221], v[116:119]
	v_mfma_f32_16x16x32_bf16 v[104:107], v[238:241], v[222:225], v[104:107]
	v_mfma_f32_16x16x32_bf16 v[88:91], v[238:241], v[226:229], v[88:91]
	v_mfma_f32_16x16x32_bf16 v[72:75], v[238:241], v[230:233], v[72:75]
	s_waitcnt lgkmcnt(5)
	s_waitcnt vmcnt(9)
	ds_write_b128 v150, v[24:27] offset:36864
	ds_write_b128 v150, v[40:43] offset:40960
	v_mfma_f32_16x16x32_bf16 v[112:115], v[242:245], v[218:221], v[112:115]
	v_mfma_f32_16x16x32_bf16 v[96:99], v[242:245], v[222:225], v[96:99]
	v_mfma_f32_16x16x32_bf16 v[84:87], v[242:245], v[226:229], v[84:87]
	v_mfma_f32_16x16x32_bf16 v[68:71], v[242:245], v[230:233], v[68:71]
	s_waitcnt lgkmcnt(6)
	s_waitcnt vmcnt(8)
	ds_write_b128 v150, v[56:59] offset:45056
	ds_write_b128 v150, v[60:63] offset:61440
	v_mfma_f32_16x16x32_bf16 v[108:111], v[156:159], v[218:221], v[108:111]
	v_mfma_f32_16x16x32_bf16 v[92:95], v[156:159], v[222:225], v[92:95]
	v_mfma_f32_16x16x32_bf16 v[76:79], v[156:159], v[226:229], v[76:79]
	v_mfma_f32_16x16x32_bf16 v[64:67], v[156:159], v[230:233], v[64:67]
	s_setprio 0
	s_waitcnt lgkmcnt(0)
	s_barrier
; #define GLOAD(ra, rb, koff)                                                        \
;   {                                                                                \
;     _Pragma("unroll") for (int j = 0; j < 4; j++) ra[j] = *(const u32x4*)(pa + j * sa32 + (koff));   \
;     _Pragma("unroll") for (int j = 0; j < NB_; j++) rb[j] = *(const u32x4*)(pbv[j] + (koff));         \
;   }
; template <int NT, bool PRE> ...
;     ...
;   if (!PRE) {
;     GLOAD(ra0, rb0, 0);
;     GLOAD(ra1, rb1, 64);
;   }
;   __syncthreads();
;   for (int k0 = 0; k0 < K; k0 += 128) {
;     LSTORE(ra0, rb0, 0);
;     __syncthreads();
;     GLOAD(ra0, rb0, min(k0 + 128, K - 128));
;     __builtin_amdgcn_sched_barrier(0);
;     COMPUTE(0);
;     LSTORE(ra1, rb1, 1);
;     __syncthreads();
;     GLOAD(ra1, rb1, min(k0 + 192, K - 64));
;     __builtin_amdgcn_sched_barrier(0);
;     COMPUTE(1);
;   }
	s_min_u32 s5, s4, 0xf00
	s_lshl_b32 s54, s5, 1
	ds_read_b128 v[156:159], v152 offset:32768
	ds_read_b128 v[202:205], v153 offset:49152
	ds_read_b128 v[206:209], v153 offset:51200
	ds_read_b128 v[210:213], v153 offset:53248
	ds_read_b128 v[214:217], v153 offset:55296
	ds_read_b128 v[160:163], v152 offset:34816
	ds_read_b128 v[164:167], v152 offset:36864
	ds_read_b128 v[198:201], v152 offset:38912
	ds_read_b128 v[218:221], v154 offset:32768
	ds_read_b128 v[222:225], v154 offset:34816
	ds_read_b128 v[226:229], v154 offset:36864
	ds_read_b128 v[230:233], v154 offset:38912
	ds_read_b128 v[234:237], v155 offset:49152
	ds_read_b128 v[238:241], v155 offset:51200
	ds_read_b128 v[242:245], v155 offset:53248
	v_lshl_add_u64 v[12:13], v[142:143], 0, s[54:55]
	v_add_co_u32_e32 v42, vcc, s19, v12
	v_lshl_add_u64 v[14:15], v[134:135], 0, s[54:55]
	s_nop 0
	v_addc_co_u32_e32 v43, vcc, 0, v13, vcc
	v_add_co_u32_e32 v56, vcc, s20, v12
	v_lshl_add_u64 v[24:25], v[136:137], 0, s[54:55]
	s_nop 0
	v_addc_co_u32_e32 v57, vcc, 0, v13, vcc
	v_add_co_u32_e32 v58, vcc, s21, v12
	v_lshl_add_u64 v[26:27], v[138:139], 0, s[54:55]
	v_lshl_add_u64 v[40:41], v[140:141], 0, s[54:55]
	v_addc_co_u32_e32 v59, vcc, 0, v13, vcc
	s_setprio 1
	global_load_dwordx4 v[28:31], v[14:15], off offset:384
	s_nop 0
	global_load_dwordx4 v[36:39], v[24:25], off offset:384
	s_waitcnt lgkmcnt(13)
	v_mfma_f32_16x16x32_bf16 v[124:127], v[202:205], v[156:159], v[124:127]
	s_waitcnt lgkmcnt(12)
	v_mfma_f32_16x16x32_bf16 v[116:119], v[206:209], v[156:159], v[116:119]
	s_waitcnt lgkmcnt(11)
	v_mfma_f32_16x16x32_bf16 v[112:115], v[210:213], v[156:159], v[112:115]
	s_waitcnt lgkmcnt(10)
	v_mfma_f32_16x16x32_bf16 v[108:111], v[214:217], v[156:159], v[108:111]
	ds_read_b128 v[156:159], v155 offset:55296
	global_load_dwordx4 v[44:47], v[26:27], off offset:384
	s_nop 0
	global_load_dwordx4 v[60:63], v[40:41], off offset:384
	s_waitcnt lgkmcnt(10)
	v_mfma_f32_16x16x32_bf16 v[120:123], v[202:205], v[160:163], v[120:123]
	v_mfma_f32_16x16x32_bf16 v[104:107], v[206:209], v[160:163], v[104:107]
	v_mfma_f32_16x16x32_bf16 v[96:99], v[210:213], v[160:163], v[96:99]
	v_mfma_f32_16x16x32_bf16 v[92:95], v[214:217], v[160:163], v[92:95]
	global_load_dwordx4 v[12:15], v[12:13], off offset:384
	s_nop 0
	global_load_dwordx4 v[24:27], v[42:43], off offset:384
	s_waitcnt lgkmcnt(9)
	v_mfma_f32_16x16x32_bf16 v[100:103], v[202:205], v[164:167], v[100:103]
	v_mfma_f32_16x16x32_bf16 v[88:91], v[206:209], v[164:167], v[88:91]
	v_mfma_f32_16x16x32_bf16 v[84:87], v[210:213], v[164:167], v[84:87]
	v_mfma_f32_16x16x32_bf16 v[76:79], v[214:217], v[164:167], v[76:79]
	global_load_dwordx4 v[40:43], v[56:57], off offset:384
	s_nop 0
	global_load_dwordx4 v[56:59], v[58:59], off offset:384
	s_waitcnt lgkmcnt(8)
	v_mfma_f32_16x16x32_bf16 v[80:83], v[202:205], v[198:201], v[80:83]
	v_mfma_f32_16x16x32_bf16 v[72:75], v[206:209], v[198:201], v[72:75]
	v_mfma_f32_16x16x32_bf16 v[68:71], v[210:213], v[198:201], v[68:71]
	v_mfma_f32_16x16x32_bf16 v[64:67], v[214:217], v[198:201], v[64:67]
	s_waitcnt lgkmcnt(3)
	s_waitcnt vmcnt(14)
	ds_write_b128 v150, v[20:23] offset:16384
	ds_write_b128 v150, v[0:3] offset:20480
	v_mfma_f32_16x16x32_bf16 v[124:127], v[234:237], v[218:221], v[124:127]
	v_mfma_f32_16x16x32_bf16 v[120:123], v[234:237], v[222:225], v[120:123]
	v_mfma_f32_16x16x32_bf16 v[100:103], v[234:237], v[226:229], v[100:103]
	v_mfma_f32_16x16x32_bf16 v[80:83], v[234:237], v[230:233], v[80:83]
	s_waitcnt lgkmcnt(4)
	s_waitcnt vmcnt(12)
	ds_write_b128 v150, v[4:7] offset:24576
	ds_write_b128 v150, v[52:55] offset:28672
	v_mfma_f32_16x16x32_bf16 v[116:119], v[238:241], v[218:221], v[116:119]
	v_mfma_f32_16x16x32_bf16 v[104:107], v[238:241], v[222:225], v[104:107]
	v_mfma_f32_16x16x32_bf16 v[88:91], v[238:241], v[226:229], v[88:91]
	v_mfma_f32_16x16x32_bf16 v[72:75], v[238:241], v[230:233], v[72:75]
	s_waitcnt lgkmcnt(5)
	s_waitcnt vmcnt(10)
	ds_write_b128 v150, v[8:11]
	ds_write_b128 v150, v[16:19] offset:4096
	v_mfma_f32_16x16x32_bf16 v[112:115], v[242:245], v[218:221], v[112:115]
	v_mfma_f32_16x16x32_bf16 v[96:99], v[242:245], v[222:225], v[96:99]
	v_mfma_f32_16x16x32_bf16 v[84:87], v[242:245], v[226:229], v[84:87]
	v_mfma_f32_16x16x32_bf16 v[68:71], v[242:245], v[230:233], v[68:71]
	s_waitcnt lgkmcnt(6)
	s_waitcnt vmcnt(8)
	ds_write_b128 v150, v[32:35] offset:8192
	ds_write_b128 v150, v[48:51] offset:12288
	v_mfma_f32_16x16x32_bf16 v[108:111], v[156:159], v[218:221], v[108:111]
	v_mfma_f32_16x16x32_bf16 v[92:95], v[156:159], v[222:225], v[92:95]
	v_mfma_f32_16x16x32_bf16 v[76:79], v[156:159], v[226:229], v[76:79]
	v_mfma_f32_16x16x32_bf16 v[64:67], v[156:159], v[230:233], v[64:67]
	s_setprio 0
	s_waitcnt lgkmcnt(0)
	s_barrier
	s_cmpk_lt_u32 s4, 0xf00
	s_cbranch_scc1 .LBB0_2289
; #define GLOAD(ra, rb, koff)                                                        \
;   {                                                                                \
;     _Pragma("unroll") for (int j = 0; j < 4; j++) ra[j] = *(const u32x4*)(pa + j * sa32 + (koff));   \
;     _Pragma("unroll") for (int j = 0; j < NB_; j++) rb[j] = *(const u32x4*)(pbv[j] + (koff));         \
;   }
; template <int NT, bool PRE> ...
;     ...
;   if (!PRE) {
;     GLOAD(ra0, rb0, 0);
;     GLOAD(ra1, rb1, 64);
;   }
;   __syncthreads();
;   for (int k0 = 0; k0 < K; k0 += 128) {
;     LSTORE(ra0, rb0, 0);
;     __syncthreads();
;     GLOAD(ra0, rb0, min(k0 + 128, K - 128));
;     __builtin_amdgcn_sched_barrier(0);
;     COMPUTE(0);
;     LSTORE(ra1, rb1, 1);
;     __syncthreads();
;     GLOAD(ra1, rb1, min(k0 + 192, K - 64));
;     __builtin_amdgcn_sched_barrier(0);
;     COMPUTE(1);
;   }
	ds_read_b128 v[156:159], v152
	ds_read_b128 v[202:205], v153 offset:16384
	ds_read_b128 v[206:209], v153 offset:18432
	ds_read_b128 v[210:213], v153 offset:20480
	ds_read_b128 v[214:217], v153 offset:22528
	ds_read_b128 v[160:163], v152 offset:2048
	ds_read_b128 v[164:167], v152 offset:4096
	ds_read_b128 v[198:201], v152 offset:6144
	ds_read_b128 v[218:221], v154
	ds_read_b128 v[222:225], v154 offset:2048
	ds_read_b128 v[226:229], v154 offset:4096
	ds_read_b128 v[230:233], v154 offset:6144
	ds_read_b128 v[234:237], v155 offset:16384
	ds_read_b128 v[238:241], v155 offset:18432
	ds_read_b128 v[242:245], v155 offset:20480
	s_addk_i32 s4, 0x80
	s_setprio 1
	s_waitcnt lgkmcnt(13)
	v_mfma_f32_16x16x32_bf16 v[124:127], v[202:205], v[156:159], v[124:127]
	s_waitcnt lgkmcnt(12)
	v_mfma_f32_16x16x32_bf16 v[116:119], v[206:209], v[156:159], v[116:119]
	s_waitcnt lgkmcnt(11)
	v_mfma_f32_16x16x32_bf16 v[112:115], v[210:213], v[156:159], v[112:115]
	s_waitcnt lgkmcnt(10)
	v_mfma_f32_16x16x32_bf16 v[108:111], v[214:217], v[156:159], v[108:111]
	ds_read_b128 v[156:159], v155 offset:22528
	s_waitcnt lgkmcnt(10)
	v_mfma_f32_16x16x32_bf16 v[120:123], v[202:205], v[160:163], v[120:123]
	v_mfma_f32_16x16x32_bf16 v[104:107], v[206:209], v[160:163], v[104:107]
	v_mfma_f32_16x16x32_bf16 v[96:99], v[210:213], v[160:163], v[96:99]
	v_mfma_f32_16x16x32_bf16 v[92:95], v[214:217], v[160:163], v[92:95]
	s_waitcnt lgkmcnt(9)
	v_mfma_f32_16x16x32_bf16 v[100:103], v[202:205], v[164:167], v[100:103]
	v_mfma_f32_16x16x32_bf16 v[88:91], v[206:209], v[164:167], v[88:91]
	v_mfma_f32_16x16x32_bf16 v[84:87], v[210:213], v[164:167], v[84:87]
	v_mfma_f32_16x16x32_bf16 v[76:79], v[214:217], v[164:167], v[76:79]
	s_waitcnt lgkmcnt(8)
	v_mfma_f32_16x16x32_bf16 v[80:83], v[202:205], v[198:201], v[80:83]
	v_mfma_f32_16x16x32_bf16 v[72:75], v[206:209], v[198:201], v[72:75]
	v_mfma_f32_16x16x32_bf16 v[68:71], v[210:213], v[198:201], v[68:71]
	v_mfma_f32_16x16x32_bf16 v[64:67], v[214:217], v[198:201], v[64:67]
	s_waitcnt lgkmcnt(3)
	s_waitcnt vmcnt(6)
	ds_write_b128 v150, v[28:31] offset:49152
	ds_write_b128 v150, v[36:39] offset:53248
	v_mfma_f32_16x16x32_bf16 v[124:127], v[234:237], v[218:221], v[124:127]
	v_mfma_f32_16x16x32_bf16 v[120:123], v[234:237], v[222:225], v[120:123]
	v_mfma_f32_16x16x32_bf16 v[100:103], v[234:237], v[226:229], v[100:103]
	v_mfma_f32_16x16x32_bf16 v[80:83], v[234:237], v[230:233], v[80:83]
	s_waitcnt lgkmcnt(4)
	s_waitcnt vmcnt(3)
	ds_write_b128 v150, v[44:47] offset:57344
	ds_write_b128 v150, v[12:15] offset:32768
	v_mfma_f32_16x16x32_bf16 v[116:119], v[238:241], v[218:221], v[116:119]
	v_mfma_f32_16x16x32_bf16 v[104:107], v[238:241], v[222:225], v[104:107]
	v_mfma_f32_16x16x32_bf16 v[88:91], v[238:241], v[226:229], v[88:91]
	v_mfma_f32_16x16x32_bf16 v[72:75], v[238:241], v[230:233], v[72:75]
	s_waitcnt lgkmcnt(5)
	s_waitcnt vmcnt(1)
	ds_write_b128 v150, v[24:27] offset:36864
	ds_write_b128 v150, v[40:43] offset:40960
	v_mfma_f32_16x16x32_bf16 v[112:115], v[242:245], v[218:221], v[112:115]
	v_mfma_f32_16x16x32_bf16 v[96:99], v[242:245], v[222:225], v[96:99]
	v_mfma_f32_16x16x32_bf16 v[84:87], v[242:245], v[226:229], v[84:87]
	v_mfma_f32_16x16x32_bf16 v[68:71], v[242:245], v[230:233], v[68:71]
	s_waitcnt lgkmcnt(6)
	s_waitcnt vmcnt(0)
	ds_write_b128 v150, v[56:59] offset:45056
	ds_write_b128 v150, v[60:63] offset:61440
	v_mfma_f32_16x16x32_bf16 v[108:111], v[156:159], v[218:221], v[108:111]
	v_mfma_f32_16x16x32_bf16 v[92:95], v[156:159], v[222:225], v[92:95]
	v_mfma_f32_16x16x32_bf16 v[76:79], v[156:159], v[226:229], v[76:79]
	v_mfma_f32_16x16x32_bf16 v[64:67], v[156:159], v[230:233], v[64:67]
	s_setprio 0
	s_waitcnt lgkmcnt(0)
	s_barrier
; #define GLOAD(ra, rb, koff)                                                        \
;   {                                                                                \
;     _Pragma("unroll") for (int j = 0; j < 4; j++) ra[j] = *(const u32x4*)(pa + j * sa32 + (koff));   \
;     _Pragma("unroll") for (int j = 0; j < NB_; j++) rb[j] = *(const u32x4*)(pbv[j] + (koff));         \
;   }
; template <int NT, bool PRE> ...
;     ...
;   if (!PRE) {
;     GLOAD(ra0, rb0, 0);
;     GLOAD(ra1, rb1, 64);
;   }
;   __syncthreads();
;   for (int k0 = 0; k0 < K; k0 += 128) {
;     LSTORE(ra0, rb0, 0);
;     __syncthreads();
;     GLOAD(ra0, rb0, min(k0 + 128, K - 128));
;     __builtin_amdgcn_sched_barrier(0);
;     COMPUTE(0);
;     LSTORE(ra1, rb1, 1);
;     __syncthreads();
;     GLOAD(ra1, rb1, min(k0 + 192, K - 64));
;     __builtin_amdgcn_sched_barrier(0);
;     COMPUTE(1);
;   }
; template <int EPI>
; __device__ __forceinline__ void phase_gemm(const Params& P, const u16* A, int lda, const u16* Bt, int K, int N, u16* sA, u16* sB) {
;     ...
;     for (; t < Tfull; t += G) {
;       const int m0 = (t % 132) * 128, n0 = (t / 132) * 128;
;       f32x4 acc[4][4];
;       zero_acc<4>(acc);
;       gemm_core_r<4, true>(pa, (size_t)32 * lda, pbv, K, acc, sA, sB, tq, ra0, rb0, ra1, rb1);
;       if (t + G < Tfull) {
;         PG_PTRS(t + G);
;         gemm_preload<4>(pa, (size_t)32 * lda, pbv, ra0, rb0, ra1, rb1);
	ds_read_b128 v[156:159], v152 offset:32768
	ds_read_b128 v[202:205], v153 offset:49152
	ds_read_b128 v[206:209], v153 offset:51200
	ds_read_b128 v[210:213], v153 offset:53248
	ds_read_b128 v[214:217], v153 offset:55296
	ds_read_b128 v[160:163], v152 offset:34816
	ds_read_b128 v[164:167], v152 offset:36864
	ds_read_b128 v[198:201], v152 offset:38912
	ds_read_b128 v[218:221], v154 offset:32768
	ds_read_b128 v[222:225], v154 offset:34816
	ds_read_b128 v[226:229], v154 offset:36864
	ds_read_b128 v[230:233], v154 offset:38912
	ds_read_b128 v[234:237], v155 offset:49152
	ds_read_b128 v[238:241], v155 offset:51200
	ds_read_b128 v[242:245], v155 offset:53248
	s_setprio 1
	s_waitcnt lgkmcnt(13)
	v_mfma_f32_16x16x32_bf16 v[124:127], v[202:205], v[156:159], v[124:127]
	s_waitcnt lgkmcnt(12)
	v_mfma_f32_16x16x32_bf16 v[116:119], v[206:209], v[156:159], v[116:119]
	s_waitcnt lgkmcnt(11)
	v_mfma_f32_16x16x32_bf16 v[112:115], v[210:213], v[156:159], v[112:115]
	s_waitcnt lgkmcnt(10)
	v_mfma_f32_16x16x32_bf16 v[108:111], v[214:217], v[156:159], v[108:111]
	ds_read_b128 v[156:159], v155 offset:55296
	s_waitcnt lgkmcnt(10)
	v_mfma_f32_16x16x32_bf16 v[120:123], v[202:205], v[160:163], v[120:123]
	v_mfma_f32_16x16x32_bf16 v[104:107], v[206:209], v[160:163], v[104:107]
	v_mfma_f32_16x16x32_bf16 v[96:99], v[210:213], v[160:163], v[96:99]
	v_mfma_f32_16x16x32_bf16 v[92:95], v[214:217], v[160:163], v[92:95]
	s_waitcnt lgkmcnt(9)
	v_mfma_f32_16x16x32_bf16 v[100:103], v[202:205], v[164:167], v[100:103]
	v_mfma_f32_16x16x32_bf16 v[88:91], v[206:209], v[164:167], v[88:91]
	v_mfma_f32_16x16x32_bf16 v[84:87], v[210:213], v[164:167], v[84:87]
	v_mfma_f32_16x16x32_bf16 v[76:79], v[214:217], v[164:167], v[76:79]
	s_waitcnt lgkmcnt(8)
	v_mfma_f32_16x16x32_bf16 v[80:83], v[202:205], v[198:201], v[80:83]
	v_mfma_f32_16x16x32_bf16 v[72:75], v[206:209], v[198:201], v[72:75]
	v_mfma_f32_16x16x32_bf16 v[68:71], v[210:213], v[198:201], v[68:71]
	v_mfma_f32_16x16x32_bf16 v[64:67], v[214:217], v[198:201], v[64:67]
	s_waitcnt lgkmcnt(3)
	v_mfma_f32_16x16x32_bf16 v[124:127], v[234:237], v[218:221], v[124:127]
	v_mfma_f32_16x16x32_bf16 v[120:123], v[234:237], v[222:225], v[120:123]
	v_mfma_f32_16x16x32_bf16 v[100:103], v[234:237], v[226:229], v[100:103]
	v_mfma_f32_16x16x32_bf16 v[80:83], v[234:237], v[230:233], v[80:83]
	s_waitcnt lgkmcnt(2)
	v_mfma_f32_16x16x32_bf16 v[116:119], v[238:241], v[218:221], v[116:119]
	v_mfma_f32_16x16x32_bf16 v[104:107], v[238:241], v[222:225], v[104:107]
	v_mfma_f32_16x16x32_bf16 v[88:91], v[238:241], v[226:229], v[88:91]
	v_mfma_f32_16x16x32_bf16 v[72:75], v[238:241], v[230:233], v[72:75]
	s_waitcnt lgkmcnt(1)
	v_mfma_f32_16x16x32_bf16 v[112:115], v[242:245], v[218:221], v[112:115]
	v_mfma_f32_16x16x32_bf16 v[96:99], v[242:245], v[222:225], v[96:99]
	v_mfma_f32_16x16x32_bf16 v[84:87], v[242:245], v[226:229], v[84:87]
	v_mfma_f32_16x16x32_bf16 v[68:71], v[242:245], v[230:233], v[68:71]
	s_waitcnt lgkmcnt(0)
	v_mfma_f32_16x16x32_bf16 v[108:111], v[156:159], v[218:221], v[108:111]
	v_mfma_f32_16x16x32_bf16 v[92:95], v[156:159], v[222:225], v[92:95]
	v_mfma_f32_16x16x32_bf16 v[76:79], v[156:159], v[226:229], v[76:79]
	v_mfma_f32_16x16x32_bf16 v[64:67], v[156:159], v[230:233], v[64:67]
	s_setprio 0
	s_waitcnt lgkmcnt(0)
	s_add_i32 s7, s6, s90
	s_cmp_ge_i32 s7, s18
	s_cselect_b64 s[4:5], -1, 0
	s_and_b64 vcc, exec, s[4:5]
	s_cbranch_vccnz .LBB0_2287
	s_cmp_lg_u32 s90, 0x200
	s_cbranch_scc1 .Lrm_w2p_orig
	s_and_b32 s54, s7, 7
	s_lshl_b32 s54, s54, 6
	s_bfe_u32 s8, s7, 0x60003
	s_or_b32 s54, s54, s8
	s_andn2_b32 s8, s7, 0x1ff
	s_or_b32 s54, s54, s8
	s_cmp_lt_u32 s54, 0
	s_cbranch_scc0 .Lrm_w2p_b
	s_lshr_b32 s8, s54, 3
	s_mul_hi_u32 s8, s8, 0x3e0f83e1
	s_lshr_b32 s8, s8, 5
	s_mul_i32 s9, s8, 1056
	s_sub_i32 s54, s54, s9
	s_lshl_b32 s8, s8, 3
	s_and_b32 s9, s54, 7
	s_add_i32 s8, s8, s9
	s_lshr_b32 s9, s54, 3
	s_branch .Lrm_w2p_done
